# Resid GEMM epilogues: row sum-of-squares partial stores paired (16-lane masked dword stores of two row-sets merged into one 32-lane store via v_permlane16_swap_b32), 8 -> 5 per wave per tile
# speedup vs baseline: 1.0059x; 1.0059x over previous
.LBB0_397:
	ds_read_b128 v[128:131], v187
	ds_read_b128 v[132:135], v188
	ds_read_b128 v[136:139], v189
	ds_read_b128 v[140:143], v190
	s_add_u32 s20, s16, 0xfff50080
	s_addc_u32 s21, s17, -1
	s_cmp_eq_u32 s19, 40
	s_cselect_b32 s57, s13, s21
	s_cselect_b32 s56, s12, s20
	s_cselect_b32 s39, s15, s18
	s_cselect_b32 s38, s14, s37
	s_mov_b32 m0, s90
	v_lshl_add_u64 v[228:229], s[16:17], 0, v[158:159]
	ds_read_b128 v[164:167], v145
	ds_read_b128 v[168:171], v145 offset:1024
	ds_read_b128 v[204:207], v145 offset:2048
	ds_read_b128 v[208:211], v145 offset:3072
	ds_read_b128 v[212:215], v145 offset:4096
	ds_read_b128 v[216:219], v145 offset:5120
	ds_read_b128 v[220:223], v145 offset:6144
	ds_read_b128 v[224:227], v145 offset:7168
	global_load_lds_dwordx4 v[228:229], off
	v_lshl_add_u64 v[228:229], s[16:17], 0, v[156:157]
	s_mov_b32 m0, s91
	s_nop 0
	global_load_lds_dwordx4 v[228:229], off
	s_waitcnt lgkmcnt(8)
	s_barrier
	s_waitcnt lgkmcnt(0)
	s_setprio 1
	s_waitcnt lgkmcnt(0)
	v_mfma_f32_16x16x32_bf16 v[124:127], v[128:131], v[164:167], v[124:127]
	v_mfma_f32_16x16x32_bf16 v[120:123], v[136:139], v[164:167], v[120:123]
	v_mfma_f32_16x16x32_bf16 v[108:111], v[128:131], v[204:207], v[108:111]
	v_mfma_f32_16x16x32_bf16 v[104:107], v[136:139], v[204:207], v[104:107]
	v_mfma_f32_16x16x32_bf16 v[92:95], v[128:131], v[212:215], v[92:95]
	v_mfma_f32_16x16x32_bf16 v[88:91], v[136:139], v[212:215], v[88:91]
	v_mfma_f32_16x16x32_bf16 v[76:79], v[128:131], v[220:223], v[76:79]
	v_mfma_f32_16x16x32_bf16 v[72:75], v[136:139], v[220:223], v[72:75]
	v_mfma_f32_16x16x32_bf16 v[124:127], v[132:135], v[168:171], v[124:127]
	v_mfma_f32_16x16x32_bf16 v[120:123], v[140:143], v[168:171], v[120:123]
	v_mfma_f32_16x16x32_bf16 v[108:111], v[132:135], v[208:211], v[108:111]
	v_mfma_f32_16x16x32_bf16 v[104:107], v[140:143], v[208:211], v[104:107]
	v_mfma_f32_16x16x32_bf16 v[92:95], v[132:135], v[216:219], v[92:95]
	v_mfma_f32_16x16x32_bf16 v[88:91], v[140:143], v[216:219], v[88:91]
	v_mfma_f32_16x16x32_bf16 v[76:79], v[132:135], v[224:227], v[76:79]
	v_mfma_f32_16x16x32_bf16 v[72:75], v[140:143], v[224:227], v[72:75]
	s_setprio 0
	s_barrier
	s_mov_b32 m0, s68
	v_lshl_add_u64 v[244:245], s[38:39], 0, v[146:147]
	ds_read_b128 v[228:231], v191
	ds_read_b128 v[232:235], v192
	ds_read_b128 v[236:239], v193
	ds_read_b128 v[240:243], v194
	global_load_lds_dwordx4 v[244:245], off
	v_lshl_add_u64 v[246:247], s[38:39], 0, v[148:149]
	s_mov_b32 m0, s69
	s_nop 0
	global_load_lds_dwordx4 v[246:247], off
	s_barrier
	s_waitcnt lgkmcnt(0)
	s_setprio 1
	s_waitcnt lgkmcnt(0)
	v_mfma_f32_16x16x32_bf16 v[116:119], v[228:231], v[164:167], v[116:119]
	v_mfma_f32_16x16x32_bf16 v[112:115], v[236:239], v[164:167], v[112:115]
	v_mfma_f32_16x16x32_bf16 v[100:103], v[228:231], v[204:207], v[100:103]
	v_mfma_f32_16x16x32_bf16 v[96:99], v[236:239], v[204:207], v[96:99]
	v_mfma_f32_16x16x32_bf16 v[84:87], v[228:231], v[212:215], v[84:87]
	v_mfma_f32_16x16x32_bf16 v[80:83], v[236:239], v[212:215], v[80:83]
	v_mfma_f32_16x16x32_bf16 v[68:71], v[228:231], v[220:223], v[68:71]
	v_mfma_f32_16x16x32_bf16 v[64:67], v[236:239], v[220:223], v[64:67]
	v_mfma_f32_16x16x32_bf16 v[116:119], v[232:235], v[168:171], v[116:119]
	v_mfma_f32_16x16x32_bf16 v[112:115], v[240:243], v[168:171], v[112:115]
	v_mfma_f32_16x16x32_bf16 v[100:103], v[232:235], v[208:211], v[100:103]
	v_mfma_f32_16x16x32_bf16 v[96:99], v[240:243], v[208:211], v[96:99]
	v_mfma_f32_16x16x32_bf16 v[84:87], v[232:235], v[216:219], v[84:87]
	v_mfma_f32_16x16x32_bf16 v[80:83], v[240:243], v[216:219], v[80:83]
	v_mfma_f32_16x16x32_bf16 v[68:71], v[232:235], v[224:227], v[68:71]
	v_mfma_f32_16x16x32_bf16 v[64:67], v[240:243], v[224:227], v[64:67]
	s_setprio 0
	s_mov_b32 m0, s67
	v_lshl_add_u64 v[248:249], s[56:57], 0, v[146:147]
	s_barrier
	ds_read_b128 v[164:167], v145 offset:16384
	ds_read_b128 v[168:171], v145 offset:17408
	ds_read_b128 v[204:207], v145 offset:18432
	ds_read_b128 v[208:211], v145 offset:19456
	ds_read_b128 v[212:215], v145 offset:20480
	ds_read_b128 v[216:219], v145 offset:21504
	ds_read_b128 v[220:223], v145 offset:22528
	ds_read_b128 v[224:227], v145 offset:23552
	global_load_lds_dwordx4 v[248:249], off
	v_lshl_add_u64 v[250:251], s[56:57], 0, v[148:149]
	s_mov_b32 m0, s70
	s_nop 0
	global_load_lds_dwordx4 v[250:251], off
	s_barrier
	s_waitcnt lgkmcnt(0)
	s_setprio 1
	s_waitcnt lgkmcnt(0)
	v_mfma_f32_16x16x32_bf16 v[60:63], v[128:131], v[164:167], v[60:63]
	v_mfma_f32_16x16x32_bf16 v[56:59], v[136:139], v[164:167], v[56:59]
	v_mfma_f32_16x16x32_bf16 v[44:47], v[128:131], v[204:207], v[44:47]
	v_mfma_f32_16x16x32_bf16 v[40:43], v[136:139], v[204:207], v[40:43]
	v_mfma_f32_16x16x32_bf16 v[28:31], v[128:131], v[212:215], v[28:31]
	v_mfma_f32_16x16x32_bf16 v[24:27], v[136:139], v[212:215], v[24:27]
	v_mfma_f32_16x16x32_bf16 v[12:15], v[128:131], v[220:223], v[12:15]
	v_mfma_f32_16x16x32_bf16 v[8:11], v[136:139], v[220:223], v[8:11]
	v_mfma_f32_16x16x32_bf16 v[60:63], v[132:135], v[168:171], v[60:63]
	v_mfma_f32_16x16x32_bf16 v[56:59], v[140:143], v[168:171], v[56:59]
	v_mfma_f32_16x16x32_bf16 v[44:47], v[132:135], v[208:211], v[44:47]
	v_mfma_f32_16x16x32_bf16 v[40:43], v[140:143], v[208:211], v[40:43]
	v_mfma_f32_16x16x32_bf16 v[28:31], v[132:135], v[216:219], v[28:31]
	v_mfma_f32_16x16x32_bf16 v[24:27], v[140:143], v[216:219], v[24:27]
	v_mfma_f32_16x16x32_bf16 v[12:15], v[132:135], v[224:227], v[12:15]
	v_mfma_f32_16x16x32_bf16 v[8:11], v[140:143], v[224:227], v[8:11]
	s_setprio 0
	s_barrier
	s_add_u32 s20, s38, 0xb0000
	s_addc_u32 s21, s39, 0
	s_mov_b32 m0, s71
	v_lshl_add_u64 v[128:129], s[20:21], 0, v[146:147]
	global_load_lds_dwordx4 v[128:129], off
	v_lshl_add_u64 v[128:129], s[20:21], 0, v[148:149]
	s_mov_b32 m0, s80
	s_nop 0
	global_load_lds_dwordx4 v[128:129], off
	s_waitcnt vmcnt(6)
	s_barrier
	s_setprio 1
	v_mfma_f32_16x16x32_bf16 v[52:55], v[228:231], v[164:167], v[52:55]
	v_mfma_f32_16x16x32_bf16 v[48:51], v[236:239], v[164:167], v[48:51]
	v_mfma_f32_16x16x32_bf16 v[36:39], v[228:231], v[204:207], v[36:39]
	v_mfma_f32_16x16x32_bf16 v[32:35], v[236:239], v[204:207], v[32:35]
	v_mfma_f32_16x16x32_bf16 v[20:23], v[228:231], v[212:215], v[20:23]
	v_mfma_f32_16x16x32_bf16 v[16:19], v[236:239], v[212:215], v[16:19]
	v_mfma_f32_16x16x32_bf16 v[4:7], v[228:231], v[220:223], v[4:7]
	v_mfma_f32_16x16x32_bf16 v[0:3], v[236:239], v[220:223], v[0:3]
	v_mfma_f32_16x16x32_bf16 v[52:55], v[232:235], v[168:171], v[52:55]
	v_mfma_f32_16x16x32_bf16 v[48:51], v[240:243], v[168:171], v[48:51]
	v_mfma_f32_16x16x32_bf16 v[36:39], v[232:235], v[208:211], v[36:39]
	v_mfma_f32_16x16x32_bf16 v[32:35], v[240:243], v[208:211], v[32:35]
	v_mfma_f32_16x16x32_bf16 v[20:23], v[232:235], v[216:219], v[20:23]
	v_mfma_f32_16x16x32_bf16 v[16:19], v[240:243], v[216:219], v[16:19]
	v_mfma_f32_16x16x32_bf16 v[4:7], v[232:235], v[224:227], v[4:7]
	v_mfma_f32_16x16x32_bf16 v[0:3], v[240:243], v[224:227], v[0:3]
	s_setprio 0
	s_barrier
	ds_read_b128 v[128:131], v195
	ds_read_b128 v[132:135], v196
	ds_read_b128 v[136:139], v197
	ds_read_b128 v[140:143], v198
	s_add_u32 s20, s56, 0xb0000
	s_addc_u32 s21, s57, 0
	s_mov_b32 m0, s81
	v_lshl_add_u64 v[228:229], s[20:21], 0, v[146:147]
	ds_read_b128 v[164:167], v145 offset:32768
	ds_read_b128 v[168:171], v145 offset:33792
	ds_read_b128 v[204:207], v145 offset:34816
	ds_read_b128 v[208:211], v145 offset:35840
	ds_read_b128 v[212:215], v145 offset:36864
	ds_read_b128 v[216:219], v145 offset:37888
	ds_read_b128 v[220:223], v145 offset:38912
	ds_read_b128 v[224:227], v145 offset:39936
	global_load_lds_dwordx4 v[228:229], off
	v_lshl_add_u64 v[228:229], s[20:21], 0, v[148:149]
	s_mov_b32 m0, s82
	s_nop 0
	global_load_lds_dwordx4 v[228:229], off
	s_waitcnt lgkmcnt(8)
	s_barrier
	s_waitcnt lgkmcnt(0)
	s_setprio 1
	s_waitcnt lgkmcnt(0)
	v_mfma_f32_16x16x32_bf16 v[124:127], v[128:131], v[164:167], v[124:127]
	v_mfma_f32_16x16x32_bf16 v[120:123], v[136:139], v[164:167], v[120:123]
	v_mfma_f32_16x16x32_bf16 v[108:111], v[128:131], v[204:207], v[108:111]
	v_mfma_f32_16x16x32_bf16 v[104:107], v[136:139], v[204:207], v[104:107]
	v_mfma_f32_16x16x32_bf16 v[92:95], v[128:131], v[212:215], v[92:95]
	v_mfma_f32_16x16x32_bf16 v[88:91], v[136:139], v[212:215], v[88:91]
	v_mfma_f32_16x16x32_bf16 v[76:79], v[128:131], v[220:223], v[76:79]
	v_mfma_f32_16x16x32_bf16 v[72:75], v[136:139], v[220:223], v[72:75]
	v_mfma_f32_16x16x32_bf16 v[124:127], v[132:135], v[168:171], v[124:127]
	v_mfma_f32_16x16x32_bf16 v[120:123], v[140:143], v[168:171], v[120:123]
	v_mfma_f32_16x16x32_bf16 v[108:111], v[132:135], v[208:211], v[108:111]
	v_mfma_f32_16x16x32_bf16 v[104:107], v[140:143], v[208:211], v[104:107]
	v_mfma_f32_16x16x32_bf16 v[92:95], v[132:135], v[216:219], v[92:95]
	v_mfma_f32_16x16x32_bf16 v[88:91], v[140:143], v[216:219], v[88:91]
	v_mfma_f32_16x16x32_bf16 v[76:79], v[132:135], v[224:227], v[76:79]
	v_mfma_f32_16x16x32_bf16 v[72:75], v[140:143], v[224:227], v[72:75]
	s_setprio 0
	s_barrier
	s_mov_b32 m0, s84
	v_lshl_add_u64 v[244:245], v[244:245], 0, s[4:5]
	ds_read_b128 v[228:231], v199
	ds_read_b128 v[232:235], v200
	ds_read_b128 v[236:239], v201
	ds_read_b128 v[240:243], v202
	global_load_lds_dwordx4 v[244:245], off
	v_lshl_add_u64 v[244:245], v[246:247], 0, s[4:5]
	s_mov_b32 m0, s85
	s_nop 0
	global_load_lds_dwordx4 v[244:245], off
	s_barrier
	s_waitcnt lgkmcnt(0)
	s_setprio 1
	s_waitcnt lgkmcnt(0)
	v_mfma_f32_16x16x32_bf16 v[116:119], v[228:231], v[164:167], v[116:119]
	v_mfma_f32_16x16x32_bf16 v[112:115], v[236:239], v[164:167], v[112:115]
	v_mfma_f32_16x16x32_bf16 v[100:103], v[228:231], v[204:207], v[100:103]
	v_mfma_f32_16x16x32_bf16 v[96:99], v[236:239], v[204:207], v[96:99]
	v_mfma_f32_16x16x32_bf16 v[84:87], v[228:231], v[212:215], v[84:87]
	v_mfma_f32_16x16x32_bf16 v[80:83], v[236:239], v[212:215], v[80:83]
	v_mfma_f32_16x16x32_bf16 v[68:71], v[228:231], v[220:223], v[68:71]
	v_mfma_f32_16x16x32_bf16 v[64:67], v[236:239], v[220:223], v[64:67]
	v_mfma_f32_16x16x32_bf16 v[116:119], v[232:235], v[168:171], v[116:119]
	v_mfma_f32_16x16x32_bf16 v[112:115], v[240:243], v[168:171], v[112:115]
	v_mfma_f32_16x16x32_bf16 v[100:103], v[232:235], v[208:211], v[100:103]
	v_mfma_f32_16x16x32_bf16 v[96:99], v[240:243], v[208:211], v[96:99]
	v_mfma_f32_16x16x32_bf16 v[84:87], v[232:235], v[216:219], v[84:87]
	v_mfma_f32_16x16x32_bf16 v[80:83], v[240:243], v[216:219], v[80:83]
	v_mfma_f32_16x16x32_bf16 v[68:71], v[232:235], v[224:227], v[68:71]
	v_mfma_f32_16x16x32_bf16 v[64:67], v[240:243], v[224:227], v[64:67]
	s_setprio 0
	s_mov_b32 m0, s86
	v_lshl_add_u64 v[244:245], v[248:249], 0, s[4:5]
	s_barrier
	ds_read_b128 v[164:167], v145 offset:49152
	ds_read_b128 v[168:171], v145 offset:50176
	ds_read_b128 v[204:207], v145 offset:51200
	ds_read_b128 v[208:211], v145 offset:52224
	ds_read_b128 v[212:215], v145 offset:53248
	ds_read_b128 v[216:219], v145 offset:54272
	ds_read_b128 v[220:223], v145 offset:55296
	ds_read_b128 v[224:227], v145 offset:56320
	global_load_lds_dwordx4 v[244:245], off
	v_lshl_add_u64 v[244:245], v[250:251], 0, s[4:5]
	s_mov_b32 m0, s87
	s_nop 0
	global_load_lds_dwordx4 v[244:245], off
	s_barrier
	s_waitcnt lgkmcnt(0)
	s_setprio 1
	s_waitcnt lgkmcnt(0)
	v_mfma_f32_16x16x32_bf16 v[60:63], v[128:131], v[164:167], v[60:63]
	v_mfma_f32_16x16x32_bf16 v[56:59], v[136:139], v[164:167], v[56:59]
	v_mfma_f32_16x16x32_bf16 v[44:47], v[128:131], v[204:207], v[44:47]
	v_mfma_f32_16x16x32_bf16 v[40:43], v[136:139], v[204:207], v[40:43]
	v_mfma_f32_16x16x32_bf16 v[28:31], v[128:131], v[212:215], v[28:31]
	v_mfma_f32_16x16x32_bf16 v[24:27], v[136:139], v[212:215], v[24:27]
	v_mfma_f32_16x16x32_bf16 v[12:15], v[128:131], v[220:223], v[12:15]
	v_mfma_f32_16x16x32_bf16 v[8:11], v[136:139], v[220:223], v[8:11]
	v_mfma_f32_16x16x32_bf16 v[60:63], v[132:135], v[168:171], v[60:63]
	v_mfma_f32_16x16x32_bf16 v[56:59], v[140:143], v[168:171], v[56:59]
	v_mfma_f32_16x16x32_bf16 v[44:47], v[132:135], v[208:211], v[44:47]
	v_mfma_f32_16x16x32_bf16 v[40:43], v[140:143], v[208:211], v[40:43]
	v_mfma_f32_16x16x32_bf16 v[28:31], v[132:135], v[216:219], v[28:31]
	v_mfma_f32_16x16x32_bf16 v[24:27], v[140:143], v[216:219], v[24:27]
	v_mfma_f32_16x16x32_bf16 v[12:15], v[132:135], v[224:227], v[12:15]
	v_mfma_f32_16x16x32_bf16 v[8:11], v[140:143], v[224:227], v[8:11]
	s_setprio 0
	s_barrier
	s_add_u32 s20, s38, 0xb0080
	s_addc_u32 s21, s39, 0
	s_mov_b32 m0, s88
	v_lshl_add_u64 v[128:129], s[20:21], 0, v[146:147]
	global_load_lds_dwordx4 v[128:129], off
	v_lshl_add_u64 v[128:129], s[20:21], 0, v[148:149]
	s_mov_b32 m0, s89
	s_nop 0
	global_load_lds_dwordx4 v[128:129], off
	s_waitcnt vmcnt(6)
	s_barrier
	s_setprio 1
	v_mfma_f32_16x16x32_bf16 v[52:55], v[228:231], v[164:167], v[52:55]
	v_mfma_f32_16x16x32_bf16 v[48:51], v[236:239], v[164:167], v[48:51]
	v_mfma_f32_16x16x32_bf16 v[36:39], v[228:231], v[204:207], v[36:39]
	v_mfma_f32_16x16x32_bf16 v[32:35], v[236:239], v[204:207], v[32:35]
	v_mfma_f32_16x16x32_bf16 v[20:23], v[228:231], v[212:215], v[20:23]
	v_mfma_f32_16x16x32_bf16 v[16:19], v[236:239], v[212:215], v[16:19]
	v_mfma_f32_16x16x32_bf16 v[4:7], v[228:231], v[220:223], v[4:7]
	v_mfma_f32_16x16x32_bf16 v[0:3], v[236:239], v[220:223], v[0:3]
	v_mfma_f32_16x16x32_bf16 v[52:55], v[232:235], v[168:171], v[52:55]
	v_mfma_f32_16x16x32_bf16 v[48:51], v[240:243], v[168:171], v[48:51]
	v_mfma_f32_16x16x32_bf16 v[36:39], v[232:235], v[208:211], v[36:39]
	v_mfma_f32_16x16x32_bf16 v[32:35], v[240:243], v[208:211], v[32:35]
	v_mfma_f32_16x16x32_bf16 v[20:23], v[232:235], v[216:219], v[20:23]
	v_mfma_f32_16x16x32_bf16 v[16:19], v[240:243], v[216:219], v[16:19]
	v_mfma_f32_16x16x32_bf16 v[4:7], v[232:235], v[224:227], v[4:7]
	v_mfma_f32_16x16x32_bf16 v[0:3], v[240:243], v[224:227], v[0:3]
	s_setprio 0
	s_add_i32 s19, s19, 2
	s_add_u32 s37, s37, 0x100
	s_addc_u32 s18, s18, 0
	s_add_u32 s16, s16, 0x100
	s_addc_u32 s17, s17, 0
	s_cmp_gt_u32 s19, 41
	s_barrier
	s_cbranch_scc0 .LBB0_397
	s_ashr_i32 s37, s36, 31
	s_lshl_b64 s[16:17], s[36:37], 8
	s_lshl_b32 s18, s6, 8
	v_lshl_add_u64 v[166:167], s[16:17], 0, v[150:151]
	s_ashr_i32 s19, s18, 31
	v_lshl_add_u64 v[168:169], s[18:19], 2, v[154:155]
	v_lshlrev_b64 v[128:129], 12, v[166:167]
	v_lshl_add_u64 v[128:129], v[168:169], 0, v[128:129]
	global_load_dwordx4 v[204:207], v[128:129], off
	global_load_dwordx4 v[208:211], v[128:129], off offset:64
	global_load_dwordx4 v[212:215], v[128:129], off offset:512
	global_load_dwordx4 v[216:219], v[128:129], off offset:576
	v_or_b32_e32 v170, 16, v166
	v_mov_b32_e32 v171, v167
	v_lshlrev_b64 v[128:129], 12, v[170:171]
	v_lshl_add_u64 v[128:129], v[168:169], 0, v[128:129]
	global_load_dwordx4 v[140:143], v[128:129], off
	global_load_dwordx4 v[136:139], v[128:129], off offset:64
	global_load_dwordx4 v[132:135], v[128:129], off offset:512
	s_nop 0
	global_load_dwordx4 v[128:131], v[128:129], off offset:576
	v_mov_b32_e32 v165, s19
	v_or_b32_e32 v164, s18, v152
	v_lshlrev_b64 v[220:221], 10, v[166:167]
	v_lshl_add_u64 v[220:221], v[220:221], 0, v[164:165]
	s_waitcnt vmcnt(0)
	s_lshl_b32 s16, s6, 2
	s_ashr_i32 s17, s16, 31
	s_waitcnt vmcnt(0)
	v_pk_fma_f32 v[126:127], v[126:127], 0.5, v[206:207] op_sel_hi:[1,0,1]
	v_lshlrev_b64 v[206:207], 1, v[220:221]
	v_pk_fma_f32 v[124:125], v[124:125], 0.5, v[204:205] op_sel_hi:[1,0,1]
	v_lshl_add_u64 v[204:205], v[220:221], 2, s[78:79]
	v_lshl_add_u64 v[220:221], s[0:1], 0, v[206:207]
	global_store_dwordx4 v[204:205], v[124:127], off
	v_cvt_pk_bf16_f32 v222, v124, v125
	v_cvt_pk_bf16_f32 v223, v126, v127
	v_bfe_u32 v246, v176, 4, 1
	v_mul_u32_u24_e32 v246, 24, v246
	v_mov_b32_e32 v247, 0
	s_nop 1
	v_mov_b32_e32 v240, v222
	v_mov_b32_e32 v241, v223
	v_lshl_add_u64 v[244:245], v[220:221], 0, v[246:247]
	v_mul_f32_e32 v220, v124, v124
	v_fmac_f32_e32 v220, v125, v125
	v_pk_fma_f32 v[122:123], v[122:123], 0.5, v[210:211] op_sel_hi:[1,0,1]
	v_pk_fma_f32 v[120:121], v[120:121], 0.5, v[208:209] op_sel_hi:[1,0,1]
	v_fmac_f32_e32 v220, v126, v126
	global_store_dwordx4 v[204:205], v[120:123], off offset:64
	v_cvt_pk_bf16_f32 v126, v120, v121
	v_or_b32_e32 v124, 32, v206
	v_mov_b32_e32 v125, v207
	v_mul_f32_e32 v120, v120, v120
	v_fmac_f32_e32 v120, v121, v121
	v_fmac_f32_e32 v120, v122, v122
	v_fmac_f32_e32 v220, v127, v127
	v_lshl_add_u64 v[124:125], s[0:1], 0, v[124:125]
	v_fmac_f32_e32 v120, v123, v123
	v_pk_fma_f32 v[118:119], v[118:119], 0.5, v[214:215] op_sel_hi:[1,0,1]
	v_pk_fma_f32 v[116:117], v[116:117], 0.5, v[212:213] op_sel_hi:[1,0,1]
	v_cvt_pk_bf16_f32 v127, v122, v123
	v_mov_b32_e32 v242, v126
	v_mov_b32_e32 v243, v127
	s_nop 1
	v_permlane16_swap_b32 v240, v242
	v_permlane16_swap_b32 v241, v243
	global_store_dwordx4 v[244:245], v[240:243], off
	v_add_f32_e32 v124, v220, v120
	global_store_dwordx4 v[204:205], v[116:119], off offset:512
	v_or_b32_e32 v120, 0x100, v206
	v_mov_b32_e32 v121, v207
	v_cvt_pk_bf16_f32 v122, v116, v117
	v_mul_f32_e32 v116, v116, v116
	v_lshl_add_u64 v[120:121], s[0:1], 0, v[120:121]
	v_fmac_f32_e32 v116, v117, v117
	v_pk_fma_f32 v[114:115], v[114:115], 0.5, v[218:219] op_sel_hi:[1,0,1]
	v_pk_fma_f32 v[112:113], v[112:113], 0.5, v[216:217] op_sel_hi:[1,0,1]
	v_cvt_pk_bf16_f32 v123, v118, v119
	s_nop 1
	v_mov_b32_e32 v240, v122
	v_mov_b32_e32 v241, v123
	v_lshl_add_u64 v[244:245], v[120:121], 0, v[246:247]
	v_fmac_f32_e32 v116, v118, v118
	global_store_dwordx4 v[204:205], v[112:115], off offset:576
	v_cvt_pk_bf16_f32 v118, v112, v113
	v_fmac_f32_e32 v116, v119, v119
	v_cvt_pk_bf16_f32 v119, v114, v115
	v_or_b32_e32 v206, 0x120, v206
	v_mul_f32_e32 v112, v112, v112
	v_fmac_f32_e32 v112, v113, v113
	v_fmac_f32_e32 v112, v114, v114
	v_and_b32_e32 v114, 64, v203
	v_xor_b32_e32 v113, 16, v203
	v_add_u32_e32 v114, 64, v114
	v_cmp_lt_i32_e32 vcc, v113, v114
	v_add_f32_e32 v120, v124, v116
	v_lshl_add_u64 v[116:117], s[0:1], 0, v[206:207]
	v_fmac_f32_e32 v112, v115, v115
	v_cndmask_b32_e32 v113, v203, v113, vcc
	v_mov_b32_e32 v242, v118
	v_mov_b32_e32 v243, v119
	s_nop 1
	v_permlane16_swap_b32 v240, v242
	v_permlane16_swap_b32 v241, v243
	global_store_dwordx4 v[244:245], v[240:243], off
	v_add_f32_e32 v112, v120, v112
	v_lshlrev_b32_e32 v116, 2, v113
	ds_bpermute_b32 v113, v116, v112
	s_waitcnt lgkmcnt(0)
	v_add_f32_e32 v112, v112, v113
	v_xor_b32_e32 v113, 32, v203
	v_cmp_lt_i32_e32 vcc, v113, v114
	s_nop 1
	v_cndmask_b32_e32 v113, v203, v113, vcc
	v_lshlrev_b32_e32 v117, 2, v113
	ds_bpermute_b32 v113, v117, v112
	s_and_saveexec_b64 s[36:37], s[8:9]
	s_cbranch_execz .LBB0_400
	v_lshlrev_b64 v[114:115], 6, v[166:167]
	v_lshl_add_u64 v[114:115], s[2:3], 0, v[114:115]
	v_lshl_add_u64 v[114:115], s[16:17], 2, v[114:115]
	s_lshl_b32 s6, s83, 2
	v_lshl_add_u64 v[114:115], v[114:115], 0, s[6:7]
	s_waitcnt lgkmcnt(0)
	v_add_f32_e32 v112, v112, v113
	v_mov_b32_e32 v232, v114
	v_mov_b32_e32 v233, v115
	v_mov_b32_e32 v234, v112
.LBB0_400:
	s_or_b64 exec, exec, s[36:37]
	s_waitcnt lgkmcnt(0)
	v_lshlrev_b64 v[112:113], 10, v[170:171]
	v_lshl_add_u64 v[112:113], v[112:113], 0, v[164:165]
	v_lshl_add_u64 v[114:115], v[112:113], 2, s[78:79]
	v_lshlrev_b64 v[112:113], 1, v[112:113]
	v_pk_fma_f32 v[110:111], v[110:111], 0.5, v[142:143] op_sel_hi:[1,0,1]
	v_pk_fma_f32 v[108:109], v[108:109], 0.5, v[140:141] op_sel_hi:[1,0,1]
	v_lshl_add_u64 v[118:119], s[0:1], 0, v[112:113]
	global_store_dwordx4 v[114:115], v[108:111], off
	v_cvt_pk_bf16_f32 v120, v108, v109
	v_cvt_pk_bf16_f32 v121, v110, v111
	s_nop 1
	v_mov_b32_e32 v240, v120
	v_mov_b32_e32 v241, v121
	v_lshl_add_u64 v[244:245], v[118:119], 0, v[246:247]
	v_mul_f32_e32 v118, v108, v108
	v_fmac_f32_e32 v118, v109, v109
	v_pk_fma_f32 v[106:107], v[106:107], 0.5, v[138:139] op_sel_hi:[1,0,1]
	v_pk_fma_f32 v[104:105], v[104:105], 0.5, v[136:137] op_sel_hi:[1,0,1]
	v_fmac_f32_e32 v118, v110, v110
	global_store_dwordx4 v[114:115], v[104:107], off offset:64
	v_or_b32_e32 v108, 32, v112
	v_mov_b32_e32 v109, v113
	v_cvt_pk_bf16_f32 v110, v104, v105
	v_mul_f32_e32 v104, v104, v104
	v_lshl_add_u64 v[108:109], s[0:1], 0, v[108:109]
	v_fmac_f32_e32 v104, v105, v105
	v_pk_fma_f32 v[102:103], v[102:103], 0.5, v[134:135] op_sel_hi:[1,0,1]
	v_pk_fma_f32 v[100:101], v[100:101], 0.5, v[132:133] op_sel_hi:[1,0,1]
	v_fmac_f32_e32 v118, v111, v111
	v_cvt_pk_bf16_f32 v111, v106, v107
	v_mov_b32_e32 v242, v110
	v_mov_b32_e32 v243, v111
	s_nop 1
	v_permlane16_swap_b32 v240, v242
	v_permlane16_swap_b32 v241, v243
	global_store_dwordx4 v[244:245], v[240:243], off
	v_fmac_f32_e32 v104, v106, v106
	global_store_dwordx4 v[114:115], v[100:103], off offset:512
	v_cvt_pk_bf16_f32 v106, v100, v101
	v_fmac_f32_e32 v104, v107, v107
	v_add_f32_e32 v107, v118, v104
	v_mul_f32_e32 v100, v100, v100
	v_fmac_f32_e32 v100, v101, v101
	v_fmac_f32_e32 v100, v102, v102
	v_fmac_f32_e32 v100, v103, v103
	v_add_f32_e32 v107, v107, v100
	v_pk_fma_f32 v[100:101], v[98:99], 0.5, v[130:131] op_sel_hi:[1,0,1]
	v_pk_fma_f32 v[98:99], v[96:97], 0.5, v[128:129] op_sel_hi:[1,0,1]
	v_or_b32_e32 v104, 0x100, v112
	v_mul_f32_e32 v96, v98, v98
	v_fmac_f32_e32 v96, v99, v99
	v_fmac_f32_e32 v96, v100, v100
	v_fmac_f32_e32 v96, v101, v101
	v_add_f32_e32 v96, v107, v96
	ds_bpermute_b32 v97, v116, v96
	v_mov_b32_e32 v105, v113
	v_or_b32_e32 v112, 0x120, v112
	v_lshl_add_u64 v[104:105], s[0:1], 0, v[104:105]
	v_cvt_pk_bf16_f32 v107, v102, v103
	s_waitcnt lgkmcnt(0)
	v_add_f32_e32 v96, v96, v97
	ds_bpermute_b32 v97, v117, v96
	v_lshl_add_u64 v[102:103], s[0:1], 0, v[112:113]
	s_nop 1
	v_mov_b32_e32 v240, v106
	v_mov_b32_e32 v241, v107
	v_lshl_add_u64 v[244:245], v[104:105], 0, v[246:247]
	global_store_dwordx4 v[114:115], v[98:101], off offset:576
	s_nop 1
	v_cvt_pk_bf16_f32 v98, v98, v99
	v_cvt_pk_bf16_f32 v99, v100, v101
	v_mov_b32_e32 v242, v98
	v_mov_b32_e32 v243, v99
	s_nop 1
	v_permlane16_swap_b32 v240, v242
	v_permlane16_swap_b32 v241, v243
	global_store_dwordx4 v[244:245], v[240:243], off
	s_and_saveexec_b64 s[36:37], s[8:9]
	s_cbranch_execz .LBB0_402
	v_lshlrev_b64 v[98:99], 6, v[170:171]
	v_lshl_add_u64 v[98:99], s[2:3], 0, v[98:99]
	v_lshl_add_u64 v[98:99], s[16:17], 2, v[98:99]
	s_lshl_b32 s6, s83, 2
	v_lshl_add_u64 v[98:99], v[98:99], 0, s[6:7]
	s_waitcnt lgkmcnt(0)
	v_add_f32_e32 v96, v96, v97
	v_mov_b32_e32 v236, v98
	v_mov_b32_e32 v237, v99
	v_mov_b32_e32 v238, v96
.LBB0_402:
	s_or_b64 exec, exec, s[36:37]
	s_nop 4
	v_permlane16_swap_b32 v236, v232
	v_permlane16_swap_b32 v237, v233
	v_permlane16_swap_b32 v238, v234
	s_mov_b64 s[36:37], exec
	s_mov_b64 exec, 0xffffffff
	global_store_dword v[236:237], v238, off
	s_mov_b64 exec, s[36:37]
	v_or_b32_e32 v114, 32, v166
	v_mov_b32_e32 v115, v167
	s_waitcnt lgkmcnt(0)
	v_lshlrev_b64 v[96:97], 12, v[114:115]
	v_lshl_add_u64 v[96:97], v[168:169], 0, v[96:97]
	global_load_dwordx4 v[118:121], v[96:97], off
	global_load_dwordx4 v[122:125], v[96:97], off offset:64
	global_load_dwordx4 v[126:129], v[96:97], off offset:512
	global_load_dwordx4 v[130:133], v[96:97], off offset:576
	v_or_b32_e32 v112, 48, v166
	v_mov_b32_e32 v113, v167
	v_lshlrev_b64 v[96:97], 12, v[112:113]
	v_lshl_add_u64 v[96:97], v[168:169], 0, v[96:97]
	global_load_dwordx4 v[108:111], v[96:97], off
	global_load_dwordx4 v[104:107], v[96:97], off offset:64
	global_load_dwordx4 v[100:103], v[96:97], off offset:512
	s_nop 0
	global_load_dwordx4 v[96:99], v[96:97], off offset:576
	v_lshlrev_b64 v[134:135], 10, v[114:115]
	v_lshl_add_u64 v[134:135], v[134:135], 0, v[164:165]
	s_waitcnt vmcnt(0)
	s_waitcnt vmcnt(0)
	v_pk_fma_f32 v[94:95], v[94:95], 0.5, v[120:121] op_sel_hi:[1,0,1]
	v_lshlrev_b64 v[120:121], 1, v[134:135]
	v_pk_fma_f32 v[92:93], v[92:93], 0.5, v[118:119] op_sel_hi:[1,0,1]
	v_lshl_add_u64 v[118:119], v[134:135], 2, s[78:79]
	v_lshl_add_u64 v[134:135], s[0:1], 0, v[120:121]
	global_store_dwordx4 v[118:119], v[92:95], off
	v_cvt_pk_bf16_f32 v136, v92, v93
	v_cvt_pk_bf16_f32 v137, v94, v95
	s_nop 1
	v_mov_b32_e32 v240, v136
	v_mov_b32_e32 v241, v137
	v_lshl_add_u64 v[244:245], v[134:135], 0, v[246:247]
	v_mul_f32_e32 v134, v92, v92
	v_fmac_f32_e32 v134, v93, v93
	v_pk_fma_f32 v[90:91], v[90:91], 0.5, v[124:125] op_sel_hi:[1,0,1]
	v_pk_fma_f32 v[88:89], v[88:89], 0.5, v[122:123] op_sel_hi:[1,0,1]
	v_fmac_f32_e32 v134, v94, v94
	global_store_dwordx4 v[118:119], v[88:91], off offset:64
	v_cvt_pk_bf16_f32 v94, v88, v89
	v_or_b32_e32 v92, 32, v120
	v_mov_b32_e32 v93, v121
	v_mul_f32_e32 v88, v88, v88
	v_fmac_f32_e32 v88, v89, v89
	v_fmac_f32_e32 v88, v90, v90
	v_fmac_f32_e32 v134, v95, v95
	v_lshl_add_u64 v[92:93], s[0:1], 0, v[92:93]
	v_fmac_f32_e32 v88, v91, v91
	v_pk_fma_f32 v[86:87], v[86:87], 0.5, v[128:129] op_sel_hi:[1,0,1]
	v_pk_fma_f32 v[84:85], v[84:85], 0.5, v[126:127] op_sel_hi:[1,0,1]
	v_cvt_pk_bf16_f32 v95, v90, v91
	v_mov_b32_e32 v242, v94
	v_mov_b32_e32 v243, v95
	s_nop 1
	v_permlane16_swap_b32 v240, v242
	v_permlane16_swap_b32 v241, v243
	global_store_dwordx4 v[244:245], v[240:243], off
	v_add_f32_e32 v92, v134, v88
	global_store_dwordx4 v[118:119], v[84:87], off offset:512
	v_or_b32_e32 v88, 0x100, v120
	v_mov_b32_e32 v89, v121
	v_cvt_pk_bf16_f32 v90, v84, v85
	v_mul_f32_e32 v84, v84, v84
	v_lshl_add_u64 v[88:89], s[0:1], 0, v[88:89]
	v_fmac_f32_e32 v84, v85, v85
	v_pk_fma_f32 v[82:83], v[82:83], 0.5, v[132:133] op_sel_hi:[1,0,1]
	v_pk_fma_f32 v[80:81], v[80:81], 0.5, v[130:131] op_sel_hi:[1,0,1]
	v_cvt_pk_bf16_f32 v91, v86, v87
	s_nop 1
	v_mov_b32_e32 v240, v90
	v_mov_b32_e32 v241, v91
	v_lshl_add_u64 v[244:245], v[88:89], 0, v[246:247]
	v_fmac_f32_e32 v84, v86, v86
	global_store_dwordx4 v[118:119], v[80:83], off offset:576
	v_cvt_pk_bf16_f32 v86, v80, v81
	v_fmac_f32_e32 v84, v87, v87
	v_add_f32_e32 v88, v92, v84
	v_mul_f32_e32 v80, v80, v80
	v_fmac_f32_e32 v80, v81, v81
	v_fmac_f32_e32 v80, v82, v82
	v_fmac_f32_e32 v80, v83, v83
	v_add_f32_e32 v80, v88, v80
	ds_bpermute_b32 v81, v116, v80
	v_or_b32_e32 v120, 0x120, v120
	v_lshl_add_u64 v[84:85], s[0:1], 0, v[120:121]
	v_cvt_pk_bf16_f32 v87, v82, v83
	v_mov_b32_e32 v242, v86
	v_mov_b32_e32 v243, v87
	s_nop 1
	v_permlane16_swap_b32 v240, v242
	v_permlane16_swap_b32 v241, v243
	global_store_dwordx4 v[244:245], v[240:243], off
	s_waitcnt lgkmcnt(0)
	v_add_f32_e32 v80, v80, v81
	ds_bpermute_b32 v81, v117, v80
	s_and_saveexec_b64 s[36:37], s[8:9]
	s_cbranch_execz .LBB0_404
	v_lshlrev_b64 v[82:83], 6, v[114:115]
	v_lshl_add_u64 v[82:83], s[2:3], 0, v[82:83]
	v_lshl_add_u64 v[82:83], s[16:17], 2, v[82:83]
	s_lshl_b32 s6, s83, 2
	v_lshl_add_u64 v[82:83], v[82:83], 0, s[6:7]
	s_waitcnt lgkmcnt(0)
	v_add_f32_e32 v80, v80, v81
	v_mov_b32_e32 v232, v82
	v_mov_b32_e32 v233, v83
	v_mov_b32_e32 v234, v80
.LBB0_404:
	s_or_b64 exec, exec, s[36:37]
	s_waitcnt lgkmcnt(0)
	v_lshlrev_b64 v[80:81], 10, v[112:113]
	v_lshl_add_u64 v[80:81], v[80:81], 0, v[164:165]
	v_lshl_add_u64 v[82:83], v[80:81], 2, s[78:79]
	v_lshlrev_b64 v[80:81], 1, v[80:81]
	v_pk_fma_f32 v[78:79], v[78:79], 0.5, v[110:111] op_sel_hi:[1,0,1]
	v_pk_fma_f32 v[76:77], v[76:77], 0.5, v[108:109] op_sel_hi:[1,0,1]
	v_lshl_add_u64 v[84:85], s[0:1], 0, v[80:81]
	global_store_dwordx4 v[82:83], v[76:79], off
	v_cvt_pk_bf16_f32 v86, v76, v77
	v_cvt_pk_bf16_f32 v87, v78, v79
	s_nop 1
	v_mov_b32_e32 v240, v86
	v_mov_b32_e32 v241, v87
	v_lshl_add_u64 v[244:245], v[84:85], 0, v[246:247]
	v_mul_f32_e32 v84, v76, v76
	v_fmac_f32_e32 v84, v77, v77
	v_pk_fma_f32 v[74:75], v[74:75], 0.5, v[106:107] op_sel_hi:[1,0,1]
	v_pk_fma_f32 v[72:73], v[72:73], 0.5, v[104:105] op_sel_hi:[1,0,1]
	v_fmac_f32_e32 v84, v78, v78
	global_store_dwordx4 v[82:83], v[72:75], off offset:64
	v_or_b32_e32 v76, 32, v80
	v_mov_b32_e32 v77, v81
	v_cvt_pk_bf16_f32 v78, v72, v73
	v_mul_f32_e32 v72, v72, v72
	v_lshl_add_u64 v[76:77], s[0:1], 0, v[76:77]
	v_fmac_f32_e32 v72, v73, v73
	v_pk_fma_f32 v[70:71], v[70:71], 0.5, v[102:103] op_sel_hi:[1,0,1]
	v_pk_fma_f32 v[68:69], v[68:69], 0.5, v[100:101] op_sel_hi:[1,0,1]
	v_fmac_f32_e32 v84, v79, v79
	v_cvt_pk_bf16_f32 v79, v74, v75
	v_mov_b32_e32 v242, v78
	v_mov_b32_e32 v243, v79
	s_nop 1
	v_permlane16_swap_b32 v240, v242
	v_permlane16_swap_b32 v241, v243
	global_store_dwordx4 v[244:245], v[240:243], off
	v_fmac_f32_e32 v72, v74, v74
	global_store_dwordx4 v[82:83], v[68:71], off offset:512
	v_cvt_pk_bf16_f32 v74, v68, v69
	v_fmac_f32_e32 v72, v75, v75
	v_add_f32_e32 v75, v84, v72
	v_mul_f32_e32 v68, v68, v68
	v_fmac_f32_e32 v68, v69, v69
	v_fmac_f32_e32 v68, v70, v70
	v_fmac_f32_e32 v68, v71, v71
	v_add_f32_e32 v75, v75, v68
	v_pk_fma_f32 v[68:69], v[66:67], 0.5, v[98:99] op_sel_hi:[1,0,1]
	v_pk_fma_f32 v[66:67], v[64:65], 0.5, v[96:97] op_sel_hi:[1,0,1]
	v_or_b32_e32 v72, 0x100, v80
	v_mul_f32_e32 v64, v66, v66
	v_fmac_f32_e32 v64, v67, v67
	v_fmac_f32_e32 v64, v68, v68
	v_fmac_f32_e32 v64, v69, v69
	v_add_f32_e32 v64, v75, v64
	ds_bpermute_b32 v65, v116, v64
	v_mov_b32_e32 v73, v81
	v_or_b32_e32 v80, 0x120, v80
	v_lshl_add_u64 v[72:73], s[0:1], 0, v[72:73]
	v_cvt_pk_bf16_f32 v75, v70, v71
	s_waitcnt lgkmcnt(0)
	v_add_f32_e32 v64, v64, v65
	ds_bpermute_b32 v65, v117, v64
	v_lshl_add_u64 v[70:71], s[0:1], 0, v[80:81]
	s_nop 1
	v_mov_b32_e32 v240, v74
	v_mov_b32_e32 v241, v75
	v_lshl_add_u64 v[244:245], v[72:73], 0, v[246:247]
	global_store_dwordx4 v[82:83], v[66:69], off offset:576
	s_nop 1
	v_cvt_pk_bf16_f32 v66, v66, v67
	v_cvt_pk_bf16_f32 v67, v68, v69
	v_mov_b32_e32 v242, v66
	v_mov_b32_e32 v243, v67
	s_nop 1
	v_permlane16_swap_b32 v240, v242
	v_permlane16_swap_b32 v241, v243
	global_store_dwordx4 v[244:245], v[240:243], off
	s_and_saveexec_b64 s[36:37], s[8:9]
	s_cbranch_execz .LBB0_406
	v_lshlrev_b64 v[66:67], 6, v[112:113]
	v_lshl_add_u64 v[66:67], s[2:3], 0, v[66:67]
	v_lshl_add_u64 v[66:67], s[16:17], 2, v[66:67]
	s_lshl_b32 s6, s83, 2
	v_lshl_add_u64 v[66:67], v[66:67], 0, s[6:7]
	s_waitcnt lgkmcnt(0)
	v_add_f32_e32 v64, v64, v65
	v_mov_b32_e32 v236, v66
	v_mov_b32_e32 v237, v67
	v_mov_b32_e32 v238, v64
.LBB0_406:
	s_or_b64 exec, exec, s[36:37]
	s_nop 4
	v_permlane16_swap_b32 v236, v232
	v_permlane16_swap_b32 v237, v233
	v_permlane16_swap_b32 v238, v234
	s_mov_b64 s[36:37], exec
	s_mov_b64 exec, 0xffffffff
	global_store_dword v[236:237], v238, off
	s_mov_b64 exec, s[36:37]
	v_lshl_add_u64 v[82:83], v[166:167], 0, s[4:5]
	s_waitcnt lgkmcnt(0)
	v_lshlrev_b64 v[64:65], 12, v[82:83]
	v_lshl_add_u64 v[64:65], v[168:169], 0, v[64:65]
	global_load_dwordx4 v[84:87], v[64:65], off
	global_load_dwordx4 v[88:91], v[64:65], off offset:64
	global_load_dwordx4 v[92:95], v[64:65], off offset:512
	global_load_dwordx4 v[96:99], v[64:65], off offset:576
	s_mov_b64 s[18:19], 0x90
	v_lshl_add_u64 v[80:81], v[166:167], 0, s[18:19]
	v_lshlrev_b64 v[64:65], 12, v[80:81]
	v_lshl_add_u64 v[64:65], v[168:169], 0, v[64:65]
	global_load_dwordx4 v[76:79], v[64:65], off
	global_load_dwordx4 v[72:75], v[64:65], off offset:64
	global_load_dwordx4 v[68:71], v[64:65], off offset:512
	s_nop 0
	global_load_dwordx4 v[64:67], v[64:65], off offset:576
	v_lshlrev_b64 v[100:101], 10, v[82:83]
	v_lshl_add_u64 v[100:101], v[100:101], 0, v[164:165]
	s_waitcnt vmcnt(0)
	s_waitcnt vmcnt(0)
	v_pk_fma_f32 v[62:63], v[62:63], 0.5, v[86:87] op_sel_hi:[1,0,1]
	v_lshlrev_b64 v[86:87], 1, v[100:101]
	v_pk_fma_f32 v[60:61], v[60:61], 0.5, v[84:85] op_sel_hi:[1,0,1]
	v_lshl_add_u64 v[84:85], v[100:101], 2, s[78:79]
	v_lshl_add_u64 v[100:101], s[0:1], 0, v[86:87]
	global_store_dwordx4 v[84:85], v[60:63], off
	v_cvt_pk_bf16_f32 v102, v60, v61
	v_cvt_pk_bf16_f32 v103, v62, v63
	s_nop 1
	v_mov_b32_e32 v240, v102
	v_mov_b32_e32 v241, v103
	v_lshl_add_u64 v[244:245], v[100:101], 0, v[246:247]
	v_mul_f32_e32 v100, v60, v60
	v_fmac_f32_e32 v100, v61, v61
	v_pk_fma_f32 v[58:59], v[58:59], 0.5, v[90:91] op_sel_hi:[1,0,1]
	v_pk_fma_f32 v[56:57], v[56:57], 0.5, v[88:89] op_sel_hi:[1,0,1]
	v_fmac_f32_e32 v100, v62, v62
	global_store_dwordx4 v[84:85], v[56:59], off offset:64
	v_cvt_pk_bf16_f32 v62, v56, v57
	v_or_b32_e32 v60, 32, v86
	v_mov_b32_e32 v61, v87
	v_mul_f32_e32 v56, v56, v56
	v_fmac_f32_e32 v56, v57, v57
	v_fmac_f32_e32 v56, v58, v58
	v_fmac_f32_e32 v100, v63, v63
	v_lshl_add_u64 v[60:61], s[0:1], 0, v[60:61]
	v_fmac_f32_e32 v56, v59, v59
	v_pk_fma_f32 v[54:55], v[54:55], 0.5, v[94:95] op_sel_hi:[1,0,1]
	v_pk_fma_f32 v[52:53], v[52:53], 0.5, v[92:93] op_sel_hi:[1,0,1]
	v_cvt_pk_bf16_f32 v63, v58, v59
	v_mov_b32_e32 v242, v62
	v_mov_b32_e32 v243, v63
	s_nop 1
	v_permlane16_swap_b32 v240, v242
	v_permlane16_swap_b32 v241, v243
	global_store_dwordx4 v[244:245], v[240:243], off
	v_add_f32_e32 v60, v100, v56
	global_store_dwordx4 v[84:85], v[52:55], off offset:512
	v_or_b32_e32 v56, 0x100, v86
	v_mov_b32_e32 v57, v87
	v_cvt_pk_bf16_f32 v58, v52, v53
	v_mul_f32_e32 v52, v52, v52
	v_lshl_add_u64 v[56:57], s[0:1], 0, v[56:57]
	v_fmac_f32_e32 v52, v53, v53
	v_pk_fma_f32 v[50:51], v[50:51], 0.5, v[98:99] op_sel_hi:[1,0,1]
	v_pk_fma_f32 v[48:49], v[48:49], 0.5, v[96:97] op_sel_hi:[1,0,1]
	v_cvt_pk_bf16_f32 v59, v54, v55
	s_nop 1
	v_mov_b32_e32 v240, v58
	v_mov_b32_e32 v241, v59
	v_lshl_add_u64 v[244:245], v[56:57], 0, v[246:247]
	v_fmac_f32_e32 v52, v54, v54
	global_store_dwordx4 v[84:85], v[48:51], off offset:576
	v_cvt_pk_bf16_f32 v54, v48, v49
	v_fmac_f32_e32 v52, v55, v55
	v_add_f32_e32 v56, v60, v52
	v_mul_f32_e32 v48, v48, v48
	v_fmac_f32_e32 v48, v49, v49
	v_fmac_f32_e32 v48, v50, v50
	v_fmac_f32_e32 v48, v51, v51
	v_add_f32_e32 v48, v56, v48
	ds_bpermute_b32 v49, v116, v48
	v_or_b32_e32 v86, 0x120, v86
	v_lshl_add_u64 v[52:53], s[0:1], 0, v[86:87]
	v_cvt_pk_bf16_f32 v55, v50, v51
	v_mov_b32_e32 v242, v54
	v_mov_b32_e32 v243, v55
	s_nop 1
	v_permlane16_swap_b32 v240, v242
	v_permlane16_swap_b32 v241, v243
	global_store_dwordx4 v[244:245], v[240:243], off
	s_waitcnt lgkmcnt(0)
	v_add_f32_e32 v48, v48, v49
	ds_bpermute_b32 v49, v117, v48
	s_and_saveexec_b64 s[36:37], s[8:9]
	s_cbranch_execz .LBB0_408
	v_lshlrev_b64 v[50:51], 6, v[82:83]
	v_lshl_add_u64 v[50:51], s[2:3], 0, v[50:51]
	v_lshl_add_u64 v[50:51], s[16:17], 2, v[50:51]
	s_lshl_b32 s6, s83, 2
	v_lshl_add_u64 v[50:51], v[50:51], 0, s[6:7]
	s_waitcnt lgkmcnt(0)
	v_add_f32_e32 v48, v48, v49
	v_mov_b32_e32 v232, v50
	v_mov_b32_e32 v233, v51
	v_mov_b32_e32 v234, v48
.LBB0_408:
	s_or_b64 exec, exec, s[36:37]
	s_waitcnt lgkmcnt(0)
	v_lshlrev_b64 v[48:49], 10, v[80:81]
	v_lshl_add_u64 v[48:49], v[48:49], 0, v[164:165]
	v_lshl_add_u64 v[50:51], v[48:49], 2, s[78:79]
	v_lshlrev_b64 v[48:49], 1, v[48:49]
	v_pk_fma_f32 v[46:47], v[46:47], 0.5, v[78:79] op_sel_hi:[1,0,1]
	v_pk_fma_f32 v[44:45], v[44:45], 0.5, v[76:77] op_sel_hi:[1,0,1]
	v_lshl_add_u64 v[52:53], s[0:1], 0, v[48:49]
	global_store_dwordx4 v[50:51], v[44:47], off
	v_cvt_pk_bf16_f32 v54, v44, v45
	v_cvt_pk_bf16_f32 v55, v46, v47
	s_nop 1
	v_mov_b32_e32 v240, v54
	v_mov_b32_e32 v241, v55
	v_lshl_add_u64 v[244:245], v[52:53], 0, v[246:247]
	v_mul_f32_e32 v52, v44, v44
	v_fmac_f32_e32 v52, v45, v45
	v_pk_fma_f32 v[42:43], v[42:43], 0.5, v[74:75] op_sel_hi:[1,0,1]
	v_pk_fma_f32 v[40:41], v[40:41], 0.5, v[72:73] op_sel_hi:[1,0,1]
	v_fmac_f32_e32 v52, v46, v46
	global_store_dwordx4 v[50:51], v[40:43], off offset:64
	v_or_b32_e32 v44, 32, v48
	v_mov_b32_e32 v45, v49
	v_cvt_pk_bf16_f32 v46, v40, v41
	v_mul_f32_e32 v40, v40, v40
	v_lshl_add_u64 v[44:45], s[0:1], 0, v[44:45]
	v_fmac_f32_e32 v40, v41, v41
	v_pk_fma_f32 v[38:39], v[38:39], 0.5, v[70:71] op_sel_hi:[1,0,1]
	v_pk_fma_f32 v[36:37], v[36:37], 0.5, v[68:69] op_sel_hi:[1,0,1]
	v_fmac_f32_e32 v52, v47, v47
	v_cvt_pk_bf16_f32 v47, v42, v43
	v_mov_b32_e32 v242, v46
	v_mov_b32_e32 v243, v47
	s_nop 1
	v_permlane16_swap_b32 v240, v242
	v_permlane16_swap_b32 v241, v243
	global_store_dwordx4 v[244:245], v[240:243], off
	v_fmac_f32_e32 v40, v42, v42
	global_store_dwordx4 v[50:51], v[36:39], off offset:512
	v_cvt_pk_bf16_f32 v42, v36, v37
	v_fmac_f32_e32 v40, v43, v43
	v_add_f32_e32 v43, v52, v40
	v_mul_f32_e32 v36, v36, v36
	v_fmac_f32_e32 v36, v37, v37
	v_fmac_f32_e32 v36, v38, v38
	v_fmac_f32_e32 v36, v39, v39
	v_add_f32_e32 v43, v43, v36
	v_pk_fma_f32 v[36:37], v[34:35], 0.5, v[66:67] op_sel_hi:[1,0,1]
	v_pk_fma_f32 v[34:35], v[32:33], 0.5, v[64:65] op_sel_hi:[1,0,1]
	v_or_b32_e32 v40, 0x100, v48
	v_mul_f32_e32 v32, v34, v34
	v_fmac_f32_e32 v32, v35, v35
	v_fmac_f32_e32 v32, v36, v36
	v_fmac_f32_e32 v32, v37, v37
	v_add_f32_e32 v32, v43, v32
	ds_bpermute_b32 v33, v116, v32
	v_mov_b32_e32 v41, v49
	v_or_b32_e32 v48, 0x120, v48
	v_lshl_add_u64 v[40:41], s[0:1], 0, v[40:41]
	v_cvt_pk_bf16_f32 v43, v38, v39
	s_waitcnt lgkmcnt(0)
	v_add_f32_e32 v32, v32, v33
	ds_bpermute_b32 v33, v117, v32
	v_lshl_add_u64 v[38:39], s[0:1], 0, v[48:49]
	s_nop 1
	v_mov_b32_e32 v240, v42
	v_mov_b32_e32 v241, v43
	v_lshl_add_u64 v[244:245], v[40:41], 0, v[246:247]
	global_store_dwordx4 v[50:51], v[34:37], off offset:576
	s_nop 1
	v_cvt_pk_bf16_f32 v34, v34, v35
	v_cvt_pk_bf16_f32 v35, v36, v37
	v_mov_b32_e32 v242, v34
	v_mov_b32_e32 v243, v35
	s_nop 1
	v_permlane16_swap_b32 v240, v242
	v_permlane16_swap_b32 v241, v243
	global_store_dwordx4 v[244:245], v[240:243], off
	s_and_saveexec_b64 s[36:37], s[8:9]
	s_cbranch_execz .LBB0_410
	v_lshlrev_b64 v[34:35], 6, v[80:81]
	v_lshl_add_u64 v[34:35], s[2:3], 0, v[34:35]
	v_lshl_add_u64 v[34:35], s[16:17], 2, v[34:35]
	s_lshl_b32 s6, s83, 2
	v_lshl_add_u64 v[34:35], v[34:35], 0, s[6:7]
	s_waitcnt lgkmcnt(0)
	v_add_f32_e32 v32, v32, v33
	v_mov_b32_e32 v236, v34
	v_mov_b32_e32 v237, v35
	v_mov_b32_e32 v238, v32
.LBB0_410:
	s_or_b64 exec, exec, s[36:37]
	s_nop 4
	v_permlane16_swap_b32 v236, v232
	v_permlane16_swap_b32 v237, v233
	v_permlane16_swap_b32 v238, v234
	s_mov_b64 s[36:37], exec
	s_mov_b64 exec, 0xffffffff
	global_store_dword v[236:237], v238, off
	s_mov_b64 exec, s[36:37]
	s_mov_b64 s[18:19], 0xa0
	v_lshl_add_u64 v[50:51], v[166:167], 0, s[18:19]
	s_waitcnt lgkmcnt(0)
	v_lshlrev_b64 v[32:33], 12, v[50:51]
	v_lshl_add_u64 v[32:33], v[168:169], 0, v[32:33]
	global_load_dwordx4 v[52:55], v[32:33], off
	global_load_dwordx4 v[56:59], v[32:33], off offset:64
	global_load_dwordx4 v[60:63], v[32:33], off offset:512
	global_load_dwordx4 v[64:67], v[32:33], off offset:576
	s_mov_b64 s[18:19], 0xb0
	v_lshl_add_u64 v[48:49], v[166:167], 0, s[18:19]
	v_lshlrev_b64 v[32:33], 12, v[48:49]
	v_lshl_add_u64 v[32:33], v[168:169], 0, v[32:33]
	global_load_dwordx4 v[44:47], v[32:33], off
	global_load_dwordx4 v[40:43], v[32:33], off offset:64
	global_load_dwordx4 v[36:39], v[32:33], off offset:512
	s_nop 0
	global_load_dwordx4 v[32:35], v[32:33], off offset:576
	v_lshlrev_b64 v[68:69], 10, v[50:51]
	v_lshl_add_u64 v[68:69], v[68:69], 0, v[164:165]
	s_waitcnt vmcnt(0)
	s_waitcnt vmcnt(0)
	v_pk_fma_f32 v[30:31], v[30:31], 0.5, v[54:55] op_sel_hi:[1,0,1]
	v_lshlrev_b64 v[54:55], 1, v[68:69]
	v_pk_fma_f32 v[28:29], v[28:29], 0.5, v[52:53] op_sel_hi:[1,0,1]
	v_lshl_add_u64 v[52:53], v[68:69], 2, s[78:79]
	v_lshl_add_u64 v[68:69], s[0:1], 0, v[54:55]
	global_store_dwordx4 v[52:53], v[28:31], off
	v_cvt_pk_bf16_f32 v70, v28, v29
	v_cvt_pk_bf16_f32 v71, v30, v31
	s_nop 1
	v_mov_b32_e32 v240, v70
	v_mov_b32_e32 v241, v71
	v_lshl_add_u64 v[244:245], v[68:69], 0, v[246:247]
	v_mul_f32_e32 v68, v28, v28
	v_fmac_f32_e32 v68, v29, v29
	v_pk_fma_f32 v[26:27], v[26:27], 0.5, v[58:59] op_sel_hi:[1,0,1]
	v_pk_fma_f32 v[24:25], v[24:25], 0.5, v[56:57] op_sel_hi:[1,0,1]
	v_fmac_f32_e32 v68, v30, v30
	global_store_dwordx4 v[52:53], v[24:27], off offset:64
	v_cvt_pk_bf16_f32 v30, v24, v25
	v_or_b32_e32 v28, 32, v54
	v_mov_b32_e32 v29, v55
	v_mul_f32_e32 v24, v24, v24
	v_fmac_f32_e32 v24, v25, v25
	v_fmac_f32_e32 v24, v26, v26
	v_fmac_f32_e32 v68, v31, v31
	v_lshl_add_u64 v[28:29], s[0:1], 0, v[28:29]
	v_fmac_f32_e32 v24, v27, v27
	v_pk_fma_f32 v[22:23], v[22:23], 0.5, v[62:63] op_sel_hi:[1,0,1]
	v_pk_fma_f32 v[20:21], v[20:21], 0.5, v[60:61] op_sel_hi:[1,0,1]
	v_cvt_pk_bf16_f32 v31, v26, v27
	v_mov_b32_e32 v242, v30
	v_mov_b32_e32 v243, v31
	s_nop 1
	v_permlane16_swap_b32 v240, v242
	v_permlane16_swap_b32 v241, v243
	global_store_dwordx4 v[244:245], v[240:243], off
	v_add_f32_e32 v28, v68, v24
	global_store_dwordx4 v[52:53], v[20:23], off offset:512
	v_or_b32_e32 v24, 0x100, v54
	v_mov_b32_e32 v25, v55
	v_cvt_pk_bf16_f32 v26, v20, v21
	v_mul_f32_e32 v20, v20, v20
	v_lshl_add_u64 v[24:25], s[0:1], 0, v[24:25]
	v_fmac_f32_e32 v20, v21, v21
	v_pk_fma_f32 v[18:19], v[18:19], 0.5, v[66:67] op_sel_hi:[1,0,1]
	v_pk_fma_f32 v[16:17], v[16:17], 0.5, v[64:65] op_sel_hi:[1,0,1]
	v_cvt_pk_bf16_f32 v27, v22, v23
	s_nop 1
	v_mov_b32_e32 v240, v26
	v_mov_b32_e32 v241, v27
	v_lshl_add_u64 v[244:245], v[24:25], 0, v[246:247]
	v_fmac_f32_e32 v20, v22, v22
	global_store_dwordx4 v[52:53], v[16:19], off offset:576
	v_cvt_pk_bf16_f32 v22, v16, v17
	v_fmac_f32_e32 v20, v23, v23
	v_add_f32_e32 v24, v28, v20
	v_mul_f32_e32 v16, v16, v16
	v_fmac_f32_e32 v16, v17, v17
	v_fmac_f32_e32 v16, v18, v18
	v_fmac_f32_e32 v16, v19, v19
	v_add_f32_e32 v16, v24, v16
	ds_bpermute_b32 v17, v116, v16
	v_or_b32_e32 v54, 0x120, v54
	v_lshl_add_u64 v[20:21], s[0:1], 0, v[54:55]
	v_cvt_pk_bf16_f32 v23, v18, v19
	v_mov_b32_e32 v242, v22
	v_mov_b32_e32 v243, v23
	s_nop 1
	v_permlane16_swap_b32 v240, v242
	v_permlane16_swap_b32 v241, v243
	global_store_dwordx4 v[244:245], v[240:243], off
	s_waitcnt lgkmcnt(0)
	v_add_f32_e32 v16, v16, v17
	ds_bpermute_b32 v17, v117, v16
	s_and_saveexec_b64 s[36:37], s[8:9]
	s_cbranch_execz .LBB0_412
	v_lshlrev_b64 v[18:19], 6, v[50:51]
	v_lshl_add_u64 v[18:19], s[2:3], 0, v[18:19]
	v_lshl_add_u64 v[18:19], s[16:17], 2, v[18:19]
	s_lshl_b32 s6, s83, 2
	v_lshl_add_u64 v[18:19], v[18:19], 0, s[6:7]
	s_waitcnt lgkmcnt(0)
	v_add_f32_e32 v16, v16, v17
	flat_store_dword v[18:19], v16

.LBB0_1480:
	ds_read_b128 v[128:131], v170
	ds_read_b128 v[132:135], v171
	ds_read_b128 v[136:139], v172
	ds_read_b128 v[140:143], v173
	s_add_u32 s34, s30, 0xfffc0080
	s_addc_u32 s35, s31, -1
	s_cmp_eq_u32 s69, 12
	s_cselect_b32 s37, s23, s35
	s_cselect_b32 s36, s29, s34
	s_cselect_b32 s35, s21, s68
	s_cselect_b32 s34, s66, s67
	s_mov_b32 m0, s63
	v_lshl_add_u64 v[214:215], s[30:31], 0, v[156:157]
	ds_read_b128 v[162:165], v151
	ds_read_b128 v[166:169], v151 offset:1024
	ds_read_b128 v[190:193], v151 offset:2048
	ds_read_b128 v[194:197], v151 offset:3072
	ds_read_b128 v[198:201], v151 offset:4096
	ds_read_b128 v[202:205], v151 offset:5120
	ds_read_b128 v[206:209], v151 offset:6144
	ds_read_b128 v[210:213], v151 offset:7168
	global_load_lds_dwordx4 v[214:215], off
	v_lshl_add_u64 v[214:215], s[30:31], 0, v[154:155]
	s_mov_b32 m0, s64
	s_nop 0
	global_load_lds_dwordx4 v[214:215], off
	s_waitcnt lgkmcnt(8)
	s_barrier
	s_waitcnt lgkmcnt(0)
	s_setprio 1
	s_waitcnt lgkmcnt(0)
	v_mfma_f32_16x16x32_bf16 v[124:127], v[128:131], v[162:165], v[124:127]
	v_mfma_f32_16x16x32_bf16 v[120:123], v[136:139], v[162:165], v[120:123]
	v_mfma_f32_16x16x32_bf16 v[108:111], v[128:131], v[190:193], v[108:111]
	v_mfma_f32_16x16x32_bf16 v[104:107], v[136:139], v[190:193], v[104:107]
	v_mfma_f32_16x16x32_bf16 v[92:95], v[128:131], v[198:201], v[92:95]
	v_mfma_f32_16x16x32_bf16 v[88:91], v[136:139], v[198:201], v[88:91]
	v_mfma_f32_16x16x32_bf16 v[76:79], v[128:131], v[206:209], v[76:79]
	v_mfma_f32_16x16x32_bf16 v[72:75], v[136:139], v[206:209], v[72:75]
	v_mfma_f32_16x16x32_bf16 v[124:127], v[132:135], v[166:169], v[124:127]
	v_mfma_f32_16x16x32_bf16 v[120:123], v[140:143], v[166:169], v[120:123]
	v_mfma_f32_16x16x32_bf16 v[108:111], v[132:135], v[194:197], v[108:111]
	v_mfma_f32_16x16x32_bf16 v[104:107], v[140:143], v[194:197], v[104:107]
	v_mfma_f32_16x16x32_bf16 v[92:95], v[132:135], v[202:205], v[92:95]
	v_mfma_f32_16x16x32_bf16 v[88:91], v[140:143], v[202:205], v[88:91]
	v_mfma_f32_16x16x32_bf16 v[76:79], v[132:135], v[210:213], v[76:79]
	v_mfma_f32_16x16x32_bf16 v[72:75], v[140:143], v[210:213], v[72:75]
	s_setprio 0
	s_barrier
	s_mov_b32 m0, s46
	v_lshl_add_u64 v[230:231], s[34:35], 0, v[144:145]
	ds_read_b128 v[214:217], v174
	ds_read_b128 v[218:221], v175
	ds_read_b128 v[222:225], v177
	ds_read_b128 v[226:229], v178
	global_load_lds_dwordx4 v[230:231], off
	v_lshl_add_u64 v[232:233], s[34:35], 0, v[146:147]
	s_mov_b32 m0, s47
	s_nop 0
	global_load_lds_dwordx4 v[232:233], off
	s_barrier
	s_waitcnt lgkmcnt(0)
	s_setprio 1
	s_waitcnt lgkmcnt(0)
	v_mfma_f32_16x16x32_bf16 v[116:119], v[214:217], v[162:165], v[116:119]
	v_mfma_f32_16x16x32_bf16 v[112:115], v[222:225], v[162:165], v[112:115]
	v_mfma_f32_16x16x32_bf16 v[100:103], v[214:217], v[190:193], v[100:103]
	v_mfma_f32_16x16x32_bf16 v[96:99], v[222:225], v[190:193], v[96:99]
	v_mfma_f32_16x16x32_bf16 v[84:87], v[214:217], v[198:201], v[84:87]
	v_mfma_f32_16x16x32_bf16 v[80:83], v[222:225], v[198:201], v[80:83]
	v_mfma_f32_16x16x32_bf16 v[68:71], v[214:217], v[206:209], v[68:71]
	v_mfma_f32_16x16x32_bf16 v[64:67], v[222:225], v[206:209], v[64:67]
	v_mfma_f32_16x16x32_bf16 v[116:119], v[218:221], v[166:169], v[116:119]
	v_mfma_f32_16x16x32_bf16 v[112:115], v[226:229], v[166:169], v[112:115]
	v_mfma_f32_16x16x32_bf16 v[100:103], v[218:221], v[194:197], v[100:103]
	v_mfma_f32_16x16x32_bf16 v[96:99], v[226:229], v[194:197], v[96:99]
	v_mfma_f32_16x16x32_bf16 v[84:87], v[218:221], v[202:205], v[84:87]
	v_mfma_f32_16x16x32_bf16 v[80:83], v[226:229], v[202:205], v[80:83]
	v_mfma_f32_16x16x32_bf16 v[68:71], v[218:221], v[210:213], v[68:71]
	v_mfma_f32_16x16x32_bf16 v[64:67], v[226:229], v[210:213], v[64:67]
	s_setprio 0
	s_mov_b32 m0, s45
	v_lshl_add_u64 v[234:235], s[36:37], 0, v[144:145]
	s_barrier
	ds_read_b128 v[162:165], v151 offset:16384
	ds_read_b128 v[166:169], v151 offset:17408
	ds_read_b128 v[190:193], v151 offset:18432
	ds_read_b128 v[194:197], v151 offset:19456
	ds_read_b128 v[198:201], v151 offset:20480
	ds_read_b128 v[202:205], v151 offset:21504
	ds_read_b128 v[206:209], v151 offset:22528
	ds_read_b128 v[210:213], v151 offset:23552
	global_load_lds_dwordx4 v[234:235], off
	v_lshl_add_u64 v[236:237], s[36:37], 0, v[146:147]
	s_mov_b32 m0, s48
	s_nop 0
	global_load_lds_dwordx4 v[236:237], off
	s_barrier
	s_waitcnt lgkmcnt(0)
	s_setprio 1
	s_waitcnt lgkmcnt(0)
	v_mfma_f32_16x16x32_bf16 v[60:63], v[128:131], v[162:165], v[60:63]
	v_mfma_f32_16x16x32_bf16 v[56:59], v[136:139], v[162:165], v[56:59]
	v_mfma_f32_16x16x32_bf16 v[44:47], v[128:131], v[190:193], v[44:47]
	v_mfma_f32_16x16x32_bf16 v[40:43], v[136:139], v[190:193], v[40:43]
	v_mfma_f32_16x16x32_bf16 v[28:31], v[128:131], v[198:201], v[28:31]
	v_mfma_f32_16x16x32_bf16 v[24:27], v[136:139], v[198:201], v[24:27]
	v_mfma_f32_16x16x32_bf16 v[12:15], v[128:131], v[206:209], v[12:15]
	v_mfma_f32_16x16x32_bf16 v[8:11], v[136:139], v[206:209], v[8:11]
	v_mfma_f32_16x16x32_bf16 v[60:63], v[132:135], v[166:169], v[60:63]
	v_mfma_f32_16x16x32_bf16 v[56:59], v[140:143], v[166:169], v[56:59]
	v_mfma_f32_16x16x32_bf16 v[44:47], v[132:135], v[194:197], v[44:47]
	v_mfma_f32_16x16x32_bf16 v[40:43], v[140:143], v[194:197], v[40:43]
	v_mfma_f32_16x16x32_bf16 v[28:31], v[132:135], v[202:205], v[28:31]
	v_mfma_f32_16x16x32_bf16 v[24:27], v[140:143], v[202:205], v[24:27]
	v_mfma_f32_16x16x32_bf16 v[12:15], v[132:135], v[210:213], v[12:15]
	v_mfma_f32_16x16x32_bf16 v[8:11], v[140:143], v[210:213], v[8:11]
	s_setprio 0
	s_barrier
	s_add_u32 s70, s34, 0x40000
	s_addc_u32 s71, s35, 0
	s_mov_b32 m0, s49
	v_lshl_add_u64 v[128:129], s[70:71], 0, v[144:145]
	global_load_lds_dwordx4 v[128:129], off
	v_lshl_add_u64 v[128:129], s[70:71], 0, v[146:147]
	s_mov_b32 m0, s52
	s_nop 0
	global_load_lds_dwordx4 v[128:129], off
	s_waitcnt vmcnt(6)
	s_barrier
	s_setprio 1
	v_mfma_f32_16x16x32_bf16 v[52:55], v[214:217], v[162:165], v[52:55]
	v_mfma_f32_16x16x32_bf16 v[48:51], v[222:225], v[162:165], v[48:51]
	v_mfma_f32_16x16x32_bf16 v[36:39], v[214:217], v[190:193], v[36:39]
	v_mfma_f32_16x16x32_bf16 v[32:35], v[222:225], v[190:193], v[32:35]
	v_mfma_f32_16x16x32_bf16 v[20:23], v[214:217], v[198:201], v[20:23]
	v_mfma_f32_16x16x32_bf16 v[16:19], v[222:225], v[198:201], v[16:19]
	v_mfma_f32_16x16x32_bf16 v[4:7], v[214:217], v[206:209], v[4:7]
	v_mfma_f32_16x16x32_bf16 v[0:3], v[222:225], v[206:209], v[0:3]
	v_mfma_f32_16x16x32_bf16 v[52:55], v[218:221], v[166:169], v[52:55]
	v_mfma_f32_16x16x32_bf16 v[48:51], v[226:229], v[166:169], v[48:51]
	v_mfma_f32_16x16x32_bf16 v[36:39], v[218:221], v[194:197], v[36:39]
	v_mfma_f32_16x16x32_bf16 v[32:35], v[226:229], v[194:197], v[32:35]
	v_mfma_f32_16x16x32_bf16 v[20:23], v[218:221], v[202:205], v[20:23]
	v_mfma_f32_16x16x32_bf16 v[16:19], v[226:229], v[202:205], v[16:19]
	v_mfma_f32_16x16x32_bf16 v[4:7], v[218:221], v[210:213], v[4:7]
	v_mfma_f32_16x16x32_bf16 v[0:3], v[226:229], v[210:213], v[0:3]
	s_setprio 0
	s_barrier
	ds_read_b128 v[128:131], v180
	ds_read_b128 v[132:135], v181
	ds_read_b128 v[136:139], v182
	ds_read_b128 v[140:143], v183
	s_add_u32 s36, s36, 0x40000
	s_addc_u32 s37, s37, 0
	s_mov_b32 m0, s53
	v_lshl_add_u64 v[214:215], s[36:37], 0, v[144:145]
	ds_read_b128 v[162:165], v151 offset:32768
	ds_read_b128 v[166:169], v151 offset:33792
	ds_read_b128 v[190:193], v151 offset:34816
	ds_read_b128 v[194:197], v151 offset:35840
	ds_read_b128 v[198:201], v151 offset:36864
	ds_read_b128 v[202:205], v151 offset:37888
	ds_read_b128 v[206:209], v151 offset:38912
	ds_read_b128 v[210:213], v151 offset:39936
	global_load_lds_dwordx4 v[214:215], off
	v_lshl_add_u64 v[214:215], s[36:37], 0, v[146:147]
	s_mov_b32 m0, s54
	s_nop 0
	global_load_lds_dwordx4 v[214:215], off
	s_waitcnt lgkmcnt(8)
	s_barrier
	s_waitcnt lgkmcnt(0)
	s_setprio 1
	s_waitcnt lgkmcnt(0)
	v_mfma_f32_16x16x32_bf16 v[124:127], v[128:131], v[162:165], v[124:127]
	v_mfma_f32_16x16x32_bf16 v[120:123], v[136:139], v[162:165], v[120:123]
	v_mfma_f32_16x16x32_bf16 v[108:111], v[128:131], v[190:193], v[108:111]
	v_mfma_f32_16x16x32_bf16 v[104:107], v[136:139], v[190:193], v[104:107]
	v_mfma_f32_16x16x32_bf16 v[92:95], v[128:131], v[198:201], v[92:95]
	v_mfma_f32_16x16x32_bf16 v[88:91], v[136:139], v[198:201], v[88:91]
	v_mfma_f32_16x16x32_bf16 v[76:79], v[128:131], v[206:209], v[76:79]
	v_mfma_f32_16x16x32_bf16 v[72:75], v[136:139], v[206:209], v[72:75]
	v_mfma_f32_16x16x32_bf16 v[124:127], v[132:135], v[166:169], v[124:127]
	v_mfma_f32_16x16x32_bf16 v[120:123], v[140:143], v[166:169], v[120:123]
	v_mfma_f32_16x16x32_bf16 v[108:111], v[132:135], v[194:197], v[108:111]
	v_mfma_f32_16x16x32_bf16 v[104:107], v[140:143], v[194:197], v[104:107]
	v_mfma_f32_16x16x32_bf16 v[92:95], v[132:135], v[202:205], v[92:95]
	v_mfma_f32_16x16x32_bf16 v[88:91], v[140:143], v[202:205], v[88:91]
	v_mfma_f32_16x16x32_bf16 v[76:79], v[132:135], v[210:213], v[76:79]
	v_mfma_f32_16x16x32_bf16 v[72:75], v[140:143], v[210:213], v[72:75]
	s_setprio 0
	s_barrier
	s_mov_b32 m0, s56
	v_lshl_add_u64 v[230:231], v[230:231], 0, s[10:11]
	ds_read_b128 v[214:217], v184
	ds_read_b128 v[218:221], v185
	ds_read_b128 v[222:225], v186
	ds_read_b128 v[226:229], v187
	global_load_lds_dwordx4 v[230:231], off
	v_lshl_add_u64 v[230:231], v[232:233], 0, s[10:11]
	s_mov_b32 m0, s57
	s_nop 0
	global_load_lds_dwordx4 v[230:231], off
	s_barrier
	s_waitcnt lgkmcnt(0)
	s_setprio 1
	s_waitcnt lgkmcnt(0)
	v_mfma_f32_16x16x32_bf16 v[116:119], v[214:217], v[162:165], v[116:119]
	v_mfma_f32_16x16x32_bf16 v[112:115], v[222:225], v[162:165], v[112:115]
	v_mfma_f32_16x16x32_bf16 v[100:103], v[214:217], v[190:193], v[100:103]
	v_mfma_f32_16x16x32_bf16 v[96:99], v[222:225], v[190:193], v[96:99]
	v_mfma_f32_16x16x32_bf16 v[84:87], v[214:217], v[198:201], v[84:87]
	v_mfma_f32_16x16x32_bf16 v[80:83], v[222:225], v[198:201], v[80:83]
	v_mfma_f32_16x16x32_bf16 v[68:71], v[214:217], v[206:209], v[68:71]
	v_mfma_f32_16x16x32_bf16 v[64:67], v[222:225], v[206:209], v[64:67]
	v_mfma_f32_16x16x32_bf16 v[116:119], v[218:221], v[166:169], v[116:119]
	v_mfma_f32_16x16x32_bf16 v[112:115], v[226:229], v[166:169], v[112:115]
	v_mfma_f32_16x16x32_bf16 v[100:103], v[218:221], v[194:197], v[100:103]
	v_mfma_f32_16x16x32_bf16 v[96:99], v[226:229], v[194:197], v[96:99]
	v_mfma_f32_16x16x32_bf16 v[84:87], v[218:221], v[202:205], v[84:87]
	v_mfma_f32_16x16x32_bf16 v[80:83], v[226:229], v[202:205], v[80:83]
	v_mfma_f32_16x16x32_bf16 v[68:71], v[218:221], v[210:213], v[68:71]
	v_mfma_f32_16x16x32_bf16 v[64:67], v[226:229], v[210:213], v[64:67]
	s_setprio 0
	s_mov_b32 m0, s58
	v_lshl_add_u64 v[230:231], v[234:235], 0, s[10:11]
	s_barrier
	ds_read_b128 v[162:165], v151 offset:49152
	ds_read_b128 v[166:169], v151 offset:50176
	ds_read_b128 v[190:193], v151 offset:51200
	ds_read_b128 v[194:197], v151 offset:52224
	ds_read_b128 v[198:201], v151 offset:53248
	ds_read_b128 v[202:205], v151 offset:54272
	ds_read_b128 v[206:209], v151 offset:55296
	ds_read_b128 v[210:213], v151 offset:56320
	global_load_lds_dwordx4 v[230:231], off
	v_lshl_add_u64 v[230:231], v[236:237], 0, s[10:11]
	s_mov_b32 m0, s59
	s_nop 0
	global_load_lds_dwordx4 v[230:231], off
	s_barrier
	s_waitcnt lgkmcnt(0)
	s_setprio 1
	s_waitcnt lgkmcnt(0)
	v_mfma_f32_16x16x32_bf16 v[60:63], v[128:131], v[162:165], v[60:63]
	v_mfma_f32_16x16x32_bf16 v[56:59], v[136:139], v[162:165], v[56:59]
	v_mfma_f32_16x16x32_bf16 v[44:47], v[128:131], v[190:193], v[44:47]
	v_mfma_f32_16x16x32_bf16 v[40:43], v[136:139], v[190:193], v[40:43]
	v_mfma_f32_16x16x32_bf16 v[28:31], v[128:131], v[198:201], v[28:31]
	v_mfma_f32_16x16x32_bf16 v[24:27], v[136:139], v[198:201], v[24:27]
	v_mfma_f32_16x16x32_bf16 v[12:15], v[128:131], v[206:209], v[12:15]
	v_mfma_f32_16x16x32_bf16 v[8:11], v[136:139], v[206:209], v[8:11]
	v_mfma_f32_16x16x32_bf16 v[60:63], v[132:135], v[166:169], v[60:63]
	v_mfma_f32_16x16x32_bf16 v[56:59], v[140:143], v[166:169], v[56:59]
	v_mfma_f32_16x16x32_bf16 v[44:47], v[132:135], v[194:197], v[44:47]
	v_mfma_f32_16x16x32_bf16 v[40:43], v[140:143], v[194:197], v[40:43]
	v_mfma_f32_16x16x32_bf16 v[28:31], v[132:135], v[202:205], v[28:31]
	v_mfma_f32_16x16x32_bf16 v[24:27], v[140:143], v[202:205], v[24:27]
	v_mfma_f32_16x16x32_bf16 v[12:15], v[132:135], v[210:213], v[12:15]
	v_mfma_f32_16x16x32_bf16 v[8:11], v[140:143], v[210:213], v[8:11]
	s_setprio 0
	s_barrier
	s_add_u32 s34, s34, 0x40080
	s_addc_u32 s35, s35, 0
	s_mov_b32 m0, s60
	v_lshl_add_u64 v[128:129], s[34:35], 0, v[144:145]
	global_load_lds_dwordx4 v[128:129], off
	v_lshl_add_u64 v[128:129], s[34:35], 0, v[146:147]
	s_mov_b32 m0, s61
	s_nop 0
	global_load_lds_dwordx4 v[128:129], off
	s_waitcnt vmcnt(6)
	s_barrier
	s_setprio 1
	v_mfma_f32_16x16x32_bf16 v[52:55], v[214:217], v[162:165], v[52:55]
	v_mfma_f32_16x16x32_bf16 v[48:51], v[222:225], v[162:165], v[48:51]
	v_mfma_f32_16x16x32_bf16 v[36:39], v[214:217], v[190:193], v[36:39]
	v_mfma_f32_16x16x32_bf16 v[32:35], v[222:225], v[190:193], v[32:35]
	v_mfma_f32_16x16x32_bf16 v[20:23], v[214:217], v[198:201], v[20:23]
	v_mfma_f32_16x16x32_bf16 v[16:19], v[222:225], v[198:201], v[16:19]
	v_mfma_f32_16x16x32_bf16 v[4:7], v[214:217], v[206:209], v[4:7]
	v_mfma_f32_16x16x32_bf16 v[0:3], v[222:225], v[206:209], v[0:3]
	v_mfma_f32_16x16x32_bf16 v[52:55], v[218:221], v[166:169], v[52:55]
	v_mfma_f32_16x16x32_bf16 v[48:51], v[226:229], v[166:169], v[48:51]
	v_mfma_f32_16x16x32_bf16 v[36:39], v[218:221], v[194:197], v[36:39]
	v_mfma_f32_16x16x32_bf16 v[32:35], v[226:229], v[194:197], v[32:35]
	v_mfma_f32_16x16x32_bf16 v[20:23], v[218:221], v[202:205], v[20:23]
	v_mfma_f32_16x16x32_bf16 v[16:19], v[226:229], v[202:205], v[16:19]
	v_mfma_f32_16x16x32_bf16 v[4:7], v[218:221], v[210:213], v[4:7]
	v_mfma_f32_16x16x32_bf16 v[0:3], v[226:229], v[210:213], v[0:3]
	s_setprio 0
	s_add_i32 s69, s69, 2
	s_add_u32 s67, s67, 0x100
	s_addc_u32 s68, s68, 0
	s_add_u32 s30, s30, 0x100
	s_addc_u32 s31, s31, 0
	s_cmp_gt_u32 s69, 13
	s_barrier
	s_cbranch_scc0 .LBB0_1480
	s_ashr_i32 s29, s28, 31
	s_lshl_b64 s[28:29], s[28:29], 8
	s_lshl_b32 s30, s12, 8
	v_lshl_add_u64 v[164:165], s[28:29], 0, v[148:149]
	s_ashr_i32 s31, s30, 31
	v_lshl_add_u64 v[166:167], s[30:31], 2, v[152:153]
	v_lshlrev_b64 v[128:129], 12, v[164:165]
	v_lshl_add_u64 v[128:129], v[166:167], 0, v[128:129]
	global_load_dwordx4 v[190:193], v[128:129], off
	global_load_dwordx4 v[194:197], v[128:129], off offset:64
	global_load_dwordx4 v[198:201], v[128:129], off offset:512
	global_load_dwordx4 v[202:205], v[128:129], off offset:576
	v_or_b32_e32 v168, 16, v164
	v_mov_b32_e32 v169, v165
	v_lshlrev_b64 v[128:129], 12, v[168:169]
	v_lshl_add_u64 v[128:129], v[166:167], 0, v[128:129]
	global_load_dwordx4 v[140:143], v[128:129], off
	global_load_dwordx4 v[136:139], v[128:129], off offset:64
	global_load_dwordx4 v[132:135], v[128:129], off offset:512
	s_nop 0
	global_load_dwordx4 v[128:131], v[128:129], off offset:576
	v_and_b32_e32 v163, 64, v188
	v_xor_b32_e32 v189, 16, v188
	v_add_u32_e32 v207, 64, v163
	v_xor_b32_e32 v206, 32, v188
	v_cmp_lt_i32_e32 vcc, v189, v207
	v_or_b32_e32 v162, s30, v150
	v_mov_b32_e32 v163, s31
	v_cndmask_b32_e32 v189, v188, v189, vcc
	v_cmp_lt_i32_e32 vcc, v206, v207
	s_waitcnt vmcnt(0)
	v_lshlrev_b32_e32 v189, 2, v189
	s_lshl_b32 s28, s12, 2
	v_cndmask_b32_e32 v216, v188, v206, vcc
	v_lshlrev_b64 v[206:207], 10, v[164:165]
	v_lshl_add_u64 v[206:207], v[206:207], 0, v[162:163]
	v_lshl_add_u64 v[208:209], v[206:207], 2, s[78:79]
	v_lshlrev_b64 v[206:207], 1, v[206:207]
	v_lshl_add_u64 v[210:211], s[2:3], 0, v[206:207]
	v_or_b32_e32 v212, 32, v206
	v_mov_b32_e32 v213, v207
	v_or_b32_e32 v214, 0x100, v206
	v_mov_b32_e32 v215, v207
	v_lshl_add_u64 v[212:213], s[2:3], 0, v[212:213]
	v_lshl_add_u64 v[214:215], s[2:3], 0, v[214:215]
	v_or_b32_e32 v206, 0x120, v206
	s_ashr_i32 s29, s28, 31
	s_waitcnt vmcnt(0)
	v_pk_add_f32 v[126:127], v[126:127], v[192:193]
	v_pk_add_f32 v[124:125], v[124:125], v[190:191]
	v_pk_add_f32 v[120:121], v[120:121], v[194:195]
	v_pk_add_f32 v[122:123], v[122:123], v[196:197]
	v_pk_add_f32 v[116:117], v[116:117], v[198:199]
	v_pk_add_f32 v[190:191], v[112:113], v[202:203]
	global_store_dwordx4 v[208:209], v[124:127], off
	v_cvt_pk_bf16_f32 v112, v124, v125
	v_mul_f32_e32 v196, v120, v120
	v_mul_f32_e32 v197, v116, v116
	v_mul_f32_e32 v124, v124, v124
	v_fmac_f32_e32 v124, v125, v125
	v_fmac_f32_e32 v196, v121, v121
	v_pk_add_f32 v[118:119], v[118:119], v[200:201]
	v_mul_f32_e32 v198, v190, v190
	v_fmac_f32_e32 v197, v117, v117
	v_fmac_f32_e32 v124, v126, v126
	v_fmac_f32_e32 v196, v122, v122
	v_pk_add_f32 v[192:193], v[114:115], v[204:205]
	v_fmac_f32_e32 v198, v191, v191
	v_fmac_f32_e32 v197, v118, v118
	v_fmac_f32_e32 v124, v127, v127
	v_fmac_f32_e32 v196, v123, v123
	v_cvt_pk_bf16_f32 v113, v126, v127
	v_bfe_u32 v246, v176, 4, 1
	v_mul_u32_u24_e32 v246, 24, v246
	v_mov_b32_e32 v247, 0
	s_nop 1
	v_mov_b32_e32 v240, v112
	v_mov_b32_e32 v241, v113
	v_lshl_add_u64 v[244:245], v[210:211], 0, v[246:247]
	v_fmac_f32_e32 v198, v192, v192
	v_fmac_f32_e32 v197, v119, v119
	v_add_f32_e32 v112, v124, v196
	v_fmac_f32_e32 v198, v193, v193
	v_add_f32_e32 v112, v112, v197
	v_add_f32_e32 v112, v112, v198
	ds_bpermute_b32 v113, v189, v112
	v_cvt_pk_bf16_f32 v114, v120, v121
	v_cvt_pk_bf16_f32 v115, v122, v123
	v_cvt_pk_bf16_f32 v194, v116, v117
	v_cvt_pk_bf16_f32 v195, v118, v119
	global_store_dwordx4 v[208:209], v[120:123], off offset:64
	v_mov_b32_e32 v242, v114
	v_mov_b32_e32 v243, v115
	s_nop 1
	v_permlane16_swap_b32 v240, v242
	v_permlane16_swap_b32 v241, v243
	global_store_dwordx4 v[244:245], v[240:243], off
	global_store_dwordx4 v[208:209], v[116:119], off offset:512
	s_nop 1
	v_mov_b32_e32 v240, v194
	v_mov_b32_e32 v241, v195
	v_lshl_add_u64 v[244:245], v[214:215], 0, v[246:247]
	global_store_dwordx4 v[208:209], v[190:193], off offset:576
	s_waitcnt lgkmcnt(0)
	v_add_f32_e32 v112, v112, v113
	v_lshlrev_b32_e32 v116, 2, v216
	ds_bpermute_b32 v113, v116, v112
	v_lshl_add_u64 v[114:115], s[2:3], 0, v[206:207]
	v_cvt_pk_bf16_f32 v118, v190, v191
	v_cvt_pk_bf16_f32 v119, v192, v193
	v_mov_b32_e32 v242, v118
	v_mov_b32_e32 v243, v119
	s_nop 1
	v_permlane16_swap_b32 v240, v242
	v_permlane16_swap_b32 v241, v243
	global_store_dwordx4 v[244:245], v[240:243], off
	s_and_saveexec_b64 s[30:31], s[6:7]
	s_cbranch_execz .LBB0_1483
	v_lshlrev_b64 v[114:115], 6, v[164:165]
	v_lshl_add_u64 v[114:115], s[4:5], 0, v[114:115]
	v_lshl_add_u64 v[114:115], s[28:29], 2, v[114:115]
	s_lshl_b32 s12, s55, 2
	v_lshl_add_u64 v[114:115], v[114:115], 0, s[12:13]
	s_waitcnt lgkmcnt(0)
	v_add_f32_e32 v112, v112, v113
	v_mov_b32_e32 v232, v114
	v_mov_b32_e32 v233, v115
	v_mov_b32_e32 v234, v112
.LBB0_1483:
	s_or_b64 exec, exec, s[30:31]
	s_waitcnt lgkmcnt(0)
	v_lshlrev_b64 v[112:113], 10, v[168:169]
	v_lshl_add_u64 v[112:113], v[112:113], 0, v[162:163]
	v_pk_add_f32 v[108:109], v[108:109], v[140:141]
	v_lshl_add_u64 v[114:115], v[112:113], 2, s[78:79]
	v_lshlrev_b64 v[112:113], 1, v[112:113]
	v_mul_f32_e32 v117, v108, v108
	v_pk_add_f32 v[110:111], v[110:111], v[142:143]
	v_lshl_add_u64 v[118:119], s[2:3], 0, v[112:113]
	v_fmac_f32_e32 v117, v109, v109
	v_pk_add_f32 v[106:107], v[106:107], v[138:139]
	v_pk_add_f32 v[104:105], v[104:105], v[136:137]
	global_store_dwordx4 v[114:115], v[108:111], off
	v_cvt_pk_bf16_f32 v120, v108, v109
	v_cvt_pk_bf16_f32 v121, v110, v111
	s_nop 1
	v_mov_b32_e32 v240, v120
	v_mov_b32_e32 v241, v121
	v_lshl_add_u64 v[244:245], v[118:119], 0, v[246:247]
	v_fmac_f32_e32 v117, v110, v110
	global_store_dwordx4 v[114:115], v[104:107], off offset:64
	v_or_b32_e32 v108, 32, v112
	v_mov_b32_e32 v109, v113
	v_cvt_pk_bf16_f32 v110, v104, v105
	v_mul_f32_e32 v104, v104, v104
	v_lshl_add_u64 v[108:109], s[2:3], 0, v[108:109]
	v_fmac_f32_e32 v104, v105, v105
	v_pk_add_f32 v[102:103], v[102:103], v[134:135]
	v_pk_add_f32 v[100:101], v[100:101], v[132:133]
	v_fmac_f32_e32 v117, v111, v111
	v_cvt_pk_bf16_f32 v111, v106, v107
	v_mov_b32_e32 v242, v110
	v_mov_b32_e32 v243, v111
	s_nop 1
	v_permlane16_swap_b32 v240, v242
	v_permlane16_swap_b32 v241, v243
	global_store_dwordx4 v[244:245], v[240:243], off
	v_fmac_f32_e32 v104, v106, v106
	global_store_dwordx4 v[114:115], v[100:103], off offset:512
	v_cvt_pk_bf16_f32 v106, v100, v101
	v_fmac_f32_e32 v104, v107, v107
	v_add_f32_e32 v107, v117, v104
	v_mul_f32_e32 v100, v100, v100
	v_fmac_f32_e32 v100, v101, v101
	v_fmac_f32_e32 v100, v102, v102
	v_fmac_f32_e32 v100, v103, v103
	v_add_f32_e32 v107, v107, v100
	v_pk_add_f32 v[100:101], v[98:99], v[130:131]
	v_pk_add_f32 v[98:99], v[96:97], v[128:129]
	v_or_b32_e32 v104, 0x100, v112
	v_mul_f32_e32 v96, v98, v98
	v_fmac_f32_e32 v96, v99, v99
	v_fmac_f32_e32 v96, v100, v100
	v_fmac_f32_e32 v96, v101, v101
	v_add_f32_e32 v96, v107, v96
	ds_bpermute_b32 v97, v189, v96
	v_mov_b32_e32 v105, v113
	v_or_b32_e32 v112, 0x120, v112
	v_lshl_add_u64 v[104:105], s[2:3], 0, v[104:105]
	v_cvt_pk_bf16_f32 v107, v102, v103
	s_waitcnt lgkmcnt(0)
	v_add_f32_e32 v96, v96, v97
	ds_bpermute_b32 v97, v116, v96
	v_lshl_add_u64 v[102:103], s[2:3], 0, v[112:113]
	s_nop 1
	v_mov_b32_e32 v240, v106
	v_mov_b32_e32 v241, v107
	v_lshl_add_u64 v[244:245], v[104:105], 0, v[246:247]
	global_store_dwordx4 v[114:115], v[98:101], off offset:576
	s_nop 1
	v_cvt_pk_bf16_f32 v98, v98, v99
	v_cvt_pk_bf16_f32 v99, v100, v101
	v_mov_b32_e32 v242, v98
	v_mov_b32_e32 v243, v99
	s_nop 1
	v_permlane16_swap_b32 v240, v242
	v_permlane16_swap_b32 v241, v243
	global_store_dwordx4 v[244:245], v[240:243], off
	s_and_saveexec_b64 s[30:31], s[6:7]
	s_cbranch_execz .LBB0_1485
	v_lshlrev_b64 v[98:99], 6, v[168:169]
	v_lshl_add_u64 v[98:99], s[4:5], 0, v[98:99]
	v_lshl_add_u64 v[98:99], s[28:29], 2, v[98:99]
	s_lshl_b32 s12, s55, 2
	v_lshl_add_u64 v[98:99], v[98:99], 0, s[12:13]
	s_waitcnt lgkmcnt(0)
	v_add_f32_e32 v96, v96, v97
	v_mov_b32_e32 v236, v98
	v_mov_b32_e32 v237, v99
	v_mov_b32_e32 v238, v96
.LBB0_1485:
	s_or_b64 exec, exec, s[30:31]
	s_nop 4
	v_permlane16_swap_b32 v236, v232
	v_permlane16_swap_b32 v237, v233
	v_permlane16_swap_b32 v238, v234
	s_mov_b64 s[30:31], exec
	s_mov_b64 exec, 0xffffffff
	global_store_dword v[236:237], v238, off
	s_mov_b64 exec, s[30:31]
	v_or_b32_e32 v114, 32, v164
	v_mov_b32_e32 v115, v165
	s_waitcnt lgkmcnt(0)
	v_lshlrev_b64 v[96:97], 12, v[114:115]
	v_lshl_add_u64 v[96:97], v[166:167], 0, v[96:97]
	global_load_dwordx4 v[118:121], v[96:97], off
	global_load_dwordx4 v[122:125], v[96:97], off offset:64
	global_load_dwordx4 v[126:129], v[96:97], off offset:512
	global_load_dwordx4 v[130:133], v[96:97], off offset:576
	v_or_b32_e32 v112, 48, v164
	v_mov_b32_e32 v113, v165
	v_lshlrev_b64 v[96:97], 12, v[112:113]
	v_lshl_add_u64 v[96:97], v[166:167], 0, v[96:97]
	global_load_dwordx4 v[108:111], v[96:97], off
	global_load_dwordx4 v[104:107], v[96:97], off offset:64
	global_load_dwordx4 v[100:103], v[96:97], off offset:512
	s_nop 0
	global_load_dwordx4 v[96:99], v[96:97], off offset:576
	v_lshlrev_b64 v[134:135], 10, v[114:115]
	v_lshl_add_u64 v[134:135], v[134:135], 0, v[162:163]
	v_lshl_add_u64 v[136:137], v[134:135], 2, s[78:79]
	v_lshlrev_b64 v[134:135], 1, v[134:135]
	v_lshl_add_u64 v[138:139], s[2:3], 0, v[134:135]
	s_waitcnt vmcnt(0)
	v_or_b32_e32 v140, 32, v134
	v_mov_b32_e32 v141, v135
	v_or_b32_e32 v142, 0x100, v134
	v_mov_b32_e32 v143, v135
	v_or_b32_e32 v134, 0x120, v134
	v_lshl_add_u64 v[140:141], s[2:3], 0, v[140:141]
	v_lshl_add_u64 v[142:143], s[2:3], 0, v[142:143]
	s_waitcnt vmcnt(0)
	v_pk_add_f32 v[92:93], v[92:93], v[118:119]
	v_pk_add_f32 v[88:89], v[88:89], v[122:123]
	v_pk_add_f32 v[84:85], v[84:85], v[126:127]
	v_mul_f32_e32 v117, v92, v92
	v_mul_f32_e32 v122, v88, v88
	v_pk_add_f32 v[94:95], v[94:95], v[120:121]
	v_pk_add_f32 v[90:91], v[90:91], v[124:125]
	v_pk_add_f32 v[118:119], v[80:81], v[130:131]
	v_mul_f32_e32 v123, v84, v84
	v_fmac_f32_e32 v117, v93, v93
	v_fmac_f32_e32 v122, v89, v89
	v_pk_add_f32 v[86:87], v[86:87], v[128:129]
	v_mul_f32_e32 v124, v118, v118
	v_fmac_f32_e32 v123, v85, v85
	v_fmac_f32_e32 v117, v94, v94
	v_fmac_f32_e32 v122, v90, v90
	v_pk_add_f32 v[120:121], v[82:83], v[132:133]
	v_cvt_pk_bf16_f32 v80, v92, v93
	v_fmac_f32_e32 v124, v119, v119
	v_fmac_f32_e32 v123, v86, v86
	v_fmac_f32_e32 v117, v95, v95
	v_fmac_f32_e32 v122, v91, v91
	global_store_dwordx4 v[136:137], v[92:95], off
	v_cvt_pk_bf16_f32 v81, v94, v95
	s_nop 1
	v_mov_b32_e32 v240, v80
	v_mov_b32_e32 v241, v81
	v_lshl_add_u64 v[244:245], v[138:139], 0, v[246:247]
	v_fmac_f32_e32 v124, v120, v120
	v_fmac_f32_e32 v123, v87, v87
	v_add_f32_e32 v80, v117, v122
	v_add_f32_e32 v80, v80, v123
	v_fmac_f32_e32 v124, v121, v121
	v_add_f32_e32 v80, v80, v124
	ds_bpermute_b32 v81, v189, v80
	v_cvt_pk_bf16_f32 v82, v88, v89
	v_cvt_pk_bf16_f32 v83, v90, v91
	v_cvt_pk_bf16_f32 v92, v84, v85
	global_store_dwordx4 v[136:137], v[88:91], off offset:64
	v_mov_b32_e32 v242, v82
	v_mov_b32_e32 v243, v83
	s_nop 1
	v_permlane16_swap_b32 v240, v242
	v_permlane16_swap_b32 v241, v243
	global_store_dwordx4 v[244:245], v[240:243], off
	s_waitcnt lgkmcnt(0)
	v_add_f32_e32 v80, v80, v81
	ds_bpermute_b32 v81, v116, v80
	v_cvt_pk_bf16_f32 v93, v86, v87
	v_lshl_add_u64 v[82:83], s[2:3], 0, v[134:135]
	global_store_dwordx4 v[136:137], v[84:87], off offset:512
	s_nop 1
	v_mov_b32_e32 v240, v92
	v_mov_b32_e32 v241, v93
	v_lshl_add_u64 v[244:245], v[142:143], 0, v[246:247]
	global_store_dwordx4 v[136:137], v[118:121], off offset:576
	v_cvt_pk_bf16_f32 v84, v118, v119
	v_cvt_pk_bf16_f32 v85, v120, v121
	v_mov_b32_e32 v242, v84
	v_mov_b32_e32 v243, v85
	s_nop 1
	v_permlane16_swap_b32 v240, v242
	v_permlane16_swap_b32 v241, v243
	global_store_dwordx4 v[244:245], v[240:243], off
	s_and_saveexec_b64 s[30:31], s[6:7]
	s_cbranch_execz .LBB0_1487
	v_lshlrev_b64 v[82:83], 6, v[114:115]
	v_lshl_add_u64 v[82:83], s[4:5], 0, v[82:83]
	v_lshl_add_u64 v[82:83], s[28:29], 2, v[82:83]
	s_lshl_b32 s12, s55, 2
	v_lshl_add_u64 v[82:83], v[82:83], 0, s[12:13]
	s_waitcnt lgkmcnt(0)
	v_add_f32_e32 v80, v80, v81
	v_mov_b32_e32 v232, v82
	v_mov_b32_e32 v233, v83
	v_mov_b32_e32 v234, v80
.LBB0_1487:
	s_or_b64 exec, exec, s[30:31]
	s_waitcnt lgkmcnt(0)
	v_lshlrev_b64 v[80:81], 10, v[112:113]
	v_lshl_add_u64 v[80:81], v[80:81], 0, v[162:163]
	v_lshl_add_u64 v[82:83], v[80:81], 2, s[78:79]
	v_lshlrev_b64 v[80:81], 1, v[80:81]
	v_pk_add_f32 v[78:79], v[78:79], v[110:111]
	v_pk_add_f32 v[76:77], v[76:77], v[108:109]
	v_lshl_add_u64 v[84:85], s[2:3], 0, v[80:81]
	global_store_dwordx4 v[82:83], v[76:79], off
	v_cvt_pk_bf16_f32 v86, v76, v77
	v_cvt_pk_bf16_f32 v87, v78, v79
	s_nop 1
	v_mov_b32_e32 v240, v86
	v_mov_b32_e32 v241, v87
	v_lshl_add_u64 v[244:245], v[84:85], 0, v[246:247]
	v_mul_f32_e32 v84, v76, v76
	v_fmac_f32_e32 v84, v77, v77
	v_pk_add_f32 v[74:75], v[74:75], v[106:107]
	v_pk_add_f32 v[72:73], v[72:73], v[104:105]
	v_fmac_f32_e32 v84, v78, v78
	global_store_dwordx4 v[82:83], v[72:75], off offset:64
	v_or_b32_e32 v76, 32, v80
	v_mov_b32_e32 v77, v81
	v_cvt_pk_bf16_f32 v78, v72, v73
	v_mul_f32_e32 v72, v72, v72
	v_lshl_add_u64 v[76:77], s[2:3], 0, v[76:77]
	v_fmac_f32_e32 v72, v73, v73
	v_pk_add_f32 v[70:71], v[70:71], v[102:103]
	v_pk_add_f32 v[68:69], v[68:69], v[100:101]
	v_fmac_f32_e32 v84, v79, v79
	v_cvt_pk_bf16_f32 v79, v74, v75
	v_mov_b32_e32 v242, v78
	v_mov_b32_e32 v243, v79
	s_nop 1
	v_permlane16_swap_b32 v240, v242
	v_permlane16_swap_b32 v241, v243
	global_store_dwordx4 v[244:245], v[240:243], off
	v_fmac_f32_e32 v72, v74, v74
	global_store_dwordx4 v[82:83], v[68:71], off offset:512
	v_cvt_pk_bf16_f32 v74, v68, v69
	v_fmac_f32_e32 v72, v75, v75
	v_add_f32_e32 v75, v84, v72
	v_mul_f32_e32 v68, v68, v68
	v_fmac_f32_e32 v68, v69, v69
	v_fmac_f32_e32 v68, v70, v70
	v_fmac_f32_e32 v68, v71, v71
	v_add_f32_e32 v75, v75, v68
	v_pk_add_f32 v[68:69], v[66:67], v[98:99]
	v_pk_add_f32 v[66:67], v[64:65], v[96:97]
	v_or_b32_e32 v72, 0x100, v80
	v_mul_f32_e32 v64, v66, v66
	v_fmac_f32_e32 v64, v67, v67
	v_fmac_f32_e32 v64, v68, v68
	v_fmac_f32_e32 v64, v69, v69
	v_add_f32_e32 v64, v75, v64
	ds_bpermute_b32 v65, v189, v64
	v_mov_b32_e32 v73, v81
	v_or_b32_e32 v80, 0x120, v80
	v_lshl_add_u64 v[72:73], s[2:3], 0, v[72:73]
	v_cvt_pk_bf16_f32 v75, v70, v71
	s_waitcnt lgkmcnt(0)
	v_add_f32_e32 v64, v64, v65
	ds_bpermute_b32 v65, v116, v64
	v_lshl_add_u64 v[70:71], s[2:3], 0, v[80:81]
	s_nop 1
	v_mov_b32_e32 v240, v74
	v_mov_b32_e32 v241, v75
	v_lshl_add_u64 v[244:245], v[72:73], 0, v[246:247]
	global_store_dwordx4 v[82:83], v[66:69], off offset:576
	s_nop 1
	v_cvt_pk_bf16_f32 v66, v66, v67
	v_cvt_pk_bf16_f32 v67, v68, v69
	v_mov_b32_e32 v242, v66
	v_mov_b32_e32 v243, v67
	s_nop 1
	v_permlane16_swap_b32 v240, v242
	v_permlane16_swap_b32 v241, v243
	global_store_dwordx4 v[244:245], v[240:243], off
	s_and_saveexec_b64 s[30:31], s[6:7]
	s_cbranch_execz .LBB0_1489
	v_lshlrev_b64 v[66:67], 6, v[112:113]
	v_lshl_add_u64 v[66:67], s[4:5], 0, v[66:67]
	v_lshl_add_u64 v[66:67], s[28:29], 2, v[66:67]
	s_lshl_b32 s12, s55, 2
	v_lshl_add_u64 v[66:67], v[66:67], 0, s[12:13]
	s_waitcnt lgkmcnt(0)
	v_add_f32_e32 v64, v64, v65
	v_mov_b32_e32 v236, v66
	v_mov_b32_e32 v237, v67
	v_mov_b32_e32 v238, v64
.LBB0_1489:
	s_or_b64 exec, exec, s[30:31]
	s_nop 4
	v_permlane16_swap_b32 v236, v232
	v_permlane16_swap_b32 v237, v233
	v_permlane16_swap_b32 v238, v234
	s_mov_b64 s[30:31], exec
	s_mov_b64 exec, 0xffffffff
	global_store_dword v[236:237], v238, off
	s_mov_b64 exec, s[30:31]
	v_lshl_add_u64 v[82:83], v[164:165], 0, s[10:11]
	s_waitcnt lgkmcnt(0)
	v_lshlrev_b64 v[64:65], 12, v[82:83]
	v_lshl_add_u64 v[64:65], v[166:167], 0, v[64:65]
	global_load_dwordx4 v[84:87], v[64:65], off
	global_load_dwordx4 v[88:91], v[64:65], off offset:64
	global_load_dwordx4 v[92:95], v[64:65], off offset:512
	global_load_dwordx4 v[96:99], v[64:65], off offset:576
	v_lshl_add_u64 v[80:81], v[164:165], 0, s[14:15]
	v_lshlrev_b64 v[64:65], 12, v[80:81]
	v_lshl_add_u64 v[64:65], v[166:167], 0, v[64:65]
	global_load_dwordx4 v[76:79], v[64:65], off
	global_load_dwordx4 v[72:75], v[64:65], off offset:64
	global_load_dwordx4 v[68:71], v[64:65], off offset:512
	s_nop 0
	global_load_dwordx4 v[64:67], v[64:65], off offset:576
	v_lshlrev_b64 v[100:101], 10, v[82:83]
	v_lshl_add_u64 v[100:101], v[100:101], 0, v[162:163]
	v_lshl_add_u64 v[102:103], v[100:101], 2, s[78:79]
	v_lshlrev_b64 v[100:101], 1, v[100:101]
	v_lshl_add_u64 v[104:105], s[2:3], 0, v[100:101]
	s_waitcnt vmcnt(0)
	v_or_b32_e32 v106, 32, v100
	v_mov_b32_e32 v107, v101
	v_or_b32_e32 v108, 0x100, v100
	v_mov_b32_e32 v109, v101
	v_or_b32_e32 v100, 0x120, v100
	v_lshl_add_u64 v[106:107], s[2:3], 0, v[106:107]
	v_lshl_add_u64 v[108:109], s[2:3], 0, v[108:109]
	s_waitcnt vmcnt(0)
	v_pk_add_f32 v[60:61], v[60:61], v[84:85]
	v_pk_add_f32 v[56:57], v[56:57], v[88:89]
	v_pk_add_f32 v[52:53], v[52:53], v[92:93]
	v_mul_f32_e32 v88, v60, v60
	v_mul_f32_e32 v89, v56, v56
	v_pk_add_f32 v[62:63], v[62:63], v[86:87]
	v_pk_add_f32 v[58:59], v[58:59], v[90:91]
	v_pk_add_f32 v[84:85], v[48:49], v[96:97]
	v_mul_f32_e32 v90, v52, v52
	v_fmac_f32_e32 v88, v61, v61
	v_fmac_f32_e32 v89, v57, v57
	v_pk_add_f32 v[54:55], v[54:55], v[94:95]
	v_mul_f32_e32 v91, v84, v84
	v_fmac_f32_e32 v90, v53, v53
	v_fmac_f32_e32 v88, v62, v62
	v_fmac_f32_e32 v89, v58, v58
	v_pk_add_f32 v[86:87], v[50:51], v[98:99]
	v_cvt_pk_bf16_f32 v48, v60, v61
	v_fmac_f32_e32 v91, v85, v85
	v_fmac_f32_e32 v90, v54, v54
	v_fmac_f32_e32 v88, v63, v63
	v_fmac_f32_e32 v89, v59, v59
	global_store_dwordx4 v[102:103], v[60:63], off
	v_cvt_pk_bf16_f32 v49, v62, v63
	s_nop 1
	v_mov_b32_e32 v240, v48
	v_mov_b32_e32 v241, v49
	v_lshl_add_u64 v[244:245], v[104:105], 0, v[246:247]
	v_fmac_f32_e32 v91, v86, v86
	v_fmac_f32_e32 v90, v55, v55
	v_add_f32_e32 v48, v88, v89
	v_add_f32_e32 v48, v48, v90
	v_fmac_f32_e32 v91, v87, v87
	v_add_f32_e32 v48, v48, v91
	ds_bpermute_b32 v49, v189, v48
	v_cvt_pk_bf16_f32 v50, v56, v57
	v_cvt_pk_bf16_f32 v51, v58, v59
	v_cvt_pk_bf16_f32 v60, v52, v53
	global_store_dwordx4 v[102:103], v[56:59], off offset:64
	v_mov_b32_e32 v242, v50
	v_mov_b32_e32 v243, v51
	s_nop 1
	v_permlane16_swap_b32 v240, v242
	v_permlane16_swap_b32 v241, v243
	global_store_dwordx4 v[244:245], v[240:243], off
	s_waitcnt lgkmcnt(0)
	v_add_f32_e32 v48, v48, v49
	ds_bpermute_b32 v49, v116, v48
	v_cvt_pk_bf16_f32 v61, v54, v55
	v_lshl_add_u64 v[50:51], s[2:3], 0, v[100:101]
	global_store_dwordx4 v[102:103], v[52:55], off offset:512
	s_nop 1
	v_mov_b32_e32 v240, v60
	v_mov_b32_e32 v241, v61
	v_lshl_add_u64 v[244:245], v[108:109], 0, v[246:247]
	global_store_dwordx4 v[102:103], v[84:87], off offset:576
	v_cvt_pk_bf16_f32 v52, v84, v85
	v_cvt_pk_bf16_f32 v53, v86, v87
	v_mov_b32_e32 v242, v52
	v_mov_b32_e32 v243, v53
	s_nop 1
	v_permlane16_swap_b32 v240, v242
	v_permlane16_swap_b32 v241, v243
	global_store_dwordx4 v[244:245], v[240:243], off
	s_and_saveexec_b64 s[30:31], s[6:7]
	s_cbranch_execz .LBB0_1491
	v_lshlrev_b64 v[50:51], 6, v[82:83]
	v_lshl_add_u64 v[50:51], s[4:5], 0, v[50:51]
	v_lshl_add_u64 v[50:51], s[28:29], 2, v[50:51]
	s_lshl_b32 s12, s55, 2
	v_lshl_add_u64 v[50:51], v[50:51], 0, s[12:13]
	s_waitcnt lgkmcnt(0)
	v_add_f32_e32 v48, v48, v49
	v_mov_b32_e32 v232, v50
	v_mov_b32_e32 v233, v51
	v_mov_b32_e32 v234, v48
.LBB0_1491:
	s_or_b64 exec, exec, s[30:31]
	s_waitcnt lgkmcnt(0)
	v_lshlrev_b64 v[48:49], 10, v[80:81]
	v_lshl_add_u64 v[48:49], v[48:49], 0, v[162:163]
	v_lshl_add_u64 v[50:51], v[48:49], 2, s[78:79]
	v_lshlrev_b64 v[48:49], 1, v[48:49]
	v_pk_add_f32 v[46:47], v[46:47], v[78:79]
	v_pk_add_f32 v[44:45], v[44:45], v[76:77]
	v_lshl_add_u64 v[52:53], s[2:3], 0, v[48:49]
	global_store_dwordx4 v[50:51], v[44:47], off
	v_cvt_pk_bf16_f32 v54, v44, v45
	v_cvt_pk_bf16_f32 v55, v46, v47
	s_nop 1
	v_mov_b32_e32 v240, v54
	v_mov_b32_e32 v241, v55
	v_lshl_add_u64 v[244:245], v[52:53], 0, v[246:247]
	v_mul_f32_e32 v52, v44, v44
	v_fmac_f32_e32 v52, v45, v45
	v_pk_add_f32 v[42:43], v[42:43], v[74:75]
	v_pk_add_f32 v[40:41], v[40:41], v[72:73]
	v_fmac_f32_e32 v52, v46, v46
	global_store_dwordx4 v[50:51], v[40:43], off offset:64
	v_or_b32_e32 v44, 32, v48
	v_mov_b32_e32 v45, v49
	v_cvt_pk_bf16_f32 v46, v40, v41
	v_mul_f32_e32 v40, v40, v40
	v_lshl_add_u64 v[44:45], s[2:3], 0, v[44:45]
	v_fmac_f32_e32 v40, v41, v41
	v_pk_add_f32 v[38:39], v[38:39], v[70:71]
	v_pk_add_f32 v[36:37], v[36:37], v[68:69]
	v_fmac_f32_e32 v52, v47, v47
	v_cvt_pk_bf16_f32 v47, v42, v43
	v_mov_b32_e32 v242, v46
	v_mov_b32_e32 v243, v47
	s_nop 1
	v_permlane16_swap_b32 v240, v242
	v_permlane16_swap_b32 v241, v243
	global_store_dwordx4 v[244:245], v[240:243], off
	v_fmac_f32_e32 v40, v42, v42
	global_store_dwordx4 v[50:51], v[36:39], off offset:512
	v_cvt_pk_bf16_f32 v42, v36, v37
	v_fmac_f32_e32 v40, v43, v43
	v_add_f32_e32 v43, v52, v40
	v_mul_f32_e32 v36, v36, v36
	v_fmac_f32_e32 v36, v37, v37
	v_fmac_f32_e32 v36, v38, v38
	v_fmac_f32_e32 v36, v39, v39
	v_add_f32_e32 v43, v43, v36
	v_pk_add_f32 v[36:37], v[34:35], v[66:67]
	v_pk_add_f32 v[34:35], v[32:33], v[64:65]
	v_or_b32_e32 v40, 0x100, v48
	v_mul_f32_e32 v32, v34, v34
	v_fmac_f32_e32 v32, v35, v35
	v_fmac_f32_e32 v32, v36, v36
	v_fmac_f32_e32 v32, v37, v37
	v_add_f32_e32 v32, v43, v32
	ds_bpermute_b32 v33, v189, v32
	v_mov_b32_e32 v41, v49
	v_or_b32_e32 v48, 0x120, v48
	v_lshl_add_u64 v[40:41], s[2:3], 0, v[40:41]
	v_cvt_pk_bf16_f32 v43, v38, v39
	s_waitcnt lgkmcnt(0)
	v_add_f32_e32 v32, v32, v33
	ds_bpermute_b32 v33, v116, v32
	v_lshl_add_u64 v[38:39], s[2:3], 0, v[48:49]
	s_nop 1
	v_mov_b32_e32 v240, v42
	v_mov_b32_e32 v241, v43
	v_lshl_add_u64 v[244:245], v[40:41], 0, v[246:247]
	global_store_dwordx4 v[50:51], v[34:37], off offset:576
	s_nop 1
	v_cvt_pk_bf16_f32 v34, v34, v35
	v_cvt_pk_bf16_f32 v35, v36, v37
	v_mov_b32_e32 v242, v34
	v_mov_b32_e32 v243, v35
	s_nop 1
	v_permlane16_swap_b32 v240, v242
	v_permlane16_swap_b32 v241, v243
	global_store_dwordx4 v[244:245], v[240:243], off
	s_and_saveexec_b64 s[30:31], s[6:7]
	s_cbranch_execz .LBB0_1493
	v_lshlrev_b64 v[34:35], 6, v[80:81]
	v_lshl_add_u64 v[34:35], s[4:5], 0, v[34:35]
	v_lshl_add_u64 v[34:35], s[28:29], 2, v[34:35]
	s_lshl_b32 s12, s55, 2
	v_lshl_add_u64 v[34:35], v[34:35], 0, s[12:13]
	s_waitcnt lgkmcnt(0)
	v_add_f32_e32 v32, v32, v33
	v_mov_b32_e32 v236, v34
	v_mov_b32_e32 v237, v35
	v_mov_b32_e32 v238, v32
.LBB0_1493:
	s_or_b64 exec, exec, s[30:31]
	s_nop 4
	v_permlane16_swap_b32 v236, v232
	v_permlane16_swap_b32 v237, v233
	v_permlane16_swap_b32 v238, v234
	s_mov_b64 s[30:31], exec
	s_mov_b64 exec, 0xffffffff
	global_store_dword v[236:237], v238, off
	s_mov_b64 exec, s[30:31]
	v_lshl_add_u64 v[50:51], v[164:165], 0, s[16:17]
	s_waitcnt lgkmcnt(0)
	v_lshlrev_b64 v[32:33], 12, v[50:51]
	v_lshl_add_u64 v[32:33], v[166:167], 0, v[32:33]
	global_load_dwordx4 v[52:55], v[32:33], off
	global_load_dwordx4 v[56:59], v[32:33], off offset:64
	global_load_dwordx4 v[60:63], v[32:33], off offset:512
	global_load_dwordx4 v[64:67], v[32:33], off offset:576
	v_lshl_add_u64 v[48:49], v[164:165], 0, s[18:19]
	v_lshlrev_b64 v[32:33], 12, v[48:49]
	v_lshl_add_u64 v[32:33], v[166:167], 0, v[32:33]
	global_load_dwordx4 v[44:47], v[32:33], off
	global_load_dwordx4 v[40:43], v[32:33], off offset:64
	global_load_dwordx4 v[36:39], v[32:33], off offset:512
	s_nop 0
	global_load_dwordx4 v[32:35], v[32:33], off offset:576
	v_lshlrev_b64 v[68:69], 10, v[50:51]
	v_lshl_add_u64 v[68:69], v[68:69], 0, v[162:163]
	v_lshl_add_u64 v[70:71], v[68:69], 2, s[78:79]
	v_lshlrev_b64 v[68:69], 1, v[68:69]
	v_lshl_add_u64 v[72:73], s[2:3], 0, v[68:69]
	s_waitcnt vmcnt(0)
	v_or_b32_e32 v74, 32, v68
	v_mov_b32_e32 v75, v69
	v_or_b32_e32 v76, 0x100, v68
	v_mov_b32_e32 v77, v69
	v_or_b32_e32 v68, 0x120, v68
	v_lshl_add_u64 v[74:75], s[2:3], 0, v[74:75]
	v_lshl_add_u64 v[76:77], s[2:3], 0, v[76:77]
	s_waitcnt vmcnt(0)
	v_pk_add_f32 v[28:29], v[28:29], v[52:53]
	v_pk_add_f32 v[24:25], v[24:25], v[56:57]
	v_pk_add_f32 v[20:21], v[20:21], v[60:61]
	v_mul_f32_e32 v56, v28, v28
	v_mul_f32_e32 v57, v24, v24
	v_pk_add_f32 v[30:31], v[30:31], v[54:55]
	v_pk_add_f32 v[26:27], v[26:27], v[58:59]
	v_pk_add_f32 v[52:53], v[16:17], v[64:65]
	v_mul_f32_e32 v58, v20, v20
	v_fmac_f32_e32 v56, v29, v29
	v_fmac_f32_e32 v57, v25, v25
	v_pk_add_f32 v[22:23], v[22:23], v[62:63]
	v_mul_f32_e32 v59, v52, v52
	v_fmac_f32_e32 v58, v21, v21
	v_fmac_f32_e32 v56, v30, v30
	v_fmac_f32_e32 v57, v26, v26
	v_pk_add_f32 v[54:55], v[18:19], v[66:67]
	v_cvt_pk_bf16_f32 v16, v28, v29
	v_fmac_f32_e32 v59, v53, v53
	v_fmac_f32_e32 v58, v22, v22
	v_fmac_f32_e32 v56, v31, v31
	v_fmac_f32_e32 v57, v27, v27
	global_store_dwordx4 v[70:71], v[28:31], off
	v_cvt_pk_bf16_f32 v17, v30, v31
	s_nop 1
	v_mov_b32_e32 v240, v16
	v_mov_b32_e32 v241, v17
	v_lshl_add_u64 v[244:245], v[72:73], 0, v[246:247]
	v_fmac_f32_e32 v59, v54, v54
	v_fmac_f32_e32 v58, v23, v23
	v_add_f32_e32 v16, v56, v57
	v_add_f32_e32 v16, v16, v58
	v_fmac_f32_e32 v59, v55, v55
	v_add_f32_e32 v16, v16, v59
	ds_bpermute_b32 v17, v189, v16
	v_cvt_pk_bf16_f32 v18, v24, v25
	v_cvt_pk_bf16_f32 v19, v26, v27
	v_cvt_pk_bf16_f32 v28, v20, v21
	global_store_dwordx4 v[70:71], v[24:27], off offset:64
	v_mov_b32_e32 v242, v18
	v_mov_b32_e32 v243, v19
	s_nop 1
	v_permlane16_swap_b32 v240, v242
	v_permlane16_swap_b32 v241, v243
	global_store_dwordx4 v[244:245], v[240:243], off
	s_waitcnt lgkmcnt(0)
	v_add_f32_e32 v16, v16, v17
	ds_bpermute_b32 v17, v116, v16
	v_cvt_pk_bf16_f32 v29, v22, v23
	v_lshl_add_u64 v[18:19], s[2:3], 0, v[68:69]
	global_store_dwordx4 v[70:71], v[20:23], off offset:512
	s_nop 1
	v_mov_b32_e32 v240, v28
	v_mov_b32_e32 v241, v29
	v_lshl_add_u64 v[244:245], v[76:77], 0, v[246:247]
	global_store_dwordx4 v[70:71], v[52:55], off offset:576
	v_cvt_pk_bf16_f32 v20, v52, v53
	v_cvt_pk_bf16_f32 v21, v54, v55
	v_mov_b32_e32 v242, v20
	v_mov_b32_e32 v243, v21
	s_nop 1
	v_permlane16_swap_b32 v240, v242
	v_permlane16_swap_b32 v241, v243
	global_store_dwordx4 v[244:245], v[240:243], off
	s_and_saveexec_b64 s[30:31], s[6:7]
	s_cbranch_execz .LBB0_1495
	v_lshlrev_b64 v[18:19], 6, v[50:51]
	v_lshl_add_u64 v[18:19], s[4:5], 0, v[18:19]
	v_lshl_add_u64 v[18:19], s[28:29], 2, v[18:19]
	s_lshl_b32 s12, s55, 2
	v_lshl_add_u64 v[18:19], v[18:19], 0, s[12:13]
	s_waitcnt lgkmcnt(0)
	v_add_f32_e32 v16, v16, v17
	flat_store_dword v[18:19], v16

.LBB0_1642:
	ds_read_b128 v[128:131], v170
	ds_read_b128 v[132:135], v171
	ds_read_b128 v[136:139], v172
	ds_read_b128 v[140:143], v173
	s_add_u32 s28, s26, 0xfff50080
	s_addc_u32 s29, s27, -1
	s_cmp_eq_u32 s65, 40
	s_cselect_b32 s31, s11, s29
	s_cselect_b32 s30, s10, s28
	s_cselect_b32 s29, s13, s64
	s_cselect_b32 s28, s12, s25
	s_mov_b32 m0, s59
	v_lshl_add_u64 v[214:215], s[26:27], 0, v[156:157]
	ds_read_b128 v[162:165], v151
	ds_read_b128 v[166:169], v151 offset:1024
	ds_read_b128 v[190:193], v151 offset:2048
	ds_read_b128 v[194:197], v151 offset:3072
	ds_read_b128 v[198:201], v151 offset:4096
	ds_read_b128 v[202:205], v151 offset:5120
	ds_read_b128 v[206:209], v151 offset:6144
	ds_read_b128 v[210:213], v151 offset:7168
	global_load_lds_dwordx4 v[214:215], off
	v_lshl_add_u64 v[214:215], s[26:27], 0, v[154:155]
	s_mov_b32 m0, s60
	s_nop 0
	global_load_lds_dwordx4 v[214:215], off
	s_waitcnt lgkmcnt(8)
	s_barrier
	s_waitcnt lgkmcnt(0)
	s_setprio 1
	s_waitcnt lgkmcnt(0)
	v_mfma_f32_16x16x32_bf16 v[124:127], v[128:131], v[162:165], v[124:127]
	v_mfma_f32_16x16x32_bf16 v[120:123], v[136:139], v[162:165], v[120:123]
	v_mfma_f32_16x16x32_bf16 v[108:111], v[128:131], v[190:193], v[108:111]
	v_mfma_f32_16x16x32_bf16 v[104:107], v[136:139], v[190:193], v[104:107]
	v_mfma_f32_16x16x32_bf16 v[92:95], v[128:131], v[198:201], v[92:95]
	v_mfma_f32_16x16x32_bf16 v[88:91], v[136:139], v[198:201], v[88:91]
	v_mfma_f32_16x16x32_bf16 v[76:79], v[128:131], v[206:209], v[76:79]
	v_mfma_f32_16x16x32_bf16 v[72:75], v[136:139], v[206:209], v[72:75]
	v_mfma_f32_16x16x32_bf16 v[124:127], v[132:135], v[166:169], v[124:127]
	v_mfma_f32_16x16x32_bf16 v[120:123], v[140:143], v[166:169], v[120:123]
	v_mfma_f32_16x16x32_bf16 v[108:111], v[132:135], v[194:197], v[108:111]
	v_mfma_f32_16x16x32_bf16 v[104:107], v[140:143], v[194:197], v[104:107]
	v_mfma_f32_16x16x32_bf16 v[92:95], v[132:135], v[202:205], v[92:95]
	v_mfma_f32_16x16x32_bf16 v[88:91], v[140:143], v[202:205], v[88:91]
	v_mfma_f32_16x16x32_bf16 v[76:79], v[132:135], v[210:213], v[76:79]
	v_mfma_f32_16x16x32_bf16 v[72:75], v[140:143], v[210:213], v[72:75]
	s_setprio 0
	s_barrier
	s_mov_b32 m0, s42
	v_lshl_add_u64 v[230:231], s[28:29], 0, v[144:145]
	ds_read_b128 v[214:217], v174
	ds_read_b128 v[218:221], v175
	ds_read_b128 v[222:225], v177
	ds_read_b128 v[226:229], v178
	global_load_lds_dwordx4 v[230:231], off
	v_lshl_add_u64 v[232:233], s[28:29], 0, v[146:147]
	s_mov_b32 m0, s43
	s_nop 0
	global_load_lds_dwordx4 v[232:233], off
	s_barrier
	s_waitcnt lgkmcnt(0)
	s_setprio 1
	s_waitcnt lgkmcnt(0)
	v_mfma_f32_16x16x32_bf16 v[116:119], v[214:217], v[162:165], v[116:119]
	v_mfma_f32_16x16x32_bf16 v[112:115], v[222:225], v[162:165], v[112:115]
	v_mfma_f32_16x16x32_bf16 v[100:103], v[214:217], v[190:193], v[100:103]
	v_mfma_f32_16x16x32_bf16 v[96:99], v[222:225], v[190:193], v[96:99]
	v_mfma_f32_16x16x32_bf16 v[84:87], v[214:217], v[198:201], v[84:87]
	v_mfma_f32_16x16x32_bf16 v[80:83], v[222:225], v[198:201], v[80:83]
	v_mfma_f32_16x16x32_bf16 v[68:71], v[214:217], v[206:209], v[68:71]
	v_mfma_f32_16x16x32_bf16 v[64:67], v[222:225], v[206:209], v[64:67]
	v_mfma_f32_16x16x32_bf16 v[116:119], v[218:221], v[166:169], v[116:119]
	v_mfma_f32_16x16x32_bf16 v[112:115], v[226:229], v[166:169], v[112:115]
	v_mfma_f32_16x16x32_bf16 v[100:103], v[218:221], v[194:197], v[100:103]
	v_mfma_f32_16x16x32_bf16 v[96:99], v[226:229], v[194:197], v[96:99]
	v_mfma_f32_16x16x32_bf16 v[84:87], v[218:221], v[202:205], v[84:87]
	v_mfma_f32_16x16x32_bf16 v[80:83], v[226:229], v[202:205], v[80:83]
	v_mfma_f32_16x16x32_bf16 v[68:71], v[218:221], v[210:213], v[68:71]
	v_mfma_f32_16x16x32_bf16 v[64:67], v[226:229], v[210:213], v[64:67]
	s_setprio 0
	s_mov_b32 m0, s41
	v_lshl_add_u64 v[234:235], s[30:31], 0, v[144:145]
	s_barrier
	ds_read_b128 v[162:165], v151 offset:16384
	ds_read_b128 v[166:169], v151 offset:17408
	ds_read_b128 v[190:193], v151 offset:18432
	ds_read_b128 v[194:197], v151 offset:19456
	ds_read_b128 v[198:201], v151 offset:20480
	ds_read_b128 v[202:205], v151 offset:21504
	ds_read_b128 v[206:209], v151 offset:22528
	ds_read_b128 v[210:213], v151 offset:23552
	global_load_lds_dwordx4 v[234:235], off
	v_lshl_add_u64 v[236:237], s[30:31], 0, v[146:147]
	s_mov_b32 m0, s44
	s_nop 0
	global_load_lds_dwordx4 v[236:237], off
	s_barrier
	s_waitcnt lgkmcnt(0)
	s_setprio 1
	s_waitcnt lgkmcnt(0)
	v_mfma_f32_16x16x32_bf16 v[60:63], v[128:131], v[162:165], v[60:63]
	v_mfma_f32_16x16x32_bf16 v[56:59], v[136:139], v[162:165], v[56:59]
	v_mfma_f32_16x16x32_bf16 v[44:47], v[128:131], v[190:193], v[44:47]
	v_mfma_f32_16x16x32_bf16 v[40:43], v[136:139], v[190:193], v[40:43]
	v_mfma_f32_16x16x32_bf16 v[28:31], v[128:131], v[198:201], v[28:31]
	v_mfma_f32_16x16x32_bf16 v[24:27], v[136:139], v[198:201], v[24:27]
	v_mfma_f32_16x16x32_bf16 v[12:15], v[128:131], v[206:209], v[12:15]
	v_mfma_f32_16x16x32_bf16 v[8:11], v[136:139], v[206:209], v[8:11]
	v_mfma_f32_16x16x32_bf16 v[60:63], v[132:135], v[166:169], v[60:63]
	v_mfma_f32_16x16x32_bf16 v[56:59], v[140:143], v[166:169], v[56:59]
	v_mfma_f32_16x16x32_bf16 v[44:47], v[132:135], v[194:197], v[44:47]
	v_mfma_f32_16x16x32_bf16 v[40:43], v[140:143], v[194:197], v[40:43]
	v_mfma_f32_16x16x32_bf16 v[28:31], v[132:135], v[202:205], v[28:31]
	v_mfma_f32_16x16x32_bf16 v[24:27], v[140:143], v[202:205], v[24:27]
	v_mfma_f32_16x16x32_bf16 v[12:15], v[132:135], v[210:213], v[12:15]
	v_mfma_f32_16x16x32_bf16 v[8:11], v[140:143], v[210:213], v[8:11]
	s_setprio 0
	s_barrier
	s_add_u32 s66, s28, 0xb0000
	s_addc_u32 s67, s29, 0
	s_mov_b32 m0, s45
	v_lshl_add_u64 v[128:129], s[66:67], 0, v[144:145]
	global_load_lds_dwordx4 v[128:129], off
	v_lshl_add_u64 v[128:129], s[66:67], 0, v[146:147]
	s_mov_b32 m0, s46
	s_nop 0
	global_load_lds_dwordx4 v[128:129], off
	s_waitcnt vmcnt(6)
	s_barrier
	s_setprio 1
	v_mfma_f32_16x16x32_bf16 v[52:55], v[214:217], v[162:165], v[52:55]
	v_mfma_f32_16x16x32_bf16 v[48:51], v[222:225], v[162:165], v[48:51]
	v_mfma_f32_16x16x32_bf16 v[36:39], v[214:217], v[190:193], v[36:39]
	v_mfma_f32_16x16x32_bf16 v[32:35], v[222:225], v[190:193], v[32:35]
	v_mfma_f32_16x16x32_bf16 v[20:23], v[214:217], v[198:201], v[20:23]
	v_mfma_f32_16x16x32_bf16 v[16:19], v[222:225], v[198:201], v[16:19]
	v_mfma_f32_16x16x32_bf16 v[4:7], v[214:217], v[206:209], v[4:7]
	v_mfma_f32_16x16x32_bf16 v[0:3], v[222:225], v[206:209], v[0:3]
	v_mfma_f32_16x16x32_bf16 v[52:55], v[218:221], v[166:169], v[52:55]
	v_mfma_f32_16x16x32_bf16 v[48:51], v[226:229], v[166:169], v[48:51]
	v_mfma_f32_16x16x32_bf16 v[36:39], v[218:221], v[194:197], v[36:39]
	v_mfma_f32_16x16x32_bf16 v[32:35], v[226:229], v[194:197], v[32:35]
	v_mfma_f32_16x16x32_bf16 v[20:23], v[218:221], v[202:205], v[20:23]
	v_mfma_f32_16x16x32_bf16 v[16:19], v[226:229], v[202:205], v[16:19]
	v_mfma_f32_16x16x32_bf16 v[4:7], v[218:221], v[210:213], v[4:7]
	v_mfma_f32_16x16x32_bf16 v[0:3], v[226:229], v[210:213], v[0:3]
	s_setprio 0
	s_barrier
	ds_read_b128 v[128:131], v180
	ds_read_b128 v[132:135], v181
	ds_read_b128 v[136:139], v182
	ds_read_b128 v[140:143], v183
	s_add_u32 s30, s30, 0xb0000
	s_addc_u32 s31, s31, 0
	s_mov_b32 m0, s47
	v_lshl_add_u64 v[214:215], s[30:31], 0, v[144:145]
	ds_read_b128 v[162:165], v151 offset:32768
	ds_read_b128 v[166:169], v151 offset:33792
	ds_read_b128 v[190:193], v151 offset:34816
	ds_read_b128 v[194:197], v151 offset:35840
	ds_read_b128 v[198:201], v151 offset:36864
	ds_read_b128 v[202:205], v151 offset:37888
	ds_read_b128 v[206:209], v151 offset:38912
	ds_read_b128 v[210:213], v151 offset:39936
	global_load_lds_dwordx4 v[214:215], off
	v_lshl_add_u64 v[214:215], s[30:31], 0, v[146:147]
	s_mov_b32 m0, s48
	s_nop 0
	global_load_lds_dwordx4 v[214:215], off
	s_waitcnt lgkmcnt(8)
	s_barrier
	s_waitcnt lgkmcnt(0)
	s_setprio 1
	s_waitcnt lgkmcnt(0)
	v_mfma_f32_16x16x32_bf16 v[124:127], v[128:131], v[162:165], v[124:127]
	v_mfma_f32_16x16x32_bf16 v[120:123], v[136:139], v[162:165], v[120:123]
	v_mfma_f32_16x16x32_bf16 v[108:111], v[128:131], v[190:193], v[108:111]
	v_mfma_f32_16x16x32_bf16 v[104:107], v[136:139], v[190:193], v[104:107]
	v_mfma_f32_16x16x32_bf16 v[92:95], v[128:131], v[198:201], v[92:95]
	v_mfma_f32_16x16x32_bf16 v[88:91], v[136:139], v[198:201], v[88:91]
	v_mfma_f32_16x16x32_bf16 v[76:79], v[128:131], v[206:209], v[76:79]
	v_mfma_f32_16x16x32_bf16 v[72:75], v[136:139], v[206:209], v[72:75]
	v_mfma_f32_16x16x32_bf16 v[124:127], v[132:135], v[166:169], v[124:127]
	v_mfma_f32_16x16x32_bf16 v[120:123], v[140:143], v[166:169], v[120:123]
	v_mfma_f32_16x16x32_bf16 v[108:111], v[132:135], v[194:197], v[108:111]
	v_mfma_f32_16x16x32_bf16 v[104:107], v[140:143], v[194:197], v[104:107]
	v_mfma_f32_16x16x32_bf16 v[92:95], v[132:135], v[202:205], v[92:95]
	v_mfma_f32_16x16x32_bf16 v[88:91], v[140:143], v[202:205], v[88:91]
	v_mfma_f32_16x16x32_bf16 v[76:79], v[132:135], v[210:213], v[76:79]
	v_mfma_f32_16x16x32_bf16 v[72:75], v[140:143], v[210:213], v[72:75]
	s_setprio 0
	s_barrier
	s_mov_b32 m0, s52
	v_lshl_add_u64 v[230:231], v[230:231], 0, s[14:15]
	ds_read_b128 v[214:217], v184
	ds_read_b128 v[218:221], v185
	ds_read_b128 v[222:225], v186
	ds_read_b128 v[226:229], v187
	global_load_lds_dwordx4 v[230:231], off
	v_lshl_add_u64 v[230:231], v[232:233], 0, s[14:15]
	s_mov_b32 m0, s53
	s_nop 0
	global_load_lds_dwordx4 v[230:231], off
	s_barrier
	s_waitcnt lgkmcnt(0)
	s_setprio 1
	s_waitcnt lgkmcnt(0)
	v_mfma_f32_16x16x32_bf16 v[116:119], v[214:217], v[162:165], v[116:119]
	v_mfma_f32_16x16x32_bf16 v[112:115], v[222:225], v[162:165], v[112:115]
	v_mfma_f32_16x16x32_bf16 v[100:103], v[214:217], v[190:193], v[100:103]
	v_mfma_f32_16x16x32_bf16 v[96:99], v[222:225], v[190:193], v[96:99]
	v_mfma_f32_16x16x32_bf16 v[84:87], v[214:217], v[198:201], v[84:87]
	v_mfma_f32_16x16x32_bf16 v[80:83], v[222:225], v[198:201], v[80:83]
	v_mfma_f32_16x16x32_bf16 v[68:71], v[214:217], v[206:209], v[68:71]
	v_mfma_f32_16x16x32_bf16 v[64:67], v[222:225], v[206:209], v[64:67]
	v_mfma_f32_16x16x32_bf16 v[116:119], v[218:221], v[166:169], v[116:119]
	v_mfma_f32_16x16x32_bf16 v[112:115], v[226:229], v[166:169], v[112:115]
	v_mfma_f32_16x16x32_bf16 v[100:103], v[218:221], v[194:197], v[100:103]
	v_mfma_f32_16x16x32_bf16 v[96:99], v[226:229], v[194:197], v[96:99]
	v_mfma_f32_16x16x32_bf16 v[84:87], v[218:221], v[202:205], v[84:87]
	v_mfma_f32_16x16x32_bf16 v[80:83], v[226:229], v[202:205], v[80:83]
	v_mfma_f32_16x16x32_bf16 v[68:71], v[218:221], v[210:213], v[68:71]
	v_mfma_f32_16x16x32_bf16 v[64:67], v[226:229], v[210:213], v[64:67]
	s_setprio 0
	s_mov_b32 m0, s54
	v_lshl_add_u64 v[230:231], v[234:235], 0, s[14:15]
	s_barrier
	ds_read_b128 v[162:165], v151 offset:49152
	ds_read_b128 v[166:169], v151 offset:50176
	ds_read_b128 v[190:193], v151 offset:51200
	ds_read_b128 v[194:197], v151 offset:52224
	ds_read_b128 v[198:201], v151 offset:53248
	ds_read_b128 v[202:205], v151 offset:54272
	ds_read_b128 v[206:209], v151 offset:55296
	ds_read_b128 v[210:213], v151 offset:56320
	global_load_lds_dwordx4 v[230:231], off
	v_lshl_add_u64 v[230:231], v[236:237], 0, s[14:15]
	s_mov_b32 m0, s55
	s_nop 0
	global_load_lds_dwordx4 v[230:231], off
	s_barrier
	s_waitcnt lgkmcnt(0)
	s_setprio 1
	s_waitcnt lgkmcnt(0)
	v_mfma_f32_16x16x32_bf16 v[60:63], v[128:131], v[162:165], v[60:63]
	v_mfma_f32_16x16x32_bf16 v[56:59], v[136:139], v[162:165], v[56:59]
	v_mfma_f32_16x16x32_bf16 v[44:47], v[128:131], v[190:193], v[44:47]
	v_mfma_f32_16x16x32_bf16 v[40:43], v[136:139], v[190:193], v[40:43]
	v_mfma_f32_16x16x32_bf16 v[28:31], v[128:131], v[198:201], v[28:31]
	v_mfma_f32_16x16x32_bf16 v[24:27], v[136:139], v[198:201], v[24:27]
	v_mfma_f32_16x16x32_bf16 v[12:15], v[128:131], v[206:209], v[12:15]
	v_mfma_f32_16x16x32_bf16 v[8:11], v[136:139], v[206:209], v[8:11]
	v_mfma_f32_16x16x32_bf16 v[60:63], v[132:135], v[166:169], v[60:63]
	v_mfma_f32_16x16x32_bf16 v[56:59], v[140:143], v[166:169], v[56:59]
	v_mfma_f32_16x16x32_bf16 v[44:47], v[132:135], v[194:197], v[44:47]
	v_mfma_f32_16x16x32_bf16 v[40:43], v[140:143], v[194:197], v[40:43]
	v_mfma_f32_16x16x32_bf16 v[28:31], v[132:135], v[202:205], v[28:31]
	v_mfma_f32_16x16x32_bf16 v[24:27], v[140:143], v[202:205], v[24:27]
	v_mfma_f32_16x16x32_bf16 v[12:15], v[132:135], v[210:213], v[12:15]
	v_mfma_f32_16x16x32_bf16 v[8:11], v[140:143], v[210:213], v[8:11]
	s_setprio 0
	s_barrier
	s_add_u32 s28, s28, 0xb0080
	s_addc_u32 s29, s29, 0
	s_mov_b32 m0, s56
	v_lshl_add_u64 v[128:129], s[28:29], 0, v[144:145]
	global_load_lds_dwordx4 v[128:129], off
	v_lshl_add_u64 v[128:129], s[28:29], 0, v[146:147]
	s_mov_b32 m0, s57
	s_nop 0
	global_load_lds_dwordx4 v[128:129], off
	s_waitcnt vmcnt(6)
	s_barrier
	s_setprio 1
	v_mfma_f32_16x16x32_bf16 v[52:55], v[214:217], v[162:165], v[52:55]
	v_mfma_f32_16x16x32_bf16 v[48:51], v[222:225], v[162:165], v[48:51]
	v_mfma_f32_16x16x32_bf16 v[36:39], v[214:217], v[190:193], v[36:39]
	v_mfma_f32_16x16x32_bf16 v[32:35], v[222:225], v[190:193], v[32:35]
	v_mfma_f32_16x16x32_bf16 v[20:23], v[214:217], v[198:201], v[20:23]
	v_mfma_f32_16x16x32_bf16 v[16:19], v[222:225], v[198:201], v[16:19]
	v_mfma_f32_16x16x32_bf16 v[4:7], v[214:217], v[206:209], v[4:7]
	v_mfma_f32_16x16x32_bf16 v[0:3], v[222:225], v[206:209], v[0:3]
	v_mfma_f32_16x16x32_bf16 v[52:55], v[218:221], v[166:169], v[52:55]
	v_mfma_f32_16x16x32_bf16 v[48:51], v[226:229], v[166:169], v[48:51]
	v_mfma_f32_16x16x32_bf16 v[36:39], v[218:221], v[194:197], v[36:39]
	v_mfma_f32_16x16x32_bf16 v[32:35], v[226:229], v[194:197], v[32:35]
	v_mfma_f32_16x16x32_bf16 v[20:23], v[218:221], v[202:205], v[20:23]
	v_mfma_f32_16x16x32_bf16 v[16:19], v[226:229], v[202:205], v[16:19]
	v_mfma_f32_16x16x32_bf16 v[4:7], v[218:221], v[210:213], v[4:7]
	v_mfma_f32_16x16x32_bf16 v[0:3], v[226:229], v[210:213], v[0:3]
	s_setprio 0
	s_add_i32 s65, s65, 2
	s_add_u32 s25, s25, 0x100
	s_addc_u32 s64, s64, 0
	s_add_u32 s26, s26, 0x100
	s_addc_u32 s27, s27, 0
	s_cmp_gt_u32 s65, 41
	s_barrier
	s_cbranch_scc0 .LBB0_1642
	s_ashr_i32 s25, s24, 31
	s_lshl_b64 s[24:25], s[24:25], 8
	s_lshl_b32 s26, s16, 8
	v_lshl_add_u64 v[164:165], s[24:25], 0, v[148:149]
	s_ashr_i32 s27, s26, 31
	v_lshl_add_u64 v[166:167], s[26:27], 2, v[152:153]
	v_lshlrev_b64 v[128:129], 12, v[164:165]
	v_lshl_add_u64 v[128:129], v[166:167], 0, v[128:129]
	global_load_dwordx4 v[190:193], v[128:129], off
	global_load_dwordx4 v[194:197], v[128:129], off offset:64
	global_load_dwordx4 v[198:201], v[128:129], off offset:512
	global_load_dwordx4 v[202:205], v[128:129], off offset:576
	v_or_b32_e32 v168, 16, v164
	v_mov_b32_e32 v169, v165
	v_lshlrev_b64 v[128:129], 12, v[168:169]
	v_lshl_add_u64 v[128:129], v[166:167], 0, v[128:129]
	global_load_dwordx4 v[140:143], v[128:129], off
	global_load_dwordx4 v[136:139], v[128:129], off offset:64
	global_load_dwordx4 v[132:135], v[128:129], off offset:512
	s_nop 0
	global_load_dwordx4 v[128:131], v[128:129], off offset:576
	v_and_b32_e32 v163, 64, v188
	v_xor_b32_e32 v189, 16, v188
	v_add_u32_e32 v207, 64, v163
	v_xor_b32_e32 v206, 32, v188
	v_cmp_lt_i32_e32 vcc, v189, v207
	v_or_b32_e32 v162, s26, v150
	v_mov_b32_e32 v163, s27
	v_cndmask_b32_e32 v189, v188, v189, vcc
	v_cmp_lt_i32_e32 vcc, v206, v207
	s_waitcnt vmcnt(0)
	v_lshlrev_b32_e32 v189, 2, v189
	s_lshl_b32 s24, s16, 2
	v_cndmask_b32_e32 v216, v188, v206, vcc
	v_lshlrev_b64 v[206:207], 10, v[164:165]
	v_lshl_add_u64 v[206:207], v[206:207], 0, v[162:163]
	v_lshl_add_u64 v[208:209], v[206:207], 2, s[78:79]
	v_lshlrev_b64 v[206:207], 1, v[206:207]
	v_lshl_add_u64 v[210:211], s[2:3], 0, v[206:207]
	v_or_b32_e32 v212, 32, v206
	v_mov_b32_e32 v213, v207
	v_or_b32_e32 v214, 0x100, v206
	v_mov_b32_e32 v215, v207
	v_lshl_add_u64 v[212:213], s[2:3], 0, v[212:213]
	v_lshl_add_u64 v[214:215], s[2:3], 0, v[214:215]
	v_or_b32_e32 v206, 0x120, v206
	s_ashr_i32 s25, s24, 31
	s_waitcnt vmcnt(0)
	v_pk_fma_f32 v[126:127], v[126:127], 0.5, v[192:193] op_sel_hi:[1,0,1]
	v_pk_fma_f32 v[124:125], v[124:125], 0.5, v[190:191] op_sel_hi:[1,0,1]
	v_pk_fma_f32 v[120:121], v[120:121], 0.5, v[194:195] op_sel_hi:[1,0,1]
	v_pk_fma_f32 v[122:123], v[122:123], 0.5, v[196:197] op_sel_hi:[1,0,1]
	v_pk_fma_f32 v[116:117], v[116:117], 0.5, v[198:199] op_sel_hi:[1,0,1]
	v_pk_fma_f32 v[190:191], v[112:113], 0.5, v[202:203] op_sel_hi:[1,0,1]
	global_store_dwordx4 v[208:209], v[124:127], off
	v_cvt_pk_bf16_f32 v112, v124, v125
	v_mul_f32_e32 v196, v120, v120
	v_mul_f32_e32 v197, v116, v116
	v_mul_f32_e32 v124, v124, v124
	v_fmac_f32_e32 v124, v125, v125
	v_fmac_f32_e32 v196, v121, v121
	v_pk_fma_f32 v[118:119], v[118:119], 0.5, v[200:201] op_sel_hi:[1,0,1]
	v_mul_f32_e32 v198, v190, v190
	v_fmac_f32_e32 v197, v117, v117
	v_fmac_f32_e32 v124, v126, v126
	v_fmac_f32_e32 v196, v122, v122
	v_pk_fma_f32 v[192:193], v[114:115], 0.5, v[204:205] op_sel_hi:[1,0,1]
	v_fmac_f32_e32 v198, v191, v191
	v_fmac_f32_e32 v197, v118, v118
	v_fmac_f32_e32 v124, v127, v127
	v_fmac_f32_e32 v196, v123, v123
	v_cvt_pk_bf16_f32 v113, v126, v127
	v_bfe_u32 v246, v176, 4, 1
	v_mul_u32_u24_e32 v246, 24, v246
	v_mov_b32_e32 v247, 0
	s_nop 1
	v_mov_b32_e32 v240, v112
	v_mov_b32_e32 v241, v113
	v_lshl_add_u64 v[244:245], v[210:211], 0, v[246:247]
	v_fmac_f32_e32 v198, v192, v192
	v_fmac_f32_e32 v197, v119, v119
	v_add_f32_e32 v112, v124, v196
	v_fmac_f32_e32 v198, v193, v193
	v_add_f32_e32 v112, v112, v197
	v_add_f32_e32 v112, v112, v198
	ds_bpermute_b32 v113, v189, v112
	v_cvt_pk_bf16_f32 v114, v120, v121
	v_cvt_pk_bf16_f32 v115, v122, v123
	v_cvt_pk_bf16_f32 v194, v116, v117
	v_cvt_pk_bf16_f32 v195, v118, v119
	global_store_dwordx4 v[208:209], v[120:123], off offset:64
	v_mov_b32_e32 v242, v114
	v_mov_b32_e32 v243, v115
	s_nop 1
	v_permlane16_swap_b32 v240, v242
	v_permlane16_swap_b32 v241, v243
	global_store_dwordx4 v[244:245], v[240:243], off
	global_store_dwordx4 v[208:209], v[116:119], off offset:512
	s_nop 1
	v_mov_b32_e32 v240, v194
	v_mov_b32_e32 v241, v195
	v_lshl_add_u64 v[244:245], v[214:215], 0, v[246:247]
	global_store_dwordx4 v[208:209], v[190:193], off offset:576
	s_waitcnt lgkmcnt(0)
	v_add_f32_e32 v112, v112, v113
	v_lshlrev_b32_e32 v116, 2, v216
	ds_bpermute_b32 v113, v116, v112
	v_lshl_add_u64 v[114:115], s[2:3], 0, v[206:207]
	v_cvt_pk_bf16_f32 v118, v190, v191
	v_cvt_pk_bf16_f32 v119, v192, v193
	v_mov_b32_e32 v242, v118
	v_mov_b32_e32 v243, v119
	s_nop 1
	v_permlane16_swap_b32 v240, v242
	v_permlane16_swap_b32 v241, v243
	global_store_dwordx4 v[244:245], v[240:243], off
	s_and_saveexec_b64 s[26:27], s[6:7]
	s_cbranch_execz .LBB0_1645
	v_lshlrev_b64 v[114:115], 6, v[164:165]
	v_lshl_add_u64 v[114:115], s[4:5], 0, v[114:115]
	v_lshl_add_u64 v[114:115], s[24:25], 2, v[114:115]
	s_lshl_b32 s16, s49, 2
	v_lshl_add_u64 v[114:115], v[114:115], 0, s[16:17]
	s_waitcnt lgkmcnt(0)
	v_add_f32_e32 v112, v112, v113
	v_mov_b32_e32 v232, v114
	v_mov_b32_e32 v233, v115
	v_mov_b32_e32 v234, v112
.LBB0_1645:
	s_or_b64 exec, exec, s[26:27]
	s_waitcnt lgkmcnt(0)
	v_lshlrev_b64 v[112:113], 10, v[168:169]
	v_lshl_add_u64 v[112:113], v[112:113], 0, v[162:163]
	v_pk_fma_f32 v[108:109], v[108:109], 0.5, v[140:141] op_sel_hi:[1,0,1]
	v_lshl_add_u64 v[114:115], v[112:113], 2, s[78:79]
	v_lshlrev_b64 v[112:113], 1, v[112:113]
	v_mul_f32_e32 v117, v108, v108
	v_pk_fma_f32 v[110:111], v[110:111], 0.5, v[142:143] op_sel_hi:[1,0,1]
	v_lshl_add_u64 v[118:119], s[2:3], 0, v[112:113]
	v_fmac_f32_e32 v117, v109, v109
	v_pk_fma_f32 v[106:107], v[106:107], 0.5, v[138:139] op_sel_hi:[1,0,1]
	v_pk_fma_f32 v[104:105], v[104:105], 0.5, v[136:137] op_sel_hi:[1,0,1]
	global_store_dwordx4 v[114:115], v[108:111], off
	v_cvt_pk_bf16_f32 v120, v108, v109
	v_cvt_pk_bf16_f32 v121, v110, v111
	s_nop 1
	v_mov_b32_e32 v240, v120
	v_mov_b32_e32 v241, v121
	v_lshl_add_u64 v[244:245], v[118:119], 0, v[246:247]
	v_fmac_f32_e32 v117, v110, v110
	global_store_dwordx4 v[114:115], v[104:107], off offset:64
	v_or_b32_e32 v108, 32, v112
	v_mov_b32_e32 v109, v113
	v_cvt_pk_bf16_f32 v110, v104, v105
	v_mul_f32_e32 v104, v104, v104
	v_lshl_add_u64 v[108:109], s[2:3], 0, v[108:109]
	v_fmac_f32_e32 v104, v105, v105
	v_pk_fma_f32 v[102:103], v[102:103], 0.5, v[134:135] op_sel_hi:[1,0,1]
	v_pk_fma_f32 v[100:101], v[100:101], 0.5, v[132:133] op_sel_hi:[1,0,1]
	v_fmac_f32_e32 v117, v111, v111
	v_cvt_pk_bf16_f32 v111, v106, v107
	v_mov_b32_e32 v242, v110
	v_mov_b32_e32 v243, v111
	s_nop 1
	v_permlane16_swap_b32 v240, v242
	v_permlane16_swap_b32 v241, v243
	global_store_dwordx4 v[244:245], v[240:243], off
	v_fmac_f32_e32 v104, v106, v106
	global_store_dwordx4 v[114:115], v[100:103], off offset:512
	v_cvt_pk_bf16_f32 v106, v100, v101
	v_fmac_f32_e32 v104, v107, v107
	v_add_f32_e32 v107, v117, v104
	v_mul_f32_e32 v100, v100, v100
	v_fmac_f32_e32 v100, v101, v101
	v_fmac_f32_e32 v100, v102, v102
	v_fmac_f32_e32 v100, v103, v103
	v_add_f32_e32 v107, v107, v100
	v_pk_fma_f32 v[100:101], v[98:99], 0.5, v[130:131] op_sel_hi:[1,0,1]
	v_pk_fma_f32 v[98:99], v[96:97], 0.5, v[128:129] op_sel_hi:[1,0,1]
	v_or_b32_e32 v104, 0x100, v112
	v_mul_f32_e32 v96, v98, v98
	v_fmac_f32_e32 v96, v99, v99
	v_fmac_f32_e32 v96, v100, v100
	v_fmac_f32_e32 v96, v101, v101
	v_add_f32_e32 v96, v107, v96
	ds_bpermute_b32 v97, v189, v96
	v_mov_b32_e32 v105, v113
	v_or_b32_e32 v112, 0x120, v112
	v_lshl_add_u64 v[104:105], s[2:3], 0, v[104:105]
	v_cvt_pk_bf16_f32 v107, v102, v103
	s_waitcnt lgkmcnt(0)
	v_add_f32_e32 v96, v96, v97
	ds_bpermute_b32 v97, v116, v96
	v_lshl_add_u64 v[102:103], s[2:3], 0, v[112:113]
	s_nop 1
	v_mov_b32_e32 v240, v106
	v_mov_b32_e32 v241, v107
	v_lshl_add_u64 v[244:245], v[104:105], 0, v[246:247]
	global_store_dwordx4 v[114:115], v[98:101], off offset:576
	s_nop 1
	v_cvt_pk_bf16_f32 v98, v98, v99
	v_cvt_pk_bf16_f32 v99, v100, v101
	v_mov_b32_e32 v242, v98
	v_mov_b32_e32 v243, v99
	s_nop 1
	v_permlane16_swap_b32 v240, v242
	v_permlane16_swap_b32 v241, v243
	global_store_dwordx4 v[244:245], v[240:243], off
	s_and_saveexec_b64 s[26:27], s[6:7]
	s_cbranch_execz .LBB0_1647
	v_lshlrev_b64 v[98:99], 6, v[168:169]
	v_lshl_add_u64 v[98:99], s[4:5], 0, v[98:99]
	v_lshl_add_u64 v[98:99], s[24:25], 2, v[98:99]
	s_lshl_b32 s16, s49, 2
	v_lshl_add_u64 v[98:99], v[98:99], 0, s[16:17]
	s_waitcnt lgkmcnt(0)
	v_add_f32_e32 v96, v96, v97
	v_mov_b32_e32 v236, v98
	v_mov_b32_e32 v237, v99
	v_mov_b32_e32 v238, v96
.LBB0_1647:
	s_or_b64 exec, exec, s[26:27]
	s_nop 4
	v_permlane16_swap_b32 v236, v232
	v_permlane16_swap_b32 v237, v233
	v_permlane16_swap_b32 v238, v234
	s_mov_b64 s[26:27], exec
	s_mov_b64 exec, 0xffffffff
	global_store_dword v[236:237], v238, off
	s_mov_b64 exec, s[26:27]
	v_or_b32_e32 v114, 32, v164
	v_mov_b32_e32 v115, v165
	s_waitcnt lgkmcnt(0)
	v_lshlrev_b64 v[96:97], 12, v[114:115]
	v_lshl_add_u64 v[96:97], v[166:167], 0, v[96:97]
	global_load_dwordx4 v[118:121], v[96:97], off
	global_load_dwordx4 v[122:125], v[96:97], off offset:64
	global_load_dwordx4 v[126:129], v[96:97], off offset:512
	global_load_dwordx4 v[130:133], v[96:97], off offset:576
	v_or_b32_e32 v112, 48, v164
	v_mov_b32_e32 v113, v165
	v_lshlrev_b64 v[96:97], 12, v[112:113]
	v_lshl_add_u64 v[96:97], v[166:167], 0, v[96:97]
	global_load_dwordx4 v[108:111], v[96:97], off
	global_load_dwordx4 v[104:107], v[96:97], off offset:64
	global_load_dwordx4 v[100:103], v[96:97], off offset:512
	s_nop 0
	global_load_dwordx4 v[96:99], v[96:97], off offset:576
	v_lshlrev_b64 v[134:135], 10, v[114:115]
	v_lshl_add_u64 v[134:135], v[134:135], 0, v[162:163]
	v_lshl_add_u64 v[136:137], v[134:135], 2, s[78:79]
	v_lshlrev_b64 v[134:135], 1, v[134:135]
	v_lshl_add_u64 v[138:139], s[2:3], 0, v[134:135]
	s_waitcnt vmcnt(0)
	v_or_b32_e32 v140, 32, v134
	v_mov_b32_e32 v141, v135
	v_or_b32_e32 v142, 0x100, v134
	v_mov_b32_e32 v143, v135
	v_or_b32_e32 v134, 0x120, v134
	v_lshl_add_u64 v[140:141], s[2:3], 0, v[140:141]
	v_lshl_add_u64 v[142:143], s[2:3], 0, v[142:143]
	s_waitcnt vmcnt(0)
	v_pk_fma_f32 v[92:93], v[92:93], 0.5, v[118:119] op_sel_hi:[1,0,1]
	v_pk_fma_f32 v[88:89], v[88:89], 0.5, v[122:123] op_sel_hi:[1,0,1]
	v_pk_fma_f32 v[84:85], v[84:85], 0.5, v[126:127] op_sel_hi:[1,0,1]
	v_mul_f32_e32 v117, v92, v92
	v_mul_f32_e32 v122, v88, v88
	v_pk_fma_f32 v[94:95], v[94:95], 0.5, v[120:121] op_sel_hi:[1,0,1]
	v_pk_fma_f32 v[90:91], v[90:91], 0.5, v[124:125] op_sel_hi:[1,0,1]
	v_pk_fma_f32 v[118:119], v[80:81], 0.5, v[130:131] op_sel_hi:[1,0,1]
	v_mul_f32_e32 v123, v84, v84
	v_fmac_f32_e32 v117, v93, v93
	v_fmac_f32_e32 v122, v89, v89
	v_pk_fma_f32 v[86:87], v[86:87], 0.5, v[128:129] op_sel_hi:[1,0,1]
	v_mul_f32_e32 v124, v118, v118
	v_fmac_f32_e32 v123, v85, v85
	v_fmac_f32_e32 v117, v94, v94
	v_fmac_f32_e32 v122, v90, v90
	v_pk_fma_f32 v[120:121], v[82:83], 0.5, v[132:133] op_sel_hi:[1,0,1]
	v_cvt_pk_bf16_f32 v80, v92, v93
	v_fmac_f32_e32 v124, v119, v119
	v_fmac_f32_e32 v123, v86, v86
	v_fmac_f32_e32 v117, v95, v95
	v_fmac_f32_e32 v122, v91, v91
	global_store_dwordx4 v[136:137], v[92:95], off
	v_cvt_pk_bf16_f32 v81, v94, v95
	s_nop 1
	v_mov_b32_e32 v240, v80
	v_mov_b32_e32 v241, v81
	v_lshl_add_u64 v[244:245], v[138:139], 0, v[246:247]
	v_fmac_f32_e32 v124, v120, v120
	v_fmac_f32_e32 v123, v87, v87
	v_add_f32_e32 v80, v117, v122
	v_add_f32_e32 v80, v80, v123
	v_fmac_f32_e32 v124, v121, v121
	v_add_f32_e32 v80, v80, v124
	ds_bpermute_b32 v81, v189, v80
	v_cvt_pk_bf16_f32 v82, v88, v89
	v_cvt_pk_bf16_f32 v83, v90, v91
	v_cvt_pk_bf16_f32 v92, v84, v85
	global_store_dwordx4 v[136:137], v[88:91], off offset:64
	v_mov_b32_e32 v242, v82
	v_mov_b32_e32 v243, v83
	s_nop 1
	v_permlane16_swap_b32 v240, v242
	v_permlane16_swap_b32 v241, v243
	global_store_dwordx4 v[244:245], v[240:243], off
	s_waitcnt lgkmcnt(0)
	v_add_f32_e32 v80, v80, v81
	ds_bpermute_b32 v81, v116, v80
	v_cvt_pk_bf16_f32 v93, v86, v87
	v_lshl_add_u64 v[82:83], s[2:3], 0, v[134:135]
	global_store_dwordx4 v[136:137], v[84:87], off offset:512
	s_nop 1
	v_mov_b32_e32 v240, v92
	v_mov_b32_e32 v241, v93
	v_lshl_add_u64 v[244:245], v[142:143], 0, v[246:247]
	global_store_dwordx4 v[136:137], v[118:121], off offset:576
	v_cvt_pk_bf16_f32 v84, v118, v119
	v_cvt_pk_bf16_f32 v85, v120, v121
	v_mov_b32_e32 v242, v84
	v_mov_b32_e32 v243, v85
	s_nop 1
	v_permlane16_swap_b32 v240, v242
	v_permlane16_swap_b32 v241, v243
	global_store_dwordx4 v[244:245], v[240:243], off
	s_and_saveexec_b64 s[26:27], s[6:7]
	s_cbranch_execz .LBB0_1649
	v_lshlrev_b64 v[82:83], 6, v[114:115]
	v_lshl_add_u64 v[82:83], s[4:5], 0, v[82:83]
	v_lshl_add_u64 v[82:83], s[24:25], 2, v[82:83]
	s_lshl_b32 s16, s49, 2
	v_lshl_add_u64 v[82:83], v[82:83], 0, s[16:17]
	s_waitcnt lgkmcnt(0)
	v_add_f32_e32 v80, v80, v81
	v_mov_b32_e32 v232, v82
	v_mov_b32_e32 v233, v83
	v_mov_b32_e32 v234, v80
.LBB0_1649:
	s_or_b64 exec, exec, s[26:27]
	s_waitcnt lgkmcnt(0)
	v_lshlrev_b64 v[80:81], 10, v[112:113]
	v_lshl_add_u64 v[80:81], v[80:81], 0, v[162:163]
	v_lshl_add_u64 v[82:83], v[80:81], 2, s[78:79]
	v_lshlrev_b64 v[80:81], 1, v[80:81]
	v_pk_fma_f32 v[78:79], v[78:79], 0.5, v[110:111] op_sel_hi:[1,0,1]
	v_pk_fma_f32 v[76:77], v[76:77], 0.5, v[108:109] op_sel_hi:[1,0,1]
	v_lshl_add_u64 v[84:85], s[2:3], 0, v[80:81]
	global_store_dwordx4 v[82:83], v[76:79], off
	v_cvt_pk_bf16_f32 v86, v76, v77
	v_cvt_pk_bf16_f32 v87, v78, v79
	s_nop 1
	v_mov_b32_e32 v240, v86
	v_mov_b32_e32 v241, v87
	v_lshl_add_u64 v[244:245], v[84:85], 0, v[246:247]
	v_mul_f32_e32 v84, v76, v76
	v_fmac_f32_e32 v84, v77, v77
	v_pk_fma_f32 v[74:75], v[74:75], 0.5, v[106:107] op_sel_hi:[1,0,1]
	v_pk_fma_f32 v[72:73], v[72:73], 0.5, v[104:105] op_sel_hi:[1,0,1]
	v_fmac_f32_e32 v84, v78, v78
	global_store_dwordx4 v[82:83], v[72:75], off offset:64
	v_or_b32_e32 v76, 32, v80
	v_mov_b32_e32 v77, v81
	v_cvt_pk_bf16_f32 v78, v72, v73
	v_mul_f32_e32 v72, v72, v72
	v_lshl_add_u64 v[76:77], s[2:3], 0, v[76:77]
	v_fmac_f32_e32 v72, v73, v73
	v_pk_fma_f32 v[70:71], v[70:71], 0.5, v[102:103] op_sel_hi:[1,0,1]
	v_pk_fma_f32 v[68:69], v[68:69], 0.5, v[100:101] op_sel_hi:[1,0,1]
	v_fmac_f32_e32 v84, v79, v79
	v_cvt_pk_bf16_f32 v79, v74, v75
	v_mov_b32_e32 v242, v78
	v_mov_b32_e32 v243, v79
	s_nop 1
	v_permlane16_swap_b32 v240, v242
	v_permlane16_swap_b32 v241, v243
	global_store_dwordx4 v[244:245], v[240:243], off
	v_fmac_f32_e32 v72, v74, v74
	global_store_dwordx4 v[82:83], v[68:71], off offset:512
	v_cvt_pk_bf16_f32 v74, v68, v69
	v_fmac_f32_e32 v72, v75, v75
	v_add_f32_e32 v75, v84, v72
	v_mul_f32_e32 v68, v68, v68
	v_fmac_f32_e32 v68, v69, v69
	v_fmac_f32_e32 v68, v70, v70
	v_fmac_f32_e32 v68, v71, v71
	v_add_f32_e32 v75, v75, v68
	v_pk_fma_f32 v[68:69], v[66:67], 0.5, v[98:99] op_sel_hi:[1,0,1]
	v_pk_fma_f32 v[66:67], v[64:65], 0.5, v[96:97] op_sel_hi:[1,0,1]
	v_or_b32_e32 v72, 0x100, v80
	v_mul_f32_e32 v64, v66, v66
	v_fmac_f32_e32 v64, v67, v67
	v_fmac_f32_e32 v64, v68, v68
	v_fmac_f32_e32 v64, v69, v69
	v_add_f32_e32 v64, v75, v64
	ds_bpermute_b32 v65, v189, v64
	v_mov_b32_e32 v73, v81
	v_or_b32_e32 v80, 0x120, v80
	v_lshl_add_u64 v[72:73], s[2:3], 0, v[72:73]
	v_cvt_pk_bf16_f32 v75, v70, v71
	s_waitcnt lgkmcnt(0)
	v_add_f32_e32 v64, v64, v65
	ds_bpermute_b32 v65, v116, v64
	v_lshl_add_u64 v[70:71], s[2:3], 0, v[80:81]
	s_nop 1
	v_mov_b32_e32 v240, v74
	v_mov_b32_e32 v241, v75
	v_lshl_add_u64 v[244:245], v[72:73], 0, v[246:247]
	global_store_dwordx4 v[82:83], v[66:69], off offset:576
	s_nop 1
	v_cvt_pk_bf16_f32 v66, v66, v67
	v_cvt_pk_bf16_f32 v67, v68, v69
	v_mov_b32_e32 v242, v66
	v_mov_b32_e32 v243, v67
	s_nop 1
	v_permlane16_swap_b32 v240, v242
	v_permlane16_swap_b32 v241, v243
	global_store_dwordx4 v[244:245], v[240:243], off
	s_and_saveexec_b64 s[26:27], s[6:7]
	s_cbranch_execz .LBB0_1651
	v_lshlrev_b64 v[66:67], 6, v[112:113]
	v_lshl_add_u64 v[66:67], s[4:5], 0, v[66:67]
	v_lshl_add_u64 v[66:67], s[24:25], 2, v[66:67]
	s_lshl_b32 s16, s49, 2
	v_lshl_add_u64 v[66:67], v[66:67], 0, s[16:17]
	s_waitcnt lgkmcnt(0)
	v_add_f32_e32 v64, v64, v65
	v_mov_b32_e32 v236, v66
	v_mov_b32_e32 v237, v67
	v_mov_b32_e32 v238, v64
.LBB0_1651:
	s_or_b64 exec, exec, s[26:27]
	s_nop 4
	v_permlane16_swap_b32 v236, v232
	v_permlane16_swap_b32 v237, v233
	v_permlane16_swap_b32 v238, v234
	s_mov_b64 s[26:27], exec
	s_mov_b64 exec, 0xffffffff
	global_store_dword v[236:237], v238, off
	s_mov_b64 exec, s[26:27]
	v_lshl_add_u64 v[82:83], v[164:165], 0, s[14:15]
	s_waitcnt lgkmcnt(0)
	v_lshlrev_b64 v[64:65], 12, v[82:83]
	v_lshl_add_u64 v[64:65], v[166:167], 0, v[64:65]
	global_load_dwordx4 v[84:87], v[64:65], off
	global_load_dwordx4 v[88:91], v[64:65], off offset:64
	global_load_dwordx4 v[92:95], v[64:65], off offset:512
	global_load_dwordx4 v[96:99], v[64:65], off offset:576
	v_lshl_add_u64 v[80:81], v[164:165], 0, s[18:19]
	v_lshlrev_b64 v[64:65], 12, v[80:81]
	v_lshl_add_u64 v[64:65], v[166:167], 0, v[64:65]
	global_load_dwordx4 v[76:79], v[64:65], off
	global_load_dwordx4 v[72:75], v[64:65], off offset:64
	global_load_dwordx4 v[68:71], v[64:65], off offset:512
	s_nop 0
	global_load_dwordx4 v[64:67], v[64:65], off offset:576
	v_lshlrev_b64 v[100:101], 10, v[82:83]
	v_lshl_add_u64 v[100:101], v[100:101], 0, v[162:163]
	v_lshl_add_u64 v[102:103], v[100:101], 2, s[78:79]
	v_lshlrev_b64 v[100:101], 1, v[100:101]
	v_lshl_add_u64 v[104:105], s[2:3], 0, v[100:101]
	s_waitcnt vmcnt(0)
	v_or_b32_e32 v106, 32, v100
	v_mov_b32_e32 v107, v101
	v_or_b32_e32 v108, 0x100, v100
	v_mov_b32_e32 v109, v101
	v_or_b32_e32 v100, 0x120, v100
	v_lshl_add_u64 v[106:107], s[2:3], 0, v[106:107]
	v_lshl_add_u64 v[108:109], s[2:3], 0, v[108:109]
	s_waitcnt vmcnt(0)
	v_pk_fma_f32 v[60:61], v[60:61], 0.5, v[84:85] op_sel_hi:[1,0,1]
	v_pk_fma_f32 v[56:57], v[56:57], 0.5, v[88:89] op_sel_hi:[1,0,1]
	v_pk_fma_f32 v[52:53], v[52:53], 0.5, v[92:93] op_sel_hi:[1,0,1]
	v_mul_f32_e32 v88, v60, v60
	v_mul_f32_e32 v89, v56, v56
	v_pk_fma_f32 v[62:63], v[62:63], 0.5, v[86:87] op_sel_hi:[1,0,1]
	v_pk_fma_f32 v[58:59], v[58:59], 0.5, v[90:91] op_sel_hi:[1,0,1]
	v_pk_fma_f32 v[84:85], v[48:49], 0.5, v[96:97] op_sel_hi:[1,0,1]
	v_mul_f32_e32 v90, v52, v52
	v_fmac_f32_e32 v88, v61, v61
	v_fmac_f32_e32 v89, v57, v57
	v_pk_fma_f32 v[54:55], v[54:55], 0.5, v[94:95] op_sel_hi:[1,0,1]
	v_mul_f32_e32 v91, v84, v84
	v_fmac_f32_e32 v90, v53, v53
	v_fmac_f32_e32 v88, v62, v62
	v_fmac_f32_e32 v89, v58, v58
	v_pk_fma_f32 v[86:87], v[50:51], 0.5, v[98:99] op_sel_hi:[1,0,1]
	v_cvt_pk_bf16_f32 v48, v60, v61
	v_fmac_f32_e32 v91, v85, v85
	v_fmac_f32_e32 v90, v54, v54
	v_fmac_f32_e32 v88, v63, v63
	v_fmac_f32_e32 v89, v59, v59
	global_store_dwordx4 v[102:103], v[60:63], off
	v_cvt_pk_bf16_f32 v49, v62, v63
	s_nop 1
	v_mov_b32_e32 v240, v48
	v_mov_b32_e32 v241, v49
	v_lshl_add_u64 v[244:245], v[104:105], 0, v[246:247]
	v_fmac_f32_e32 v91, v86, v86
	v_fmac_f32_e32 v90, v55, v55
	v_add_f32_e32 v48, v88, v89
	v_add_f32_e32 v48, v48, v90
	v_fmac_f32_e32 v91, v87, v87
	v_add_f32_e32 v48, v48, v91
	ds_bpermute_b32 v49, v189, v48
	v_cvt_pk_bf16_f32 v50, v56, v57
	v_cvt_pk_bf16_f32 v51, v58, v59
	v_cvt_pk_bf16_f32 v60, v52, v53
	global_store_dwordx4 v[102:103], v[56:59], off offset:64
	v_mov_b32_e32 v242, v50
	v_mov_b32_e32 v243, v51
	s_nop 1
	v_permlane16_swap_b32 v240, v242
	v_permlane16_swap_b32 v241, v243
	global_store_dwordx4 v[244:245], v[240:243], off
	s_waitcnt lgkmcnt(0)
	v_add_f32_e32 v48, v48, v49
	ds_bpermute_b32 v49, v116, v48
	v_cvt_pk_bf16_f32 v61, v54, v55
	v_lshl_add_u64 v[50:51], s[2:3], 0, v[100:101]
	global_store_dwordx4 v[102:103], v[52:55], off offset:512
	s_nop 1
	v_mov_b32_e32 v240, v60
	v_mov_b32_e32 v241, v61
	v_lshl_add_u64 v[244:245], v[108:109], 0, v[246:247]
	global_store_dwordx4 v[102:103], v[84:87], off offset:576
	v_cvt_pk_bf16_f32 v52, v84, v85
	v_cvt_pk_bf16_f32 v53, v86, v87
	v_mov_b32_e32 v242, v52
	v_mov_b32_e32 v243, v53
	s_nop 1
	v_permlane16_swap_b32 v240, v242
	v_permlane16_swap_b32 v241, v243
	global_store_dwordx4 v[244:245], v[240:243], off
	s_and_saveexec_b64 s[26:27], s[6:7]
	s_cbranch_execz .LBB0_1653
	v_lshlrev_b64 v[50:51], 6, v[82:83]
	v_lshl_add_u64 v[50:51], s[4:5], 0, v[50:51]
	v_lshl_add_u64 v[50:51], s[24:25], 2, v[50:51]
	s_lshl_b32 s16, s49, 2
	v_lshl_add_u64 v[50:51], v[50:51], 0, s[16:17]
	s_waitcnt lgkmcnt(0)
	v_add_f32_e32 v48, v48, v49
	v_mov_b32_e32 v232, v50
	v_mov_b32_e32 v233, v51
	v_mov_b32_e32 v234, v48
.LBB0_1653:
	s_or_b64 exec, exec, s[26:27]
	s_waitcnt lgkmcnt(0)
	v_lshlrev_b64 v[48:49], 10, v[80:81]
	v_lshl_add_u64 v[48:49], v[48:49], 0, v[162:163]
	v_lshl_add_u64 v[50:51], v[48:49], 2, s[78:79]
	v_lshlrev_b64 v[48:49], 1, v[48:49]
	v_pk_fma_f32 v[46:47], v[46:47], 0.5, v[78:79] op_sel_hi:[1,0,1]
	v_pk_fma_f32 v[44:45], v[44:45], 0.5, v[76:77] op_sel_hi:[1,0,1]
	v_lshl_add_u64 v[52:53], s[2:3], 0, v[48:49]
	global_store_dwordx4 v[50:51], v[44:47], off
	v_cvt_pk_bf16_f32 v54, v44, v45
	v_cvt_pk_bf16_f32 v55, v46, v47
	s_nop 1
	v_mov_b32_e32 v240, v54
	v_mov_b32_e32 v241, v55
	v_lshl_add_u64 v[244:245], v[52:53], 0, v[246:247]
	v_mul_f32_e32 v52, v44, v44
	v_fmac_f32_e32 v52, v45, v45
	v_pk_fma_f32 v[42:43], v[42:43], 0.5, v[74:75] op_sel_hi:[1,0,1]
	v_pk_fma_f32 v[40:41], v[40:41], 0.5, v[72:73] op_sel_hi:[1,0,1]
	v_fmac_f32_e32 v52, v46, v46
	global_store_dwordx4 v[50:51], v[40:43], off offset:64
	v_or_b32_e32 v44, 32, v48
	v_mov_b32_e32 v45, v49
	v_cvt_pk_bf16_f32 v46, v40, v41
	v_mul_f32_e32 v40, v40, v40
	v_lshl_add_u64 v[44:45], s[2:3], 0, v[44:45]
	v_fmac_f32_e32 v40, v41, v41
	v_pk_fma_f32 v[38:39], v[38:39], 0.5, v[70:71] op_sel_hi:[1,0,1]
	v_pk_fma_f32 v[36:37], v[36:37], 0.5, v[68:69] op_sel_hi:[1,0,1]
	v_fmac_f32_e32 v52, v47, v47
	v_cvt_pk_bf16_f32 v47, v42, v43
	v_mov_b32_e32 v242, v46
	v_mov_b32_e32 v243, v47
	s_nop 1
	v_permlane16_swap_b32 v240, v242
	v_permlane16_swap_b32 v241, v243
	global_store_dwordx4 v[244:245], v[240:243], off
	v_fmac_f32_e32 v40, v42, v42
	global_store_dwordx4 v[50:51], v[36:39], off offset:512
	v_cvt_pk_bf16_f32 v42, v36, v37
	v_fmac_f32_e32 v40, v43, v43
	v_add_f32_e32 v43, v52, v40
	v_mul_f32_e32 v36, v36, v36
	v_fmac_f32_e32 v36, v37, v37
	v_fmac_f32_e32 v36, v38, v38
	v_fmac_f32_e32 v36, v39, v39
	v_add_f32_e32 v43, v43, v36
	v_pk_fma_f32 v[36:37], v[34:35], 0.5, v[66:67] op_sel_hi:[1,0,1]
	v_pk_fma_f32 v[34:35], v[32:33], 0.5, v[64:65] op_sel_hi:[1,0,1]
	v_or_b32_e32 v40, 0x100, v48
	v_mul_f32_e32 v32, v34, v34
	v_fmac_f32_e32 v32, v35, v35
	v_fmac_f32_e32 v32, v36, v36
	v_fmac_f32_e32 v32, v37, v37
	v_add_f32_e32 v32, v43, v32
	ds_bpermute_b32 v33, v189, v32
	v_mov_b32_e32 v41, v49
	v_or_b32_e32 v48, 0x120, v48
	v_lshl_add_u64 v[40:41], s[2:3], 0, v[40:41]
	v_cvt_pk_bf16_f32 v43, v38, v39
	s_waitcnt lgkmcnt(0)
	v_add_f32_e32 v32, v32, v33
	ds_bpermute_b32 v33, v116, v32
	v_lshl_add_u64 v[38:39], s[2:3], 0, v[48:49]
	s_nop 1
	v_mov_b32_e32 v240, v42
	v_mov_b32_e32 v241, v43
	v_lshl_add_u64 v[244:245], v[40:41], 0, v[246:247]
	global_store_dwordx4 v[50:51], v[34:37], off offset:576
	s_nop 1
	v_cvt_pk_bf16_f32 v34, v34, v35
	v_cvt_pk_bf16_f32 v35, v36, v37
	v_mov_b32_e32 v242, v34
	v_mov_b32_e32 v243, v35
	s_nop 1
	v_permlane16_swap_b32 v240, v242
	v_permlane16_swap_b32 v241, v243
	global_store_dwordx4 v[244:245], v[240:243], off
	s_and_saveexec_b64 s[26:27], s[6:7]
	s_cbranch_execz .LBB0_1655
	v_lshlrev_b64 v[34:35], 6, v[80:81]
	v_lshl_add_u64 v[34:35], s[4:5], 0, v[34:35]
	v_lshl_add_u64 v[34:35], s[24:25], 2, v[34:35]
	s_lshl_b32 s16, s49, 2
	v_lshl_add_u64 v[34:35], v[34:35], 0, s[16:17]
	s_waitcnt lgkmcnt(0)
	v_add_f32_e32 v32, v32, v33
	v_mov_b32_e32 v236, v34
	v_mov_b32_e32 v237, v35
	v_mov_b32_e32 v238, v32
.LBB0_1655:
	s_or_b64 exec, exec, s[26:27]
	s_nop 4
	v_permlane16_swap_b32 v236, v232
	v_permlane16_swap_b32 v237, v233
	v_permlane16_swap_b32 v238, v234
	s_mov_b64 s[26:27], exec
	s_mov_b64 exec, 0xffffffff
	global_store_dword v[236:237], v238, off
	s_mov_b64 exec, s[26:27]
	v_lshl_add_u64 v[50:51], v[164:165], 0, s[20:21]
	s_waitcnt lgkmcnt(0)
	v_lshlrev_b64 v[32:33], 12, v[50:51]
	v_lshl_add_u64 v[32:33], v[166:167], 0, v[32:33]
	global_load_dwordx4 v[52:55], v[32:33], off
	global_load_dwordx4 v[56:59], v[32:33], off offset:64
	global_load_dwordx4 v[60:63], v[32:33], off offset:512
	global_load_dwordx4 v[64:67], v[32:33], off offset:576
	v_lshl_add_u64 v[48:49], v[164:165], 0, s[22:23]
	v_lshlrev_b64 v[32:33], 12, v[48:49]
	v_lshl_add_u64 v[32:33], v[166:167], 0, v[32:33]
	global_load_dwordx4 v[44:47], v[32:33], off
	global_load_dwordx4 v[40:43], v[32:33], off offset:64
	global_load_dwordx4 v[36:39], v[32:33], off offset:512
	s_nop 0
	global_load_dwordx4 v[32:35], v[32:33], off offset:576
	v_lshlrev_b64 v[68:69], 10, v[50:51]
	v_lshl_add_u64 v[68:69], v[68:69], 0, v[162:163]
	v_lshl_add_u64 v[70:71], v[68:69], 2, s[78:79]
	v_lshlrev_b64 v[68:69], 1, v[68:69]
	v_lshl_add_u64 v[72:73], s[2:3], 0, v[68:69]
	s_waitcnt vmcnt(0)
	v_or_b32_e32 v74, 32, v68
	v_mov_b32_e32 v75, v69
	v_or_b32_e32 v76, 0x100, v68
	v_mov_b32_e32 v77, v69
	v_or_b32_e32 v68, 0x120, v68
	v_lshl_add_u64 v[74:75], s[2:3], 0, v[74:75]
	v_lshl_add_u64 v[76:77], s[2:3], 0, v[76:77]
	s_waitcnt vmcnt(0)
	v_pk_fma_f32 v[28:29], v[28:29], 0.5, v[52:53] op_sel_hi:[1,0,1]
	v_pk_fma_f32 v[24:25], v[24:25], 0.5, v[56:57] op_sel_hi:[1,0,1]
	v_pk_fma_f32 v[20:21], v[20:21], 0.5, v[60:61] op_sel_hi:[1,0,1]
	v_mul_f32_e32 v56, v28, v28
	v_mul_f32_e32 v57, v24, v24
	v_pk_fma_f32 v[30:31], v[30:31], 0.5, v[54:55] op_sel_hi:[1,0,1]
	v_pk_fma_f32 v[26:27], v[26:27], 0.5, v[58:59] op_sel_hi:[1,0,1]
	v_pk_fma_f32 v[52:53], v[16:17], 0.5, v[64:65] op_sel_hi:[1,0,1]
	v_mul_f32_e32 v58, v20, v20
	v_fmac_f32_e32 v56, v29, v29
	v_fmac_f32_e32 v57, v25, v25
	v_pk_fma_f32 v[22:23], v[22:23], 0.5, v[62:63] op_sel_hi:[1,0,1]
	v_mul_f32_e32 v59, v52, v52
	v_fmac_f32_e32 v58, v21, v21
	v_fmac_f32_e32 v56, v30, v30
	v_fmac_f32_e32 v57, v26, v26
	v_pk_fma_f32 v[54:55], v[18:19], 0.5, v[66:67] op_sel_hi:[1,0,1]
	v_cvt_pk_bf16_f32 v16, v28, v29
	v_fmac_f32_e32 v59, v53, v53
	v_fmac_f32_e32 v58, v22, v22
	v_fmac_f32_e32 v56, v31, v31
	v_fmac_f32_e32 v57, v27, v27
	global_store_dwordx4 v[70:71], v[28:31], off
	v_cvt_pk_bf16_f32 v17, v30, v31
	s_nop 1
	v_mov_b32_e32 v240, v16
	v_mov_b32_e32 v241, v17
	v_lshl_add_u64 v[244:245], v[72:73], 0, v[246:247]
	v_fmac_f32_e32 v59, v54, v54
	v_fmac_f32_e32 v58, v23, v23
	v_add_f32_e32 v16, v56, v57
	v_add_f32_e32 v16, v16, v58
	v_fmac_f32_e32 v59, v55, v55
	v_add_f32_e32 v16, v16, v59
	ds_bpermute_b32 v17, v189, v16
	v_cvt_pk_bf16_f32 v18, v24, v25
	v_cvt_pk_bf16_f32 v19, v26, v27
	v_cvt_pk_bf16_f32 v28, v20, v21
	global_store_dwordx4 v[70:71], v[24:27], off offset:64
	v_mov_b32_e32 v242, v18
	v_mov_b32_e32 v243, v19
	s_nop 1
	v_permlane16_swap_b32 v240, v242
	v_permlane16_swap_b32 v241, v243
	global_store_dwordx4 v[244:245], v[240:243], off
	s_waitcnt lgkmcnt(0)
	v_add_f32_e32 v16, v16, v17
	ds_bpermute_b32 v17, v116, v16
	v_cvt_pk_bf16_f32 v29, v22, v23
	v_lshl_add_u64 v[18:19], s[2:3], 0, v[68:69]
	global_store_dwordx4 v[70:71], v[20:23], off offset:512
	s_nop 1
	v_mov_b32_e32 v240, v28
	v_mov_b32_e32 v241, v29
	v_lshl_add_u64 v[244:245], v[76:77], 0, v[246:247]
	global_store_dwordx4 v[70:71], v[52:55], off offset:576
	v_cvt_pk_bf16_f32 v20, v52, v53
	v_cvt_pk_bf16_f32 v21, v54, v55
	v_mov_b32_e32 v242, v20
	v_mov_b32_e32 v243, v21
	s_nop 1
	v_permlane16_swap_b32 v240, v242
	v_permlane16_swap_b32 v241, v243
	global_store_dwordx4 v[244:245], v[240:243], off
	s_and_saveexec_b64 s[26:27], s[6:7]
	s_cbranch_execz .LBB0_1657
	v_lshlrev_b64 v[18:19], 6, v[50:51]
	v_lshl_add_u64 v[18:19], s[4:5], 0, v[18:19]
	v_lshl_add_u64 v[18:19], s[24:25], 2, v[18:19]
	s_lshl_b32 s16, s49, 2
	v_lshl_add_u64 v[18:19], v[18:19], 0, s[16:17]
	s_waitcnt lgkmcnt(0)
	v_add_f32_e32 v16, v16, v17
	flat_store_dword v[18:19], v16

.LBB0_1812:
	ds_read_b128 v[128:131], v173
	ds_read_b128 v[132:135], v174
	ds_read_b128 v[136:139], v175
	ds_read_b128 v[140:143], v177
	s_add_u32 s30, s28, 0xfff50080
	s_addc_u32 s31, s29, -1
	s_cmp_eq_u32 s67, 40
	s_cselect_b32 s35, s11, s31
	s_cselect_b32 s34, s10, s30
	s_cselect_b32 s31, s13, s66
	s_cselect_b32 s30, s12, s27
	s_mov_b32 m0, s61
	v_lshl_add_u64 v[216:217], s[28:29], 0, v[156:157]
	ds_read_b128 v[162:165], v172
	ds_read_b128 v[166:169], v172 offset:1024
	ds_read_b128 v[192:195], v172 offset:2048
	ds_read_b128 v[196:199], v172 offset:3072
	ds_read_b128 v[200:203], v172 offset:4096
	ds_read_b128 v[204:207], v172 offset:5120
	ds_read_b128 v[208:211], v172 offset:6144
	ds_read_b128 v[212:215], v172 offset:7168
	global_load_lds_dwordx4 v[216:217], off
	v_lshl_add_u64 v[216:217], s[28:29], 0, v[154:155]
	s_mov_b32 m0, s62
	s_nop 0
	global_load_lds_dwordx4 v[216:217], off
	s_waitcnt lgkmcnt(8)
	s_barrier
	s_waitcnt lgkmcnt(0)
	s_setprio 1
	s_waitcnt lgkmcnt(0)
	v_mfma_f32_16x16x32_bf16 v[124:127], v[128:131], v[162:165], v[124:127]
	v_mfma_f32_16x16x32_bf16 v[120:123], v[136:139], v[162:165], v[120:123]
	v_mfma_f32_16x16x32_bf16 v[108:111], v[128:131], v[192:195], v[108:111]
	v_mfma_f32_16x16x32_bf16 v[104:107], v[136:139], v[192:195], v[104:107]
	v_mfma_f32_16x16x32_bf16 v[92:95], v[128:131], v[200:203], v[92:95]
	v_mfma_f32_16x16x32_bf16 v[88:91], v[136:139], v[200:203], v[88:91]
	v_mfma_f32_16x16x32_bf16 v[76:79], v[128:131], v[208:211], v[76:79]
	v_mfma_f32_16x16x32_bf16 v[72:75], v[136:139], v[208:211], v[72:75]
	v_mfma_f32_16x16x32_bf16 v[124:127], v[132:135], v[166:169], v[124:127]
	v_mfma_f32_16x16x32_bf16 v[120:123], v[140:143], v[166:169], v[120:123]
	v_mfma_f32_16x16x32_bf16 v[108:111], v[132:135], v[196:199], v[108:111]
	v_mfma_f32_16x16x32_bf16 v[104:107], v[140:143], v[196:199], v[104:107]
	v_mfma_f32_16x16x32_bf16 v[92:95], v[132:135], v[204:207], v[92:95]
	v_mfma_f32_16x16x32_bf16 v[88:91], v[140:143], v[204:207], v[88:91]
	v_mfma_f32_16x16x32_bf16 v[76:79], v[132:135], v[212:215], v[76:79]
	v_mfma_f32_16x16x32_bf16 v[72:75], v[140:143], v[212:215], v[72:75]
	s_setprio 0
	s_barrier
	s_mov_b32 m0, s44
	v_lshl_add_u64 v[232:233], s[30:31], 0, v[144:145]
	ds_read_b128 v[216:219], v178
	ds_read_b128 v[220:223], v180
	ds_read_b128 v[224:227], v181
	ds_read_b128 v[228:231], v182
	global_load_lds_dwordx4 v[232:233], off
	v_lshl_add_u64 v[234:235], s[30:31], 0, v[146:147]
	s_mov_b32 m0, s45
	s_nop 0
	global_load_lds_dwordx4 v[234:235], off
	s_barrier
	s_waitcnt lgkmcnt(0)
	s_setprio 1
	s_waitcnt lgkmcnt(0)
	v_mfma_f32_16x16x32_bf16 v[116:119], v[216:219], v[162:165], v[116:119]
	v_mfma_f32_16x16x32_bf16 v[112:115], v[224:227], v[162:165], v[112:115]
	v_mfma_f32_16x16x32_bf16 v[100:103], v[216:219], v[192:195], v[100:103]
	v_mfma_f32_16x16x32_bf16 v[96:99], v[224:227], v[192:195], v[96:99]
	v_mfma_f32_16x16x32_bf16 v[84:87], v[216:219], v[200:203], v[84:87]
	v_mfma_f32_16x16x32_bf16 v[80:83], v[224:227], v[200:203], v[80:83]
	v_mfma_f32_16x16x32_bf16 v[68:71], v[216:219], v[208:211], v[68:71]
	v_mfma_f32_16x16x32_bf16 v[64:67], v[224:227], v[208:211], v[64:67]
	v_mfma_f32_16x16x32_bf16 v[116:119], v[220:223], v[166:169], v[116:119]
	v_mfma_f32_16x16x32_bf16 v[112:115], v[228:231], v[166:169], v[112:115]
	v_mfma_f32_16x16x32_bf16 v[100:103], v[220:223], v[196:199], v[100:103]
	v_mfma_f32_16x16x32_bf16 v[96:99], v[228:231], v[196:199], v[96:99]
	v_mfma_f32_16x16x32_bf16 v[84:87], v[220:223], v[204:207], v[84:87]
	v_mfma_f32_16x16x32_bf16 v[80:83], v[228:231], v[204:207], v[80:83]
	v_mfma_f32_16x16x32_bf16 v[68:71], v[220:223], v[212:215], v[68:71]
	v_mfma_f32_16x16x32_bf16 v[64:67], v[228:231], v[212:215], v[64:67]
	s_setprio 0
	s_mov_b32 m0, s43
	v_lshl_add_u64 v[236:237], s[34:35], 0, v[144:145]
	s_barrier
	ds_read_b128 v[162:165], v172 offset:16384
	ds_read_b128 v[166:169], v172 offset:17408
	ds_read_b128 v[192:195], v172 offset:18432
	ds_read_b128 v[196:199], v172 offset:19456
	ds_read_b128 v[200:203], v172 offset:20480
	ds_read_b128 v[204:207], v172 offset:21504
	ds_read_b128 v[208:211], v172 offset:22528
	ds_read_b128 v[212:215], v172 offset:23552
	global_load_lds_dwordx4 v[236:237], off
	v_lshl_add_u64 v[238:239], s[34:35], 0, v[146:147]
	s_mov_b32 m0, s46
	s_nop 0
	global_load_lds_dwordx4 v[238:239], off
	s_barrier
	s_waitcnt lgkmcnt(0)
	s_setprio 1
	s_waitcnt lgkmcnt(0)
	v_mfma_f32_16x16x32_bf16 v[60:63], v[128:131], v[162:165], v[60:63]
	v_mfma_f32_16x16x32_bf16 v[56:59], v[136:139], v[162:165], v[56:59]
	v_mfma_f32_16x16x32_bf16 v[44:47], v[128:131], v[192:195], v[44:47]
	v_mfma_f32_16x16x32_bf16 v[40:43], v[136:139], v[192:195], v[40:43]
	v_mfma_f32_16x16x32_bf16 v[28:31], v[128:131], v[200:203], v[28:31]
	v_mfma_f32_16x16x32_bf16 v[24:27], v[136:139], v[200:203], v[24:27]
	v_mfma_f32_16x16x32_bf16 v[12:15], v[128:131], v[208:211], v[12:15]
	v_mfma_f32_16x16x32_bf16 v[8:11], v[136:139], v[208:211], v[8:11]
	v_mfma_f32_16x16x32_bf16 v[60:63], v[132:135], v[166:169], v[60:63]
	v_mfma_f32_16x16x32_bf16 v[56:59], v[140:143], v[166:169], v[56:59]
	v_mfma_f32_16x16x32_bf16 v[44:47], v[132:135], v[196:199], v[44:47]
	v_mfma_f32_16x16x32_bf16 v[40:43], v[140:143], v[196:199], v[40:43]
	v_mfma_f32_16x16x32_bf16 v[28:31], v[132:135], v[204:207], v[28:31]
	v_mfma_f32_16x16x32_bf16 v[24:27], v[140:143], v[204:207], v[24:27]
	v_mfma_f32_16x16x32_bf16 v[12:15], v[132:135], v[212:215], v[12:15]
	v_mfma_f32_16x16x32_bf16 v[8:11], v[140:143], v[212:215], v[8:11]
	s_setprio 0
	s_barrier
	s_add_u32 s68, s30, 0xb0000
	s_addc_u32 s69, s31, 0
	s_mov_b32 m0, s47
	v_lshl_add_u64 v[128:129], s[68:69], 0, v[144:145]
	global_load_lds_dwordx4 v[128:129], off
	v_lshl_add_u64 v[128:129], s[68:69], 0, v[146:147]
	s_mov_b32 m0, s48
	s_nop 0
	global_load_lds_dwordx4 v[128:129], off
	s_waitcnt vmcnt(6)
	s_barrier
	s_setprio 1
	v_mfma_f32_16x16x32_bf16 v[52:55], v[216:219], v[162:165], v[52:55]
	v_mfma_f32_16x16x32_bf16 v[48:51], v[224:227], v[162:165], v[48:51]
	v_mfma_f32_16x16x32_bf16 v[36:39], v[216:219], v[192:195], v[36:39]
	v_mfma_f32_16x16x32_bf16 v[32:35], v[224:227], v[192:195], v[32:35]
	v_mfma_f32_16x16x32_bf16 v[20:23], v[216:219], v[200:203], v[20:23]
	v_mfma_f32_16x16x32_bf16 v[16:19], v[224:227], v[200:203], v[16:19]
	v_mfma_f32_16x16x32_bf16 v[4:7], v[216:219], v[208:211], v[4:7]
	v_mfma_f32_16x16x32_bf16 v[0:3], v[224:227], v[208:211], v[0:3]
	v_mfma_f32_16x16x32_bf16 v[52:55], v[220:223], v[166:169], v[52:55]
	v_mfma_f32_16x16x32_bf16 v[48:51], v[228:231], v[166:169], v[48:51]
	v_mfma_f32_16x16x32_bf16 v[36:39], v[220:223], v[196:199], v[36:39]
	v_mfma_f32_16x16x32_bf16 v[32:35], v[228:231], v[196:199], v[32:35]
	v_mfma_f32_16x16x32_bf16 v[20:23], v[220:223], v[204:207], v[20:23]
	v_mfma_f32_16x16x32_bf16 v[16:19], v[228:231], v[204:207], v[16:19]
	v_mfma_f32_16x16x32_bf16 v[4:7], v[220:223], v[212:215], v[4:7]
	v_mfma_f32_16x16x32_bf16 v[0:3], v[228:231], v[212:215], v[0:3]
	s_setprio 0
	s_barrier
	ds_read_b128 v[128:131], v183
	ds_read_b128 v[132:135], v184
	ds_read_b128 v[136:139], v185
	ds_read_b128 v[140:143], v186
	s_add_u32 s34, s34, 0xb0000
	s_addc_u32 s35, s35, 0
	s_mov_b32 m0, s49
	v_lshl_add_u64 v[216:217], s[34:35], 0, v[144:145]
	ds_read_b128 v[162:165], v172 offset:32768
	ds_read_b128 v[166:169], v172 offset:33792
	ds_read_b128 v[192:195], v172 offset:34816
	ds_read_b128 v[196:199], v172 offset:35840
	ds_read_b128 v[200:203], v172 offset:36864
	ds_read_b128 v[204:207], v172 offset:37888
	ds_read_b128 v[208:211], v172 offset:38912
	ds_read_b128 v[212:215], v172 offset:39936
	global_load_lds_dwordx4 v[216:217], off
	v_lshl_add_u64 v[216:217], s[34:35], 0, v[146:147]
	s_mov_b32 m0, s52
	s_nop 0
	global_load_lds_dwordx4 v[216:217], off
	s_waitcnt lgkmcnt(8)
	s_barrier
	s_waitcnt lgkmcnt(0)
	s_setprio 1
	s_waitcnt lgkmcnt(0)
	v_mfma_f32_16x16x32_bf16 v[124:127], v[128:131], v[162:165], v[124:127]
	v_mfma_f32_16x16x32_bf16 v[120:123], v[136:139], v[162:165], v[120:123]
	v_mfma_f32_16x16x32_bf16 v[108:111], v[128:131], v[192:195], v[108:111]
	v_mfma_f32_16x16x32_bf16 v[104:107], v[136:139], v[192:195], v[104:107]
	v_mfma_f32_16x16x32_bf16 v[92:95], v[128:131], v[200:203], v[92:95]
	v_mfma_f32_16x16x32_bf16 v[88:91], v[136:139], v[200:203], v[88:91]
	v_mfma_f32_16x16x32_bf16 v[76:79], v[128:131], v[208:211], v[76:79]
	v_mfma_f32_16x16x32_bf16 v[72:75], v[136:139], v[208:211], v[72:75]
	v_mfma_f32_16x16x32_bf16 v[124:127], v[132:135], v[166:169], v[124:127]
	v_mfma_f32_16x16x32_bf16 v[120:123], v[140:143], v[166:169], v[120:123]
	v_mfma_f32_16x16x32_bf16 v[108:111], v[132:135], v[196:199], v[108:111]
	v_mfma_f32_16x16x32_bf16 v[104:107], v[140:143], v[196:199], v[104:107]
	v_mfma_f32_16x16x32_bf16 v[92:95], v[132:135], v[204:207], v[92:95]
	v_mfma_f32_16x16x32_bf16 v[88:91], v[140:143], v[204:207], v[88:91]
	v_mfma_f32_16x16x32_bf16 v[76:79], v[132:135], v[212:215], v[76:79]
	v_mfma_f32_16x16x32_bf16 v[72:75], v[140:143], v[212:215], v[72:75]
	s_setprio 0
	s_barrier
	s_mov_b32 m0, s54
	v_lshl_add_u64 v[232:233], v[232:233], 0, s[16:17]
	ds_read_b128 v[216:219], v187
	ds_read_b128 v[220:223], v188
	ds_read_b128 v[224:227], v189
	ds_read_b128 v[228:231], v190
	global_load_lds_dwordx4 v[232:233], off
	v_lshl_add_u64 v[232:233], v[234:235], 0, s[16:17]
	s_mov_b32 m0, s55
	s_nop 0
	global_load_lds_dwordx4 v[232:233], off
	s_barrier
	s_waitcnt lgkmcnt(0)
	s_setprio 1
	s_waitcnt lgkmcnt(0)
	v_mfma_f32_16x16x32_bf16 v[116:119], v[216:219], v[162:165], v[116:119]
	v_mfma_f32_16x16x32_bf16 v[112:115], v[224:227], v[162:165], v[112:115]
	v_mfma_f32_16x16x32_bf16 v[100:103], v[216:219], v[192:195], v[100:103]
	v_mfma_f32_16x16x32_bf16 v[96:99], v[224:227], v[192:195], v[96:99]
	v_mfma_f32_16x16x32_bf16 v[84:87], v[216:219], v[200:203], v[84:87]
	v_mfma_f32_16x16x32_bf16 v[80:83], v[224:227], v[200:203], v[80:83]
	v_mfma_f32_16x16x32_bf16 v[68:71], v[216:219], v[208:211], v[68:71]
	v_mfma_f32_16x16x32_bf16 v[64:67], v[224:227], v[208:211], v[64:67]
	v_mfma_f32_16x16x32_bf16 v[116:119], v[220:223], v[166:169], v[116:119]
	v_mfma_f32_16x16x32_bf16 v[112:115], v[228:231], v[166:169], v[112:115]
	v_mfma_f32_16x16x32_bf16 v[100:103], v[220:223], v[196:199], v[100:103]
	v_mfma_f32_16x16x32_bf16 v[96:99], v[228:231], v[196:199], v[96:99]
	v_mfma_f32_16x16x32_bf16 v[84:87], v[220:223], v[204:207], v[84:87]
	v_mfma_f32_16x16x32_bf16 v[80:83], v[228:231], v[204:207], v[80:83]
	v_mfma_f32_16x16x32_bf16 v[68:71], v[220:223], v[212:215], v[68:71]
	v_mfma_f32_16x16x32_bf16 v[64:67], v[228:231], v[212:215], v[64:67]
	s_setprio 0
	s_mov_b32 m0, s56
	v_lshl_add_u64 v[232:233], v[236:237], 0, s[16:17]
	s_barrier
	ds_read_b128 v[162:165], v172 offset:49152
	ds_read_b128 v[166:169], v172 offset:50176
	ds_read_b128 v[192:195], v172 offset:51200
	ds_read_b128 v[196:199], v172 offset:52224
	ds_read_b128 v[200:203], v172 offset:53248
	ds_read_b128 v[204:207], v172 offset:54272
	ds_read_b128 v[208:211], v172 offset:55296
	ds_read_b128 v[212:215], v172 offset:56320
	global_load_lds_dwordx4 v[232:233], off
	v_lshl_add_u64 v[232:233], v[238:239], 0, s[16:17]
	s_mov_b32 m0, s57
	s_nop 0
	global_load_lds_dwordx4 v[232:233], off
	s_barrier
	s_waitcnt lgkmcnt(0)
	s_setprio 1
	s_waitcnt lgkmcnt(0)
	v_mfma_f32_16x16x32_bf16 v[60:63], v[128:131], v[162:165], v[60:63]
	v_mfma_f32_16x16x32_bf16 v[56:59], v[136:139], v[162:165], v[56:59]
	v_mfma_f32_16x16x32_bf16 v[44:47], v[128:131], v[192:195], v[44:47]
	v_mfma_f32_16x16x32_bf16 v[40:43], v[136:139], v[192:195], v[40:43]
	v_mfma_f32_16x16x32_bf16 v[28:31], v[128:131], v[200:203], v[28:31]
	v_mfma_f32_16x16x32_bf16 v[24:27], v[136:139], v[200:203], v[24:27]
	v_mfma_f32_16x16x32_bf16 v[12:15], v[128:131], v[208:211], v[12:15]
	v_mfma_f32_16x16x32_bf16 v[8:11], v[136:139], v[208:211], v[8:11]
	v_mfma_f32_16x16x32_bf16 v[60:63], v[132:135], v[166:169], v[60:63]
	v_mfma_f32_16x16x32_bf16 v[56:59], v[140:143], v[166:169], v[56:59]
	v_mfma_f32_16x16x32_bf16 v[44:47], v[132:135], v[196:199], v[44:47]
	v_mfma_f32_16x16x32_bf16 v[40:43], v[140:143], v[196:199], v[40:43]
	v_mfma_f32_16x16x32_bf16 v[28:31], v[132:135], v[204:207], v[28:31]
	v_mfma_f32_16x16x32_bf16 v[24:27], v[140:143], v[204:207], v[24:27]
	v_mfma_f32_16x16x32_bf16 v[12:15], v[132:135], v[212:215], v[12:15]
	v_mfma_f32_16x16x32_bf16 v[8:11], v[140:143], v[212:215], v[8:11]
	s_setprio 0
	s_barrier
	s_add_u32 s30, s30, 0xb0080
	s_addc_u32 s31, s31, 0
	s_mov_b32 m0, s58
	v_lshl_add_u64 v[128:129], s[30:31], 0, v[144:145]
	global_load_lds_dwordx4 v[128:129], off
	v_lshl_add_u64 v[128:129], s[30:31], 0, v[146:147]
	s_mov_b32 m0, s59
	s_nop 0
	global_load_lds_dwordx4 v[128:129], off
	s_waitcnt vmcnt(6)
	s_barrier
	s_setprio 1
	v_mfma_f32_16x16x32_bf16 v[52:55], v[216:219], v[162:165], v[52:55]
	v_mfma_f32_16x16x32_bf16 v[48:51], v[224:227], v[162:165], v[48:51]
	v_mfma_f32_16x16x32_bf16 v[36:39], v[216:219], v[192:195], v[36:39]
	v_mfma_f32_16x16x32_bf16 v[32:35], v[224:227], v[192:195], v[32:35]
	v_mfma_f32_16x16x32_bf16 v[20:23], v[216:219], v[200:203], v[20:23]
	v_mfma_f32_16x16x32_bf16 v[16:19], v[224:227], v[200:203], v[16:19]
	v_mfma_f32_16x16x32_bf16 v[4:7], v[216:219], v[208:211], v[4:7]
	v_mfma_f32_16x16x32_bf16 v[0:3], v[224:227], v[208:211], v[0:3]
	v_mfma_f32_16x16x32_bf16 v[52:55], v[220:223], v[166:169], v[52:55]
	v_mfma_f32_16x16x32_bf16 v[48:51], v[228:231], v[166:169], v[48:51]
	v_mfma_f32_16x16x32_bf16 v[36:39], v[220:223], v[196:199], v[36:39]
	v_mfma_f32_16x16x32_bf16 v[32:35], v[228:231], v[196:199], v[32:35]
	v_mfma_f32_16x16x32_bf16 v[20:23], v[220:223], v[204:207], v[20:23]
	v_mfma_f32_16x16x32_bf16 v[16:19], v[228:231], v[204:207], v[16:19]
	v_mfma_f32_16x16x32_bf16 v[4:7], v[220:223], v[212:215], v[4:7]
	v_mfma_f32_16x16x32_bf16 v[0:3], v[228:231], v[212:215], v[0:3]
	s_setprio 0
	s_add_i32 s67, s67, 2
	s_add_u32 s27, s27, 0x100
	s_addc_u32 s66, s66, 0
	s_add_u32 s28, s28, 0x100
	s_addc_u32 s29, s29, 0
	s_cmp_gt_u32 s67, 41
	s_barrier
	s_cbranch_scc0 .LBB0_1812
	s_ashr_i32 s27, s26, 31
	s_lshl_b64 s[26:27], s[26:27], 8
	s_lshl_b32 s28, s18, 8
	v_lshl_add_u64 v[164:165], s[26:27], 0, v[148:149]
	s_ashr_i32 s29, s28, 31
	v_lshl_add_u64 v[166:167], s[28:29], 2, v[152:153]
	v_lshlrev_b64 v[128:129], 12, v[164:165]
	v_lshl_add_u64 v[128:129], v[166:167], 0, v[128:129]
	global_load_dwordx4 v[194:197], v[128:129], off
	global_load_dwordx4 v[198:201], v[128:129], off offset:64
	global_load_dwordx4 v[202:205], v[128:129], off offset:512
	global_load_dwordx4 v[206:209], v[128:129], off offset:576
	v_or_b32_e32 v168, 16, v164
	v_mov_b32_e32 v169, v165
	v_lshlrev_b64 v[128:129], 12, v[168:169]
	v_lshl_add_u64 v[128:129], v[166:167], 0, v[128:129]
	global_load_dwordx4 v[140:143], v[128:129], off
	global_load_dwordx4 v[136:139], v[128:129], off offset:64
	global_load_dwordx4 v[132:135], v[128:129], off offset:512
	s_nop 0
	global_load_dwordx4 v[128:131], v[128:129], off offset:576
	v_and_b32_e32 v163, 64, v191
	v_xor_b32_e32 v192, 16, v191
	v_add_u32_e32 v210, 64, v163
	v_xor_b32_e32 v193, 32, v191
	v_cmp_lt_i32_e32 vcc, v192, v210
	v_or_b32_e32 v162, s28, v150
	v_mov_b32_e32 v163, s29
	v_cndmask_b32_e32 v192, v191, v192, vcc
	v_cmp_lt_i32_e32 vcc, v193, v210
	v_lshlrev_b64 v[210:211], 10, v[164:165]
	v_lshl_add_u64 v[210:211], v[210:211], 0, v[162:163]
	v_lshl_add_u64 v[212:213], v[210:211], 2, s[78:79]
	s_waitcnt vmcnt(0)
	v_lshlrev_b64 v[210:211], 1, v[210:211]
	v_lshl_add_u64 v[214:215], s[4:5], 0, v[210:211]
	v_lshlrev_b32_e32 v192, 2, v192
	v_or_b32_e32 v216, 32, v210
	v_mov_b32_e32 v217, v211
	v_cndmask_b32_e32 v193, v191, v193, vcc
	v_or_b32_e32 v218, 0x100, v210
	v_mov_b32_e32 v219, v211
	v_lshl_add_u64 v[216:217], s[4:5], 0, v[216:217]
	v_lshl_add_u64 v[218:219], s[4:5], 0, v[218:219]
	s_lshl_b32 s26, s18, 2
	v_or_b32_e32 v210, 0x120, v210
	s_ashr_i32 s27, s26, 31
	s_waitcnt vmcnt(0)
	v_pk_fma_f32 v[126:127], v[126:127], 0.5, v[196:197] op_sel_hi:[1,0,1]
	v_pk_fma_f32 v[124:125], v[124:125], 0.5, v[194:195] op_sel_hi:[1,0,1]
	v_pk_fma_f32 v[120:121], v[120:121], 0.5, v[198:199] op_sel_hi:[1,0,1]
	v_pk_fma_f32 v[122:123], v[122:123], 0.5, v[200:201] op_sel_hi:[1,0,1]
	v_pk_fma_f32 v[116:117], v[116:117], 0.5, v[202:203] op_sel_hi:[1,0,1]
	v_pk_fma_f32 v[194:195], v[112:113], 0.5, v[206:207] op_sel_hi:[1,0,1]
	global_store_dwordx4 v[212:213], v[124:127], off
	v_cvt_pk_bf16_f32 v112, v124, v125
	v_mul_f32_e32 v200, v120, v120
	v_mul_f32_e32 v201, v116, v116
	v_mul_f32_e32 v124, v124, v124
	v_fmac_f32_e32 v124, v125, v125
	v_fmac_f32_e32 v200, v121, v121
	v_pk_fma_f32 v[118:119], v[118:119], 0.5, v[204:205] op_sel_hi:[1,0,1]
	v_mul_f32_e32 v202, v194, v194
	v_fmac_f32_e32 v201, v117, v117
	v_fmac_f32_e32 v124, v126, v126
	v_fmac_f32_e32 v200, v122, v122
	v_pk_fma_f32 v[196:197], v[114:115], 0.5, v[208:209] op_sel_hi:[1,0,1]
	v_fmac_f32_e32 v202, v195, v195
	v_fmac_f32_e32 v201, v118, v118
	v_fmac_f32_e32 v124, v127, v127
	v_fmac_f32_e32 v200, v123, v123
	v_cvt_pk_bf16_f32 v113, v126, v127
	v_bfe_u32 v246, v176, 4, 1
	v_mul_u32_u24_e32 v246, 24, v246
	v_mov_b32_e32 v247, 0
	s_nop 1
	v_mov_b32_e32 v240, v112
	v_mov_b32_e32 v241, v113
	v_lshl_add_u64 v[244:245], v[214:215], 0, v[246:247]
	v_fmac_f32_e32 v202, v196, v196
	v_fmac_f32_e32 v201, v119, v119
	v_add_f32_e32 v112, v124, v200
	v_fmac_f32_e32 v202, v197, v197
	v_add_f32_e32 v112, v112, v201
	v_add_f32_e32 v112, v112, v202
	ds_bpermute_b32 v113, v192, v112
	v_cvt_pk_bf16_f32 v114, v120, v121
	v_cvt_pk_bf16_f32 v115, v122, v123
	v_cvt_pk_bf16_f32 v198, v116, v117
	v_cvt_pk_bf16_f32 v199, v118, v119
	global_store_dwordx4 v[212:213], v[120:123], off offset:64
	v_mov_b32_e32 v242, v114
	v_mov_b32_e32 v243, v115
	s_nop 1
	v_permlane16_swap_b32 v240, v242
	v_permlane16_swap_b32 v241, v243
	global_store_dwordx4 v[244:245], v[240:243], off
	global_store_dwordx4 v[212:213], v[116:119], off offset:512
	s_nop 1
	v_mov_b32_e32 v240, v198
	v_mov_b32_e32 v241, v199
	v_lshl_add_u64 v[244:245], v[218:219], 0, v[246:247]
	global_store_dwordx4 v[212:213], v[194:197], off offset:576
	s_waitcnt lgkmcnt(0)
	v_add_f32_e32 v112, v112, v113
	v_lshlrev_b32_e32 v116, 2, v193
	ds_bpermute_b32 v113, v116, v112
	v_lshl_add_u64 v[114:115], s[4:5], 0, v[210:211]
	v_cvt_pk_bf16_f32 v118, v194, v195
	v_cvt_pk_bf16_f32 v119, v196, v197
	v_mov_b32_e32 v242, v118
	v_mov_b32_e32 v243, v119
	s_nop 1
	v_permlane16_swap_b32 v240, v242
	v_permlane16_swap_b32 v241, v243
	global_store_dwordx4 v[244:245], v[240:243], off
	s_and_saveexec_b64 s[28:29], s[6:7]
	s_cbranch_execz .LBB0_1815
	v_lshlrev_b64 v[114:115], 6, v[164:165]
	v_lshl_add_u64 v[114:115], s[14:15], 0, v[114:115]
	v_lshl_add_u64 v[114:115], s[26:27], 2, v[114:115]
	s_lshl_b32 s18, s53, 2
	v_lshl_add_u64 v[114:115], v[114:115], 0, s[18:19]
	s_waitcnt lgkmcnt(0)
	v_add_f32_e32 v112, v112, v113
	v_mov_b32_e32 v232, v114
	v_mov_b32_e32 v233, v115
	v_mov_b32_e32 v234, v112
.LBB0_1815:
	s_or_b64 exec, exec, s[28:29]
	s_waitcnt lgkmcnt(0)
	v_lshlrev_b64 v[112:113], 10, v[168:169]
	v_lshl_add_u64 v[112:113], v[112:113], 0, v[162:163]
	v_pk_fma_f32 v[108:109], v[108:109], 0.5, v[140:141] op_sel_hi:[1,0,1]
	v_lshl_add_u64 v[114:115], v[112:113], 2, s[78:79]
	v_lshlrev_b64 v[112:113], 1, v[112:113]
	v_mul_f32_e32 v117, v108, v108
	v_pk_fma_f32 v[110:111], v[110:111], 0.5, v[142:143] op_sel_hi:[1,0,1]
	v_lshl_add_u64 v[118:119], s[4:5], 0, v[112:113]
	v_fmac_f32_e32 v117, v109, v109
	v_pk_fma_f32 v[106:107], v[106:107], 0.5, v[138:139] op_sel_hi:[1,0,1]
	v_pk_fma_f32 v[104:105], v[104:105], 0.5, v[136:137] op_sel_hi:[1,0,1]
	global_store_dwordx4 v[114:115], v[108:111], off
	v_cvt_pk_bf16_f32 v120, v108, v109
	v_cvt_pk_bf16_f32 v121, v110, v111
	s_nop 1
	v_mov_b32_e32 v240, v120
	v_mov_b32_e32 v241, v121
	v_lshl_add_u64 v[244:245], v[118:119], 0, v[246:247]
	v_fmac_f32_e32 v117, v110, v110
	global_store_dwordx4 v[114:115], v[104:107], off offset:64
	v_or_b32_e32 v108, 32, v112
	v_mov_b32_e32 v109, v113
	v_cvt_pk_bf16_f32 v110, v104, v105
	v_mul_f32_e32 v104, v104, v104
	v_lshl_add_u64 v[108:109], s[4:5], 0, v[108:109]
	v_fmac_f32_e32 v104, v105, v105
	v_pk_fma_f32 v[102:103], v[102:103], 0.5, v[134:135] op_sel_hi:[1,0,1]
	v_pk_fma_f32 v[100:101], v[100:101], 0.5, v[132:133] op_sel_hi:[1,0,1]
	v_fmac_f32_e32 v117, v111, v111
	v_cvt_pk_bf16_f32 v111, v106, v107
	v_mov_b32_e32 v242, v110
	v_mov_b32_e32 v243, v111
	s_nop 1
	v_permlane16_swap_b32 v240, v242
	v_permlane16_swap_b32 v241, v243
	global_store_dwordx4 v[244:245], v[240:243], off
	v_fmac_f32_e32 v104, v106, v106
	global_store_dwordx4 v[114:115], v[100:103], off offset:512
	v_cvt_pk_bf16_f32 v106, v100, v101
	v_fmac_f32_e32 v104, v107, v107
	v_add_f32_e32 v107, v117, v104
	v_mul_f32_e32 v100, v100, v100
	v_fmac_f32_e32 v100, v101, v101
	v_fmac_f32_e32 v100, v102, v102
	v_fmac_f32_e32 v100, v103, v103
	v_add_f32_e32 v107, v107, v100
	v_pk_fma_f32 v[100:101], v[98:99], 0.5, v[130:131] op_sel_hi:[1,0,1]
	v_pk_fma_f32 v[98:99], v[96:97], 0.5, v[128:129] op_sel_hi:[1,0,1]
	v_or_b32_e32 v104, 0x100, v112
	v_mul_f32_e32 v96, v98, v98
	v_fmac_f32_e32 v96, v99, v99
	v_fmac_f32_e32 v96, v100, v100
	v_fmac_f32_e32 v96, v101, v101
	v_add_f32_e32 v96, v107, v96
	ds_bpermute_b32 v97, v192, v96
	v_mov_b32_e32 v105, v113
	v_or_b32_e32 v112, 0x120, v112
	v_lshl_add_u64 v[104:105], s[4:5], 0, v[104:105]
	v_cvt_pk_bf16_f32 v107, v102, v103
	s_waitcnt lgkmcnt(0)
	v_add_f32_e32 v96, v96, v97
	ds_bpermute_b32 v97, v116, v96
	v_lshl_add_u64 v[102:103], s[4:5], 0, v[112:113]
	s_nop 1
	v_mov_b32_e32 v240, v106
	v_mov_b32_e32 v241, v107
	v_lshl_add_u64 v[244:245], v[104:105], 0, v[246:247]
	global_store_dwordx4 v[114:115], v[98:101], off offset:576
	s_nop 1
	v_cvt_pk_bf16_f32 v98, v98, v99
	v_cvt_pk_bf16_f32 v99, v100, v101
	v_mov_b32_e32 v242, v98
	v_mov_b32_e32 v243, v99
	s_nop 1
	v_permlane16_swap_b32 v240, v242
	v_permlane16_swap_b32 v241, v243
	global_store_dwordx4 v[244:245], v[240:243], off
	s_and_saveexec_b64 s[28:29], s[6:7]
	s_cbranch_execz .LBB0_1817
	v_lshlrev_b64 v[98:99], 6, v[168:169]
	v_lshl_add_u64 v[98:99], s[14:15], 0, v[98:99]
	v_lshl_add_u64 v[98:99], s[26:27], 2, v[98:99]
	s_lshl_b32 s18, s53, 2
	v_lshl_add_u64 v[98:99], v[98:99], 0, s[18:19]
	s_waitcnt lgkmcnt(0)
	v_add_f32_e32 v96, v96, v97
	v_mov_b32_e32 v236, v98
	v_mov_b32_e32 v237, v99
	v_mov_b32_e32 v238, v96
.LBB0_1817:
	s_or_b64 exec, exec, s[28:29]
	s_nop 4
	v_permlane16_swap_b32 v236, v232
	v_permlane16_swap_b32 v237, v233
	v_permlane16_swap_b32 v238, v234
	s_mov_b64 s[28:29], exec
	s_mov_b64 exec, 0xffffffff
	global_store_dword v[236:237], v238, off
	s_mov_b64 exec, s[28:29]
	v_or_b32_e32 v114, 32, v164
	v_mov_b32_e32 v115, v165
	s_waitcnt lgkmcnt(0)
	v_lshlrev_b64 v[96:97], 12, v[114:115]
	v_lshl_add_u64 v[96:97], v[166:167], 0, v[96:97]
	global_load_dwordx4 v[118:121], v[96:97], off
	global_load_dwordx4 v[122:125], v[96:97], off offset:64
	global_load_dwordx4 v[126:129], v[96:97], off offset:512
	global_load_dwordx4 v[130:133], v[96:97], off offset:576
	v_or_b32_e32 v112, 48, v164
	v_mov_b32_e32 v113, v165
	v_lshlrev_b64 v[96:97], 12, v[112:113]
	v_lshl_add_u64 v[96:97], v[166:167], 0, v[96:97]
	global_load_dwordx4 v[108:111], v[96:97], off
	global_load_dwordx4 v[104:107], v[96:97], off offset:64
	global_load_dwordx4 v[100:103], v[96:97], off offset:512
	s_nop 0
	global_load_dwordx4 v[96:99], v[96:97], off offset:576
	v_lshlrev_b64 v[134:135], 10, v[114:115]
	v_lshl_add_u64 v[134:135], v[134:135], 0, v[162:163]
	v_lshl_add_u64 v[136:137], v[134:135], 2, s[78:79]
	v_lshlrev_b64 v[134:135], 1, v[134:135]
	v_lshl_add_u64 v[138:139], s[4:5], 0, v[134:135]
	s_waitcnt vmcnt(0)
	v_or_b32_e32 v140, 32, v134
	v_mov_b32_e32 v141, v135
	v_or_b32_e32 v142, 0x100, v134
	v_mov_b32_e32 v143, v135
	v_or_b32_e32 v134, 0x120, v134
	v_lshl_add_u64 v[140:141], s[4:5], 0, v[140:141]
	v_lshl_add_u64 v[142:143], s[4:5], 0, v[142:143]
	s_waitcnt vmcnt(0)
	v_pk_fma_f32 v[92:93], v[92:93], 0.5, v[118:119] op_sel_hi:[1,0,1]
	v_pk_fma_f32 v[88:89], v[88:89], 0.5, v[122:123] op_sel_hi:[1,0,1]
	v_pk_fma_f32 v[84:85], v[84:85], 0.5, v[126:127] op_sel_hi:[1,0,1]
	v_mul_f32_e32 v117, v92, v92
	v_mul_f32_e32 v122, v88, v88
	v_pk_fma_f32 v[94:95], v[94:95], 0.5, v[120:121] op_sel_hi:[1,0,1]
	v_pk_fma_f32 v[90:91], v[90:91], 0.5, v[124:125] op_sel_hi:[1,0,1]
	v_pk_fma_f32 v[118:119], v[80:81], 0.5, v[130:131] op_sel_hi:[1,0,1]
	v_mul_f32_e32 v123, v84, v84
	v_fmac_f32_e32 v117, v93, v93
	v_fmac_f32_e32 v122, v89, v89
	v_pk_fma_f32 v[86:87], v[86:87], 0.5, v[128:129] op_sel_hi:[1,0,1]
	v_mul_f32_e32 v124, v118, v118
	v_fmac_f32_e32 v123, v85, v85
	v_fmac_f32_e32 v117, v94, v94
	v_fmac_f32_e32 v122, v90, v90
	v_pk_fma_f32 v[120:121], v[82:83], 0.5, v[132:133] op_sel_hi:[1,0,1]
	v_cvt_pk_bf16_f32 v80, v92, v93
	v_fmac_f32_e32 v124, v119, v119
	v_fmac_f32_e32 v123, v86, v86
	v_fmac_f32_e32 v117, v95, v95
	v_fmac_f32_e32 v122, v91, v91
	global_store_dwordx4 v[136:137], v[92:95], off
	v_cvt_pk_bf16_f32 v81, v94, v95
	s_nop 1
	v_mov_b32_e32 v240, v80
	v_mov_b32_e32 v241, v81
	v_lshl_add_u64 v[244:245], v[138:139], 0, v[246:247]
	v_fmac_f32_e32 v124, v120, v120
	v_fmac_f32_e32 v123, v87, v87
	v_add_f32_e32 v80, v117, v122
	v_add_f32_e32 v80, v80, v123
	v_fmac_f32_e32 v124, v121, v121
	v_add_f32_e32 v80, v80, v124
	ds_bpermute_b32 v81, v192, v80
	v_cvt_pk_bf16_f32 v82, v88, v89
	v_cvt_pk_bf16_f32 v83, v90, v91
	v_cvt_pk_bf16_f32 v92, v84, v85
	global_store_dwordx4 v[136:137], v[88:91], off offset:64
	v_mov_b32_e32 v242, v82
	v_mov_b32_e32 v243, v83
	s_nop 1
	v_permlane16_swap_b32 v240, v242
	v_permlane16_swap_b32 v241, v243
	global_store_dwordx4 v[244:245], v[240:243], off
	s_waitcnt lgkmcnt(0)
	v_add_f32_e32 v80, v80, v81
	ds_bpermute_b32 v81, v116, v80
	v_cvt_pk_bf16_f32 v93, v86, v87
	v_lshl_add_u64 v[82:83], s[4:5], 0, v[134:135]
	global_store_dwordx4 v[136:137], v[84:87], off offset:512
	s_nop 1
	v_mov_b32_e32 v240, v92
	v_mov_b32_e32 v241, v93
	v_lshl_add_u64 v[244:245], v[142:143], 0, v[246:247]
	global_store_dwordx4 v[136:137], v[118:121], off offset:576
	v_cvt_pk_bf16_f32 v84, v118, v119
	v_cvt_pk_bf16_f32 v85, v120, v121
	v_mov_b32_e32 v242, v84
	v_mov_b32_e32 v243, v85
	s_nop 1
	v_permlane16_swap_b32 v240, v242
	v_permlane16_swap_b32 v241, v243
	global_store_dwordx4 v[244:245], v[240:243], off
	s_and_saveexec_b64 s[28:29], s[6:7]
	s_cbranch_execz .LBB0_1819
	v_lshlrev_b64 v[82:83], 6, v[114:115]
	v_lshl_add_u64 v[82:83], s[14:15], 0, v[82:83]
	v_lshl_add_u64 v[82:83], s[26:27], 2, v[82:83]
	s_lshl_b32 s18, s53, 2
	v_lshl_add_u64 v[82:83], v[82:83], 0, s[18:19]
	s_waitcnt lgkmcnt(0)
	v_add_f32_e32 v80, v80, v81
	v_mov_b32_e32 v232, v82
	v_mov_b32_e32 v233, v83
	v_mov_b32_e32 v234, v80
.LBB0_1819:
	s_or_b64 exec, exec, s[28:29]
	s_waitcnt lgkmcnt(0)
	v_lshlrev_b64 v[80:81], 10, v[112:113]
	v_lshl_add_u64 v[80:81], v[80:81], 0, v[162:163]
	v_lshl_add_u64 v[82:83], v[80:81], 2, s[78:79]
	v_lshlrev_b64 v[80:81], 1, v[80:81]
	v_pk_fma_f32 v[78:79], v[78:79], 0.5, v[110:111] op_sel_hi:[1,0,1]
	v_pk_fma_f32 v[76:77], v[76:77], 0.5, v[108:109] op_sel_hi:[1,0,1]
	v_lshl_add_u64 v[84:85], s[4:5], 0, v[80:81]
	global_store_dwordx4 v[82:83], v[76:79], off
	v_cvt_pk_bf16_f32 v86, v76, v77
	v_cvt_pk_bf16_f32 v87, v78, v79
	s_nop 1
	v_mov_b32_e32 v240, v86
	v_mov_b32_e32 v241, v87
	v_lshl_add_u64 v[244:245], v[84:85], 0, v[246:247]
	v_mul_f32_e32 v84, v76, v76
	v_fmac_f32_e32 v84, v77, v77
	v_pk_fma_f32 v[74:75], v[74:75], 0.5, v[106:107] op_sel_hi:[1,0,1]
	v_pk_fma_f32 v[72:73], v[72:73], 0.5, v[104:105] op_sel_hi:[1,0,1]
	v_fmac_f32_e32 v84, v78, v78
	global_store_dwordx4 v[82:83], v[72:75], off offset:64
	v_or_b32_e32 v76, 32, v80
	v_mov_b32_e32 v77, v81
	v_cvt_pk_bf16_f32 v78, v72, v73
	v_mul_f32_e32 v72, v72, v72
	v_lshl_add_u64 v[76:77], s[4:5], 0, v[76:77]
	v_fmac_f32_e32 v72, v73, v73
	v_pk_fma_f32 v[70:71], v[70:71], 0.5, v[102:103] op_sel_hi:[1,0,1]
	v_pk_fma_f32 v[68:69], v[68:69], 0.5, v[100:101] op_sel_hi:[1,0,1]
	v_fmac_f32_e32 v84, v79, v79
	v_cvt_pk_bf16_f32 v79, v74, v75
	v_mov_b32_e32 v242, v78
	v_mov_b32_e32 v243, v79
	s_nop 1
	v_permlane16_swap_b32 v240, v242
	v_permlane16_swap_b32 v241, v243
	global_store_dwordx4 v[244:245], v[240:243], off
	v_fmac_f32_e32 v72, v74, v74
	global_store_dwordx4 v[82:83], v[68:71], off offset:512
	v_cvt_pk_bf16_f32 v74, v68, v69
	v_fmac_f32_e32 v72, v75, v75
	v_add_f32_e32 v75, v84, v72
	v_mul_f32_e32 v68, v68, v68
	v_fmac_f32_e32 v68, v69, v69
	v_fmac_f32_e32 v68, v70, v70
	v_fmac_f32_e32 v68, v71, v71
	v_add_f32_e32 v75, v75, v68
	v_pk_fma_f32 v[68:69], v[66:67], 0.5, v[98:99] op_sel_hi:[1,0,1]
	v_pk_fma_f32 v[66:67], v[64:65], 0.5, v[96:97] op_sel_hi:[1,0,1]
	v_or_b32_e32 v72, 0x100, v80
	v_mul_f32_e32 v64, v66, v66
	v_fmac_f32_e32 v64, v67, v67
	v_fmac_f32_e32 v64, v68, v68
	v_fmac_f32_e32 v64, v69, v69
	v_add_f32_e32 v64, v75, v64
	ds_bpermute_b32 v65, v192, v64
	v_mov_b32_e32 v73, v81
	v_or_b32_e32 v80, 0x120, v80
	v_lshl_add_u64 v[72:73], s[4:5], 0, v[72:73]
	v_cvt_pk_bf16_f32 v75, v70, v71
	s_waitcnt lgkmcnt(0)
	v_add_f32_e32 v64, v64, v65
	ds_bpermute_b32 v65, v116, v64
	v_lshl_add_u64 v[70:71], s[4:5], 0, v[80:81]
	s_nop 1
	v_mov_b32_e32 v240, v74
	v_mov_b32_e32 v241, v75
	v_lshl_add_u64 v[244:245], v[72:73], 0, v[246:247]
	global_store_dwordx4 v[82:83], v[66:69], off offset:576
	s_nop 1
	v_cvt_pk_bf16_f32 v66, v66, v67
	v_cvt_pk_bf16_f32 v67, v68, v69
	v_mov_b32_e32 v242, v66
	v_mov_b32_e32 v243, v67
	s_nop 1
	v_permlane16_swap_b32 v240, v242
	v_permlane16_swap_b32 v241, v243
	global_store_dwordx4 v[244:245], v[240:243], off
	s_and_saveexec_b64 s[28:29], s[6:7]
	s_cbranch_execz .LBB0_1821
	v_lshlrev_b64 v[66:67], 6, v[112:113]
	v_lshl_add_u64 v[66:67], s[14:15], 0, v[66:67]
	v_lshl_add_u64 v[66:67], s[26:27], 2, v[66:67]
	s_lshl_b32 s18, s53, 2
	v_lshl_add_u64 v[66:67], v[66:67], 0, s[18:19]
	s_waitcnt lgkmcnt(0)
	v_add_f32_e32 v64, v64, v65
	v_mov_b32_e32 v236, v66
	v_mov_b32_e32 v237, v67
	v_mov_b32_e32 v238, v64
.LBB0_1821:
	s_or_b64 exec, exec, s[28:29]
	s_nop 4
	v_permlane16_swap_b32 v236, v232
	v_permlane16_swap_b32 v237, v233
	v_permlane16_swap_b32 v238, v234
	s_mov_b64 s[28:29], exec
	s_mov_b64 exec, 0xffffffff
	global_store_dword v[236:237], v238, off
	s_mov_b64 exec, s[28:29]
	v_lshl_add_u64 v[82:83], v[164:165], 0, s[16:17]
	s_waitcnt lgkmcnt(0)
	v_lshlrev_b64 v[64:65], 12, v[82:83]
	v_lshl_add_u64 v[64:65], v[166:167], 0, v[64:65]
	global_load_dwordx4 v[84:87], v[64:65], off
	global_load_dwordx4 v[88:91], v[64:65], off offset:64
	global_load_dwordx4 v[92:95], v[64:65], off offset:512
	global_load_dwordx4 v[96:99], v[64:65], off offset:576
	v_lshl_add_u64 v[80:81], v[164:165], 0, s[20:21]
	v_lshlrev_b64 v[64:65], 12, v[80:81]
	v_lshl_add_u64 v[64:65], v[166:167], 0, v[64:65]
	global_load_dwordx4 v[76:79], v[64:65], off
	global_load_dwordx4 v[72:75], v[64:65], off offset:64
	global_load_dwordx4 v[68:71], v[64:65], off offset:512
	s_nop 0
	global_load_dwordx4 v[64:67], v[64:65], off offset:576
	v_lshlrev_b64 v[100:101], 10, v[82:83]
	v_lshl_add_u64 v[100:101], v[100:101], 0, v[162:163]
	v_lshl_add_u64 v[102:103], v[100:101], 2, s[78:79]
	v_lshlrev_b64 v[100:101], 1, v[100:101]
	v_lshl_add_u64 v[104:105], s[4:5], 0, v[100:101]
	s_waitcnt vmcnt(0)
	v_or_b32_e32 v106, 32, v100
	v_mov_b32_e32 v107, v101
	v_or_b32_e32 v108, 0x100, v100
	v_mov_b32_e32 v109, v101
	v_or_b32_e32 v100, 0x120, v100
	v_lshl_add_u64 v[106:107], s[4:5], 0, v[106:107]
	v_lshl_add_u64 v[108:109], s[4:5], 0, v[108:109]
	s_waitcnt vmcnt(0)
	v_pk_fma_f32 v[60:61], v[60:61], 0.5, v[84:85] op_sel_hi:[1,0,1]
	v_pk_fma_f32 v[56:57], v[56:57], 0.5, v[88:89] op_sel_hi:[1,0,1]
	v_pk_fma_f32 v[52:53], v[52:53], 0.5, v[92:93] op_sel_hi:[1,0,1]
	v_mul_f32_e32 v88, v60, v60
	v_mul_f32_e32 v89, v56, v56
	v_pk_fma_f32 v[62:63], v[62:63], 0.5, v[86:87] op_sel_hi:[1,0,1]
	v_pk_fma_f32 v[58:59], v[58:59], 0.5, v[90:91] op_sel_hi:[1,0,1]
	v_pk_fma_f32 v[84:85], v[48:49], 0.5, v[96:97] op_sel_hi:[1,0,1]
	v_mul_f32_e32 v90, v52, v52
	v_fmac_f32_e32 v88, v61, v61
	v_fmac_f32_e32 v89, v57, v57
	v_pk_fma_f32 v[54:55], v[54:55], 0.5, v[94:95] op_sel_hi:[1,0,1]
	v_mul_f32_e32 v91, v84, v84
	v_fmac_f32_e32 v90, v53, v53
	v_fmac_f32_e32 v88, v62, v62
	v_fmac_f32_e32 v89, v58, v58
	v_pk_fma_f32 v[86:87], v[50:51], 0.5, v[98:99] op_sel_hi:[1,0,1]
	v_cvt_pk_bf16_f32 v48, v60, v61
	v_fmac_f32_e32 v91, v85, v85
	v_fmac_f32_e32 v90, v54, v54
	v_fmac_f32_e32 v88, v63, v63
	v_fmac_f32_e32 v89, v59, v59
	global_store_dwordx4 v[102:103], v[60:63], off
	v_cvt_pk_bf16_f32 v49, v62, v63
	s_nop 1
	v_mov_b32_e32 v240, v48
	v_mov_b32_e32 v241, v49
	v_lshl_add_u64 v[244:245], v[104:105], 0, v[246:247]
	v_fmac_f32_e32 v91, v86, v86
	v_fmac_f32_e32 v90, v55, v55
	v_add_f32_e32 v48, v88, v89
	v_add_f32_e32 v48, v48, v90
	v_fmac_f32_e32 v91, v87, v87
	v_add_f32_e32 v48, v48, v91
	ds_bpermute_b32 v49, v192, v48
	v_cvt_pk_bf16_f32 v50, v56, v57
	v_cvt_pk_bf16_f32 v51, v58, v59
	v_cvt_pk_bf16_f32 v60, v52, v53
	global_store_dwordx4 v[102:103], v[56:59], off offset:64
	v_mov_b32_e32 v242, v50
	v_mov_b32_e32 v243, v51
	s_nop 1
	v_permlane16_swap_b32 v240, v242
	v_permlane16_swap_b32 v241, v243
	global_store_dwordx4 v[244:245], v[240:243], off
	s_waitcnt lgkmcnt(0)
	v_add_f32_e32 v48, v48, v49
	ds_bpermute_b32 v49, v116, v48
	v_cvt_pk_bf16_f32 v61, v54, v55
	v_lshl_add_u64 v[50:51], s[4:5], 0, v[100:101]
	global_store_dwordx4 v[102:103], v[52:55], off offset:512
	s_nop 1
	v_mov_b32_e32 v240, v60
	v_mov_b32_e32 v241, v61
	v_lshl_add_u64 v[244:245], v[108:109], 0, v[246:247]
	global_store_dwordx4 v[102:103], v[84:87], off offset:576
	v_cvt_pk_bf16_f32 v52, v84, v85
	v_cvt_pk_bf16_f32 v53, v86, v87
	v_mov_b32_e32 v242, v52
	v_mov_b32_e32 v243, v53
	s_nop 1
	v_permlane16_swap_b32 v240, v242
	v_permlane16_swap_b32 v241, v243
	global_store_dwordx4 v[244:245], v[240:243], off
	s_and_saveexec_b64 s[28:29], s[6:7]
	s_cbranch_execz .LBB0_1823
	v_lshlrev_b64 v[50:51], 6, v[82:83]
	v_lshl_add_u64 v[50:51], s[14:15], 0, v[50:51]
	v_lshl_add_u64 v[50:51], s[26:27], 2, v[50:51]
	s_lshl_b32 s18, s53, 2
	v_lshl_add_u64 v[50:51], v[50:51], 0, s[18:19]
	s_waitcnt lgkmcnt(0)
	v_add_f32_e32 v48, v48, v49
	v_mov_b32_e32 v232, v50
	v_mov_b32_e32 v233, v51
	v_mov_b32_e32 v234, v48
.LBB0_1823:
	s_or_b64 exec, exec, s[28:29]
	s_waitcnt lgkmcnt(0)
	v_lshlrev_b64 v[48:49], 10, v[80:81]
	v_lshl_add_u64 v[48:49], v[48:49], 0, v[162:163]
	v_lshl_add_u64 v[50:51], v[48:49], 2, s[78:79]
	v_lshlrev_b64 v[48:49], 1, v[48:49]
	v_pk_fma_f32 v[46:47], v[46:47], 0.5, v[78:79] op_sel_hi:[1,0,1]
	v_pk_fma_f32 v[44:45], v[44:45], 0.5, v[76:77] op_sel_hi:[1,0,1]
	v_lshl_add_u64 v[52:53], s[4:5], 0, v[48:49]
	global_store_dwordx4 v[50:51], v[44:47], off
	v_cvt_pk_bf16_f32 v54, v44, v45
	v_cvt_pk_bf16_f32 v55, v46, v47
	s_nop 1
	v_mov_b32_e32 v240, v54
	v_mov_b32_e32 v241, v55
	v_lshl_add_u64 v[244:245], v[52:53], 0, v[246:247]
	v_mul_f32_e32 v52, v44, v44
	v_fmac_f32_e32 v52, v45, v45
	v_pk_fma_f32 v[42:43], v[42:43], 0.5, v[74:75] op_sel_hi:[1,0,1]
	v_pk_fma_f32 v[40:41], v[40:41], 0.5, v[72:73] op_sel_hi:[1,0,1]
	v_fmac_f32_e32 v52, v46, v46
	global_store_dwordx4 v[50:51], v[40:43], off offset:64
	v_or_b32_e32 v44, 32, v48
	v_mov_b32_e32 v45, v49
	v_cvt_pk_bf16_f32 v46, v40, v41
	v_mul_f32_e32 v40, v40, v40
	v_lshl_add_u64 v[44:45], s[4:5], 0, v[44:45]
	v_fmac_f32_e32 v40, v41, v41
	v_pk_fma_f32 v[38:39], v[38:39], 0.5, v[70:71] op_sel_hi:[1,0,1]
	v_pk_fma_f32 v[36:37], v[36:37], 0.5, v[68:69] op_sel_hi:[1,0,1]
	v_fmac_f32_e32 v52, v47, v47
	v_cvt_pk_bf16_f32 v47, v42, v43
	v_mov_b32_e32 v242, v46
	v_mov_b32_e32 v243, v47
	s_nop 1
	v_permlane16_swap_b32 v240, v242
	v_permlane16_swap_b32 v241, v243
	global_store_dwordx4 v[244:245], v[240:243], off
	v_fmac_f32_e32 v40, v42, v42
	global_store_dwordx4 v[50:51], v[36:39], off offset:512
	v_cvt_pk_bf16_f32 v42, v36, v37
	v_fmac_f32_e32 v40, v43, v43
	v_add_f32_e32 v43, v52, v40
	v_mul_f32_e32 v36, v36, v36
	v_fmac_f32_e32 v36, v37, v37
	v_fmac_f32_e32 v36, v38, v38
	v_fmac_f32_e32 v36, v39, v39
	v_add_f32_e32 v43, v43, v36
	v_pk_fma_f32 v[36:37], v[34:35], 0.5, v[66:67] op_sel_hi:[1,0,1]
	v_pk_fma_f32 v[34:35], v[32:33], 0.5, v[64:65] op_sel_hi:[1,0,1]
	v_or_b32_e32 v40, 0x100, v48
	v_mul_f32_e32 v32, v34, v34
	v_fmac_f32_e32 v32, v35, v35
	v_fmac_f32_e32 v32, v36, v36
	v_fmac_f32_e32 v32, v37, v37
	v_add_f32_e32 v32, v43, v32
	ds_bpermute_b32 v33, v192, v32
	v_mov_b32_e32 v41, v49
	v_or_b32_e32 v48, 0x120, v48
	v_lshl_add_u64 v[40:41], s[4:5], 0, v[40:41]
	v_cvt_pk_bf16_f32 v43, v38, v39
	s_waitcnt lgkmcnt(0)
	v_add_f32_e32 v32, v32, v33
	ds_bpermute_b32 v33, v116, v32
	v_lshl_add_u64 v[38:39], s[4:5], 0, v[48:49]
	s_nop 1
	v_mov_b32_e32 v240, v42
	v_mov_b32_e32 v241, v43
	v_lshl_add_u64 v[244:245], v[40:41], 0, v[246:247]
	global_store_dwordx4 v[50:51], v[34:37], off offset:576
	s_nop 1
	v_cvt_pk_bf16_f32 v34, v34, v35
	v_cvt_pk_bf16_f32 v35, v36, v37
	v_mov_b32_e32 v242, v34
	v_mov_b32_e32 v243, v35
	s_nop 1
	v_permlane16_swap_b32 v240, v242
	v_permlane16_swap_b32 v241, v243
	global_store_dwordx4 v[244:245], v[240:243], off
	s_and_saveexec_b64 s[28:29], s[6:7]
	s_cbranch_execz .LBB0_1825
	v_lshlrev_b64 v[34:35], 6, v[80:81]
	v_lshl_add_u64 v[34:35], s[14:15], 0, v[34:35]
	v_lshl_add_u64 v[34:35], s[26:27], 2, v[34:35]
	s_lshl_b32 s18, s53, 2
	v_lshl_add_u64 v[34:35], v[34:35], 0, s[18:19]
	s_waitcnt lgkmcnt(0)
	v_add_f32_e32 v32, v32, v33
	v_mov_b32_e32 v236, v34
	v_mov_b32_e32 v237, v35
	v_mov_b32_e32 v238, v32
.LBB0_1825:
	s_or_b64 exec, exec, s[28:29]
	s_nop 4
	v_permlane16_swap_b32 v236, v232
	v_permlane16_swap_b32 v237, v233
	v_permlane16_swap_b32 v238, v234
	s_mov_b64 s[28:29], exec
	s_mov_b64 exec, 0xffffffff
	global_store_dword v[236:237], v238, off
	s_mov_b64 exec, s[28:29]
	v_lshl_add_u64 v[50:51], v[164:165], 0, s[22:23]
	s_waitcnt lgkmcnt(0)
	v_lshlrev_b64 v[32:33], 12, v[50:51]
	v_lshl_add_u64 v[32:33], v[166:167], 0, v[32:33]
	global_load_dwordx4 v[52:55], v[32:33], off
	global_load_dwordx4 v[56:59], v[32:33], off offset:64
	global_load_dwordx4 v[60:63], v[32:33], off offset:512
	global_load_dwordx4 v[64:67], v[32:33], off offset:576
	v_lshl_add_u64 v[48:49], v[164:165], 0, s[24:25]
	v_lshlrev_b64 v[32:33], 12, v[48:49]
	v_lshl_add_u64 v[32:33], v[166:167], 0, v[32:33]
	global_load_dwordx4 v[44:47], v[32:33], off
	global_load_dwordx4 v[40:43], v[32:33], off offset:64
	global_load_dwordx4 v[36:39], v[32:33], off offset:512
	s_nop 0
	global_load_dwordx4 v[32:35], v[32:33], off offset:576
	v_lshlrev_b64 v[68:69], 10, v[50:51]
	v_lshl_add_u64 v[68:69], v[68:69], 0, v[162:163]
	v_lshl_add_u64 v[70:71], v[68:69], 2, s[78:79]
	v_lshlrev_b64 v[68:69], 1, v[68:69]
	v_lshl_add_u64 v[72:73], s[4:5], 0, v[68:69]
	s_waitcnt vmcnt(0)
	v_or_b32_e32 v74, 32, v68
	v_mov_b32_e32 v75, v69
	v_or_b32_e32 v76, 0x100, v68
	v_mov_b32_e32 v77, v69
	v_or_b32_e32 v68, 0x120, v68
	v_lshl_add_u64 v[74:75], s[4:5], 0, v[74:75]
	v_lshl_add_u64 v[76:77], s[4:5], 0, v[76:77]
	s_waitcnt vmcnt(0)
	v_pk_fma_f32 v[28:29], v[28:29], 0.5, v[52:53] op_sel_hi:[1,0,1]
	v_pk_fma_f32 v[24:25], v[24:25], 0.5, v[56:57] op_sel_hi:[1,0,1]
	v_pk_fma_f32 v[20:21], v[20:21], 0.5, v[60:61] op_sel_hi:[1,0,1]
	v_mul_f32_e32 v56, v28, v28
	v_mul_f32_e32 v57, v24, v24
	v_pk_fma_f32 v[30:31], v[30:31], 0.5, v[54:55] op_sel_hi:[1,0,1]
	v_pk_fma_f32 v[26:27], v[26:27], 0.5, v[58:59] op_sel_hi:[1,0,1]
	v_pk_fma_f32 v[52:53], v[16:17], 0.5, v[64:65] op_sel_hi:[1,0,1]
	v_mul_f32_e32 v58, v20, v20
	v_fmac_f32_e32 v56, v29, v29
	v_fmac_f32_e32 v57, v25, v25
	v_pk_fma_f32 v[22:23], v[22:23], 0.5, v[62:63] op_sel_hi:[1,0,1]
	v_mul_f32_e32 v59, v52, v52
	v_fmac_f32_e32 v58, v21, v21
	v_fmac_f32_e32 v56, v30, v30
	v_fmac_f32_e32 v57, v26, v26
	v_pk_fma_f32 v[54:55], v[18:19], 0.5, v[66:67] op_sel_hi:[1,0,1]
	v_cvt_pk_bf16_f32 v16, v28, v29
	v_fmac_f32_e32 v59, v53, v53
	v_fmac_f32_e32 v58, v22, v22
	v_fmac_f32_e32 v56, v31, v31
	v_fmac_f32_e32 v57, v27, v27
	global_store_dwordx4 v[70:71], v[28:31], off
	v_cvt_pk_bf16_f32 v17, v30, v31
	s_nop 1
	v_mov_b32_e32 v240, v16
	v_mov_b32_e32 v241, v17
	v_lshl_add_u64 v[244:245], v[72:73], 0, v[246:247]
	v_fmac_f32_e32 v59, v54, v54
	v_fmac_f32_e32 v58, v23, v23
	v_add_f32_e32 v16, v56, v57
	v_add_f32_e32 v16, v16, v58
	v_fmac_f32_e32 v59, v55, v55
	v_add_f32_e32 v16, v16, v59
	ds_bpermute_b32 v17, v192, v16
	v_cvt_pk_bf16_f32 v18, v24, v25
	v_cvt_pk_bf16_f32 v19, v26, v27
	v_cvt_pk_bf16_f32 v28, v20, v21
	global_store_dwordx4 v[70:71], v[24:27], off offset:64
	v_mov_b32_e32 v242, v18
	v_mov_b32_e32 v243, v19
	s_nop 1
	v_permlane16_swap_b32 v240, v242
	v_permlane16_swap_b32 v241, v243
	global_store_dwordx4 v[244:245], v[240:243], off
	s_waitcnt lgkmcnt(0)
	v_add_f32_e32 v16, v16, v17
	ds_bpermute_b32 v17, v116, v16
	v_cvt_pk_bf16_f32 v29, v22, v23
	v_lshl_add_u64 v[18:19], s[4:5], 0, v[68:69]
	global_store_dwordx4 v[70:71], v[20:23], off offset:512
	s_nop 1
	v_mov_b32_e32 v240, v28
	v_mov_b32_e32 v241, v29
	v_lshl_add_u64 v[244:245], v[76:77], 0, v[246:247]
	global_store_dwordx4 v[70:71], v[52:55], off offset:576
	v_cvt_pk_bf16_f32 v20, v52, v53
	v_cvt_pk_bf16_f32 v21, v54, v55
	v_mov_b32_e32 v242, v20
	v_mov_b32_e32 v243, v21
	s_nop 1
	v_permlane16_swap_b32 v240, v242
	v_permlane16_swap_b32 v241, v243
	global_store_dwordx4 v[244:245], v[240:243], off
	s_and_saveexec_b64 s[28:29], s[6:7]
	s_cbranch_execz .LBB0_1827
	v_lshlrev_b64 v[18:19], 6, v[50:51]
	v_lshl_add_u64 v[18:19], s[14:15], 0, v[18:19]
	v_lshl_add_u64 v[18:19], s[26:27], 2, v[18:19]
	s_lshl_b32 s18, s53, 2
	v_lshl_add_u64 v[18:19], v[18:19], 0, s[18:19]
	s_waitcnt lgkmcnt(0)
	v_add_f32_e32 v16, v16, v17
	flat_store_dword v[18:19], v16

.LBB0_2164:
	ds_read_b128 v[128:131], v170
	ds_read_b128 v[132:135], v171
	ds_read_b128 v[136:139], v172
	ds_read_b128 v[140:143], v173
	s_add_u32 s34, s30, 0xfffc0080
	s_addc_u32 s35, s31, -1
	s_cmp_eq_u32 s67, 12
	s_cselect_b32 s37, s23, s35
	s_cselect_b32 s36, s29, s34
	s_cselect_b32 s35, s21, s66
	s_cselect_b32 s34, s64, s65
	s_mov_b32 m0, s61
	v_lshl_add_u64 v[212:213], s[30:31], 0, v[156:157]
	ds_read_b128 v[162:165], v151
	ds_read_b128 v[166:169], v151 offset:1024
	ds_read_b128 v[188:191], v151 offset:2048
	ds_read_b128 v[192:195], v151 offset:3072
	ds_read_b128 v[196:199], v151 offset:4096
	ds_read_b128 v[200:203], v151 offset:5120
	ds_read_b128 v[204:207], v151 offset:6144
	ds_read_b128 v[208:211], v151 offset:7168
	global_load_lds_dwordx4 v[212:213], off
	v_lshl_add_u64 v[212:213], s[30:31], 0, v[154:155]
	s_mov_b32 m0, s62
	s_nop 0
	global_load_lds_dwordx4 v[212:213], off
	s_waitcnt lgkmcnt(8)
	s_barrier
	s_waitcnt lgkmcnt(0)
	s_setprio 1
	s_waitcnt lgkmcnt(0)
	v_mfma_f32_16x16x32_bf16 v[124:127], v[128:131], v[162:165], v[124:127]
	v_mfma_f32_16x16x32_bf16 v[120:123], v[136:139], v[162:165], v[120:123]
	v_mfma_f32_16x16x32_bf16 v[108:111], v[128:131], v[188:191], v[108:111]
	v_mfma_f32_16x16x32_bf16 v[104:107], v[136:139], v[188:191], v[104:107]
	v_mfma_f32_16x16x32_bf16 v[92:95], v[128:131], v[196:199], v[92:95]
	v_mfma_f32_16x16x32_bf16 v[88:91], v[136:139], v[196:199], v[88:91]
	v_mfma_f32_16x16x32_bf16 v[76:79], v[128:131], v[204:207], v[76:79]
	v_mfma_f32_16x16x32_bf16 v[72:75], v[136:139], v[204:207], v[72:75]
	v_mfma_f32_16x16x32_bf16 v[124:127], v[132:135], v[166:169], v[124:127]
	v_mfma_f32_16x16x32_bf16 v[120:123], v[140:143], v[166:169], v[120:123]
	v_mfma_f32_16x16x32_bf16 v[108:111], v[132:135], v[192:195], v[108:111]
	v_mfma_f32_16x16x32_bf16 v[104:107], v[140:143], v[192:195], v[104:107]
	v_mfma_f32_16x16x32_bf16 v[92:95], v[132:135], v[200:203], v[92:95]
	v_mfma_f32_16x16x32_bf16 v[88:91], v[140:143], v[200:203], v[88:91]
	v_mfma_f32_16x16x32_bf16 v[76:79], v[132:135], v[208:211], v[76:79]
	v_mfma_f32_16x16x32_bf16 v[72:75], v[140:143], v[208:211], v[72:75]
	s_setprio 0
	s_barrier
	s_mov_b32 m0, s46
	v_lshl_add_u64 v[228:229], s[34:35], 0, v[144:145]
	ds_read_b128 v[212:215], v174
	ds_read_b128 v[216:219], v175
	ds_read_b128 v[220:223], v177
	ds_read_b128 v[224:227], v178
	global_load_lds_dwordx4 v[228:229], off
	v_lshl_add_u64 v[230:231], s[34:35], 0, v[146:147]
	s_mov_b32 m0, s47
	s_nop 0
	global_load_lds_dwordx4 v[230:231], off
	s_barrier
	s_waitcnt lgkmcnt(0)
	s_setprio 1
	s_waitcnt lgkmcnt(0)
	v_mfma_f32_16x16x32_bf16 v[116:119], v[212:215], v[162:165], v[116:119]
	v_mfma_f32_16x16x32_bf16 v[112:115], v[220:223], v[162:165], v[112:115]
	v_mfma_f32_16x16x32_bf16 v[100:103], v[212:215], v[188:191], v[100:103]
	v_mfma_f32_16x16x32_bf16 v[96:99], v[220:223], v[188:191], v[96:99]
	v_mfma_f32_16x16x32_bf16 v[84:87], v[212:215], v[196:199], v[84:87]
	v_mfma_f32_16x16x32_bf16 v[80:83], v[220:223], v[196:199], v[80:83]
	v_mfma_f32_16x16x32_bf16 v[68:71], v[212:215], v[204:207], v[68:71]
	v_mfma_f32_16x16x32_bf16 v[64:67], v[220:223], v[204:207], v[64:67]
	v_mfma_f32_16x16x32_bf16 v[116:119], v[216:219], v[166:169], v[116:119]
	v_mfma_f32_16x16x32_bf16 v[112:115], v[224:227], v[166:169], v[112:115]
	v_mfma_f32_16x16x32_bf16 v[100:103], v[216:219], v[192:195], v[100:103]
	v_mfma_f32_16x16x32_bf16 v[96:99], v[224:227], v[192:195], v[96:99]
	v_mfma_f32_16x16x32_bf16 v[84:87], v[216:219], v[200:203], v[84:87]
	v_mfma_f32_16x16x32_bf16 v[80:83], v[224:227], v[200:203], v[80:83]
	v_mfma_f32_16x16x32_bf16 v[68:71], v[216:219], v[208:211], v[68:71]
	v_mfma_f32_16x16x32_bf16 v[64:67], v[224:227], v[208:211], v[64:67]
	s_setprio 0
	s_mov_b32 m0, s45
	v_lshl_add_u64 v[232:233], s[36:37], 0, v[144:145]
	s_barrier
	ds_read_b128 v[162:165], v151 offset:16384
	ds_read_b128 v[166:169], v151 offset:17408
	ds_read_b128 v[188:191], v151 offset:18432
	ds_read_b128 v[192:195], v151 offset:19456
	ds_read_b128 v[196:199], v151 offset:20480
	ds_read_b128 v[200:203], v151 offset:21504
	ds_read_b128 v[204:207], v151 offset:22528
	ds_read_b128 v[208:211], v151 offset:23552
	global_load_lds_dwordx4 v[232:233], off
	v_lshl_add_u64 v[234:235], s[36:37], 0, v[146:147]
	s_mov_b32 m0, s48
	s_nop 0
	global_load_lds_dwordx4 v[234:235], off
	s_barrier
	s_waitcnt lgkmcnt(0)
	s_setprio 1
	s_waitcnt lgkmcnt(0)
	v_mfma_f32_16x16x32_bf16 v[60:63], v[128:131], v[162:165], v[60:63]
	v_mfma_f32_16x16x32_bf16 v[56:59], v[136:139], v[162:165], v[56:59]
	v_mfma_f32_16x16x32_bf16 v[44:47], v[128:131], v[188:191], v[44:47]
	v_mfma_f32_16x16x32_bf16 v[40:43], v[136:139], v[188:191], v[40:43]
	v_mfma_f32_16x16x32_bf16 v[28:31], v[128:131], v[196:199], v[28:31]
	v_mfma_f32_16x16x32_bf16 v[24:27], v[136:139], v[196:199], v[24:27]
	v_mfma_f32_16x16x32_bf16 v[12:15], v[128:131], v[204:207], v[12:15]
	v_mfma_f32_16x16x32_bf16 v[8:11], v[136:139], v[204:207], v[8:11]
	v_mfma_f32_16x16x32_bf16 v[60:63], v[132:135], v[166:169], v[60:63]
	v_mfma_f32_16x16x32_bf16 v[56:59], v[140:143], v[166:169], v[56:59]
	v_mfma_f32_16x16x32_bf16 v[44:47], v[132:135], v[192:195], v[44:47]
	v_mfma_f32_16x16x32_bf16 v[40:43], v[140:143], v[192:195], v[40:43]
	v_mfma_f32_16x16x32_bf16 v[28:31], v[132:135], v[200:203], v[28:31]
	v_mfma_f32_16x16x32_bf16 v[24:27], v[140:143], v[200:203], v[24:27]
	v_mfma_f32_16x16x32_bf16 v[12:15], v[132:135], v[208:211], v[12:15]
	v_mfma_f32_16x16x32_bf16 v[8:11], v[140:143], v[208:211], v[8:11]
	s_setprio 0
	s_barrier
	s_add_u32 s68, s34, 0x40000
	s_addc_u32 s69, s35, 0
	s_mov_b32 m0, s49
	v_lshl_add_u64 v[128:129], s[68:69], 0, v[144:145]
	global_load_lds_dwordx4 v[128:129], off
	v_lshl_add_u64 v[128:129], s[68:69], 0, v[146:147]
	s_mov_b32 m0, s50
	s_nop 0
	global_load_lds_dwordx4 v[128:129], off
	s_waitcnt vmcnt(6)
	s_barrier
	s_setprio 1
	v_mfma_f32_16x16x32_bf16 v[52:55], v[212:215], v[162:165], v[52:55]
	v_mfma_f32_16x16x32_bf16 v[48:51], v[220:223], v[162:165], v[48:51]
	v_mfma_f32_16x16x32_bf16 v[36:39], v[212:215], v[188:191], v[36:39]
	v_mfma_f32_16x16x32_bf16 v[32:35], v[220:223], v[188:191], v[32:35]
	v_mfma_f32_16x16x32_bf16 v[20:23], v[212:215], v[196:199], v[20:23]
	v_mfma_f32_16x16x32_bf16 v[16:19], v[220:223], v[196:199], v[16:19]
	v_mfma_f32_16x16x32_bf16 v[4:7], v[212:215], v[204:207], v[4:7]
	v_mfma_f32_16x16x32_bf16 v[0:3], v[220:223], v[204:207], v[0:3]
	v_mfma_f32_16x16x32_bf16 v[52:55], v[216:219], v[166:169], v[52:55]
	v_mfma_f32_16x16x32_bf16 v[48:51], v[224:227], v[166:169], v[48:51]
	v_mfma_f32_16x16x32_bf16 v[36:39], v[216:219], v[192:195], v[36:39]
	v_mfma_f32_16x16x32_bf16 v[32:35], v[224:227], v[192:195], v[32:35]
	v_mfma_f32_16x16x32_bf16 v[20:23], v[216:219], v[200:203], v[20:23]
	v_mfma_f32_16x16x32_bf16 v[16:19], v[224:227], v[200:203], v[16:19]
	v_mfma_f32_16x16x32_bf16 v[4:7], v[216:219], v[208:211], v[4:7]
	v_mfma_f32_16x16x32_bf16 v[0:3], v[224:227], v[208:211], v[0:3]
	s_setprio 0
	s_barrier
	ds_read_b128 v[128:131], v179
	ds_read_b128 v[132:135], v180
	ds_read_b128 v[136:139], v181
	ds_read_b128 v[140:143], v182
	s_add_u32 s36, s36, 0x40000
	s_addc_u32 s37, s37, 0
	s_mov_b32 m0, s51
	v_lshl_add_u64 v[212:213], s[36:37], 0, v[144:145]
	ds_read_b128 v[162:165], v151 offset:32768
	ds_read_b128 v[166:169], v151 offset:33792
	ds_read_b128 v[188:191], v151 offset:34816
	ds_read_b128 v[192:195], v151 offset:35840
	ds_read_b128 v[196:199], v151 offset:36864
	ds_read_b128 v[200:203], v151 offset:37888
	ds_read_b128 v[204:207], v151 offset:38912
	ds_read_b128 v[208:211], v151 offset:39936
	global_load_lds_dwordx4 v[212:213], off
	v_lshl_add_u64 v[212:213], s[36:37], 0, v[146:147]
	s_mov_b32 m0, s52
	s_nop 0
	global_load_lds_dwordx4 v[212:213], off
	s_waitcnt lgkmcnt(8)
	s_barrier
	s_waitcnt lgkmcnt(0)
	s_setprio 1
	s_waitcnt lgkmcnt(0)
	v_mfma_f32_16x16x32_bf16 v[124:127], v[128:131], v[162:165], v[124:127]
	v_mfma_f32_16x16x32_bf16 v[120:123], v[136:139], v[162:165], v[120:123]
	v_mfma_f32_16x16x32_bf16 v[108:111], v[128:131], v[188:191], v[108:111]
	v_mfma_f32_16x16x32_bf16 v[104:107], v[136:139], v[188:191], v[104:107]
	v_mfma_f32_16x16x32_bf16 v[92:95], v[128:131], v[196:199], v[92:95]
	v_mfma_f32_16x16x32_bf16 v[88:91], v[136:139], v[196:199], v[88:91]
	v_mfma_f32_16x16x32_bf16 v[76:79], v[128:131], v[204:207], v[76:79]
	v_mfma_f32_16x16x32_bf16 v[72:75], v[136:139], v[204:207], v[72:75]
	v_mfma_f32_16x16x32_bf16 v[124:127], v[132:135], v[166:169], v[124:127]
	v_mfma_f32_16x16x32_bf16 v[120:123], v[140:143], v[166:169], v[120:123]
	v_mfma_f32_16x16x32_bf16 v[108:111], v[132:135], v[192:195], v[108:111]
	v_mfma_f32_16x16x32_bf16 v[104:107], v[140:143], v[192:195], v[104:107]
	v_mfma_f32_16x16x32_bf16 v[92:95], v[132:135], v[200:203], v[92:95]
	v_mfma_f32_16x16x32_bf16 v[88:91], v[140:143], v[200:203], v[88:91]
	v_mfma_f32_16x16x32_bf16 v[76:79], v[132:135], v[208:211], v[76:79]
	v_mfma_f32_16x16x32_bf16 v[72:75], v[140:143], v[208:211], v[72:75]
	s_setprio 0
	s_barrier
	s_mov_b32 m0, s54
	v_lshl_add_u64 v[228:229], v[228:229], 0, s[10:11]
	ds_read_b128 v[212:215], v183
	ds_read_b128 v[216:219], v184
	ds_read_b128 v[220:223], v185
	ds_read_b128 v[224:227], v186
	global_load_lds_dwordx4 v[228:229], off
	v_lshl_add_u64 v[228:229], v[230:231], 0, s[10:11]
	s_mov_b32 m0, s55
	s_nop 0
	global_load_lds_dwordx4 v[228:229], off
	s_barrier
	s_waitcnt lgkmcnt(0)
	s_setprio 1
	s_waitcnt lgkmcnt(0)
	v_mfma_f32_16x16x32_bf16 v[116:119], v[212:215], v[162:165], v[116:119]
	v_mfma_f32_16x16x32_bf16 v[112:115], v[220:223], v[162:165], v[112:115]
	v_mfma_f32_16x16x32_bf16 v[100:103], v[212:215], v[188:191], v[100:103]
	v_mfma_f32_16x16x32_bf16 v[96:99], v[220:223], v[188:191], v[96:99]
	v_mfma_f32_16x16x32_bf16 v[84:87], v[212:215], v[196:199], v[84:87]
	v_mfma_f32_16x16x32_bf16 v[80:83], v[220:223], v[196:199], v[80:83]
	v_mfma_f32_16x16x32_bf16 v[68:71], v[212:215], v[204:207], v[68:71]
	v_mfma_f32_16x16x32_bf16 v[64:67], v[220:223], v[204:207], v[64:67]
	v_mfma_f32_16x16x32_bf16 v[116:119], v[216:219], v[166:169], v[116:119]
	v_mfma_f32_16x16x32_bf16 v[112:115], v[224:227], v[166:169], v[112:115]
	v_mfma_f32_16x16x32_bf16 v[100:103], v[216:219], v[192:195], v[100:103]
	v_mfma_f32_16x16x32_bf16 v[96:99], v[224:227], v[192:195], v[96:99]
	v_mfma_f32_16x16x32_bf16 v[84:87], v[216:219], v[200:203], v[84:87]
	v_mfma_f32_16x16x32_bf16 v[80:83], v[224:227], v[200:203], v[80:83]
	v_mfma_f32_16x16x32_bf16 v[68:71], v[216:219], v[208:211], v[68:71]
	v_mfma_f32_16x16x32_bf16 v[64:67], v[224:227], v[208:211], v[64:67]
	s_setprio 0
	s_mov_b32 m0, s56
	v_lshl_add_u64 v[228:229], v[232:233], 0, s[10:11]
	s_barrier
	ds_read_b128 v[162:165], v151 offset:49152
	ds_read_b128 v[166:169], v151 offset:50176
	ds_read_b128 v[188:191], v151 offset:51200
	ds_read_b128 v[192:195], v151 offset:52224
	ds_read_b128 v[196:199], v151 offset:53248
	ds_read_b128 v[200:203], v151 offset:54272
	ds_read_b128 v[204:207], v151 offset:55296
	ds_read_b128 v[208:211], v151 offset:56320
	global_load_lds_dwordx4 v[228:229], off
	v_lshl_add_u64 v[228:229], v[234:235], 0, s[10:11]
	s_mov_b32 m0, s57
	s_nop 0
	global_load_lds_dwordx4 v[228:229], off
	s_barrier
	s_waitcnt lgkmcnt(0)
	s_setprio 1
	s_waitcnt lgkmcnt(0)
	v_mfma_f32_16x16x32_bf16 v[60:63], v[128:131], v[162:165], v[60:63]
	v_mfma_f32_16x16x32_bf16 v[56:59], v[136:139], v[162:165], v[56:59]
	v_mfma_f32_16x16x32_bf16 v[44:47], v[128:131], v[188:191], v[44:47]
	v_mfma_f32_16x16x32_bf16 v[40:43], v[136:139], v[188:191], v[40:43]
	v_mfma_f32_16x16x32_bf16 v[28:31], v[128:131], v[196:199], v[28:31]
	v_mfma_f32_16x16x32_bf16 v[24:27], v[136:139], v[196:199], v[24:27]
	v_mfma_f32_16x16x32_bf16 v[12:15], v[128:131], v[204:207], v[12:15]
	v_mfma_f32_16x16x32_bf16 v[8:11], v[136:139], v[204:207], v[8:11]
	v_mfma_f32_16x16x32_bf16 v[60:63], v[132:135], v[166:169], v[60:63]
	v_mfma_f32_16x16x32_bf16 v[56:59], v[140:143], v[166:169], v[56:59]
	v_mfma_f32_16x16x32_bf16 v[44:47], v[132:135], v[192:195], v[44:47]
	v_mfma_f32_16x16x32_bf16 v[40:43], v[140:143], v[192:195], v[40:43]
	v_mfma_f32_16x16x32_bf16 v[28:31], v[132:135], v[200:203], v[28:31]
	v_mfma_f32_16x16x32_bf16 v[24:27], v[140:143], v[200:203], v[24:27]
	v_mfma_f32_16x16x32_bf16 v[12:15], v[132:135], v[208:211], v[12:15]
	v_mfma_f32_16x16x32_bf16 v[8:11], v[140:143], v[208:211], v[8:11]
	s_setprio 0
	s_barrier
	s_add_u32 s34, s34, 0x40080
	s_addc_u32 s35, s35, 0
	s_mov_b32 m0, s58
	v_lshl_add_u64 v[128:129], s[34:35], 0, v[144:145]
	global_load_lds_dwordx4 v[128:129], off
	v_lshl_add_u64 v[128:129], s[34:35], 0, v[146:147]
	s_mov_b32 m0, s59
	s_nop 0
	global_load_lds_dwordx4 v[128:129], off
	s_waitcnt vmcnt(6)
	s_barrier
	s_setprio 1
	v_mfma_f32_16x16x32_bf16 v[52:55], v[212:215], v[162:165], v[52:55]
	v_mfma_f32_16x16x32_bf16 v[48:51], v[220:223], v[162:165], v[48:51]
	v_mfma_f32_16x16x32_bf16 v[36:39], v[212:215], v[188:191], v[36:39]
	v_mfma_f32_16x16x32_bf16 v[32:35], v[220:223], v[188:191], v[32:35]
	v_mfma_f32_16x16x32_bf16 v[20:23], v[212:215], v[196:199], v[20:23]
	v_mfma_f32_16x16x32_bf16 v[16:19], v[220:223], v[196:199], v[16:19]
	v_mfma_f32_16x16x32_bf16 v[4:7], v[212:215], v[204:207], v[4:7]
	v_mfma_f32_16x16x32_bf16 v[0:3], v[220:223], v[204:207], v[0:3]
	v_mfma_f32_16x16x32_bf16 v[52:55], v[216:219], v[166:169], v[52:55]
	v_mfma_f32_16x16x32_bf16 v[48:51], v[224:227], v[166:169], v[48:51]
	v_mfma_f32_16x16x32_bf16 v[36:39], v[216:219], v[192:195], v[36:39]
	v_mfma_f32_16x16x32_bf16 v[32:35], v[224:227], v[192:195], v[32:35]
	v_mfma_f32_16x16x32_bf16 v[20:23], v[216:219], v[200:203], v[20:23]
	v_mfma_f32_16x16x32_bf16 v[16:19], v[224:227], v[200:203], v[16:19]
	v_mfma_f32_16x16x32_bf16 v[4:7], v[216:219], v[208:211], v[4:7]
	v_mfma_f32_16x16x32_bf16 v[0:3], v[224:227], v[208:211], v[0:3]
	s_setprio 0
	s_add_i32 s67, s67, 2
	s_add_u32 s65, s65, 0x100
	s_addc_u32 s66, s66, 0
	s_add_u32 s30, s30, 0x100
	s_addc_u32 s31, s31, 0
	s_cmp_gt_u32 s67, 13
	s_barrier
	s_cbranch_scc0 .LBB0_2164
	s_ashr_i32 s29, s28, 31
	s_lshl_b64 s[28:29], s[28:29], 8
	s_lshl_b32 s30, s12, 8
	v_lshl_add_u64 v[164:165], s[28:29], 0, v[148:149]
	s_ashr_i32 s31, s30, 31
	v_lshl_add_u64 v[166:167], s[30:31], 2, v[152:153]
	v_lshlrev_b64 v[128:129], 12, v[164:165]
	v_lshl_add_u64 v[128:129], v[166:167], 0, v[128:129]
	global_load_dwordx4 v[190:193], v[128:129], off
	global_load_dwordx4 v[194:197], v[128:129], off offset:64
	global_load_dwordx4 v[198:201], v[128:129], off offset:512
	global_load_dwordx4 v[202:205], v[128:129], off offset:576
	v_or_b32_e32 v168, 16, v164
	v_mov_b32_e32 v169, v165
	v_lshlrev_b64 v[128:129], 12, v[168:169]
	v_lshl_add_u64 v[128:129], v[166:167], 0, v[128:129]
	global_load_dwordx4 v[140:143], v[128:129], off
	global_load_dwordx4 v[136:139], v[128:129], off offset:64
	global_load_dwordx4 v[132:135], v[128:129], off offset:512
	s_nop 0
	global_load_dwordx4 v[128:131], v[128:129], off offset:576
	v_and_b32_e32 v163, 64, v187
	v_xor_b32_e32 v188, 16, v187
	v_add_u32_e32 v206, 64, v163
	v_xor_b32_e32 v189, 32, v187
	v_cmp_lt_i32_e32 vcc, v188, v206
	v_or_b32_e32 v162, s30, v150
	v_mov_b32_e32 v163, s31
	v_cndmask_b32_e32 v188, v187, v188, vcc
	v_cmp_lt_i32_e32 vcc, v189, v206
	v_lshlrev_b64 v[206:207], 10, v[164:165]
	v_lshl_add_u64 v[206:207], v[206:207], 0, v[162:163]
	v_lshl_add_u64 v[208:209], v[206:207], 2, s[78:79]
	s_waitcnt vmcnt(0)
	v_lshlrev_b64 v[206:207], 1, v[206:207]
	v_lshl_add_u64 v[210:211], s[2:3], 0, v[206:207]
	v_lshlrev_b32_e32 v188, 2, v188
	v_or_b32_e32 v212, 32, v206
	v_mov_b32_e32 v213, v207
	v_cndmask_b32_e32 v189, v187, v189, vcc
	v_or_b32_e32 v214, 0x100, v206
	v_mov_b32_e32 v215, v207
	v_lshl_add_u64 v[212:213], s[2:3], 0, v[212:213]
	v_lshl_add_u64 v[214:215], s[2:3], 0, v[214:215]
	s_lshl_b32 s28, s12, 2
	v_or_b32_e32 v206, 0x120, v206
	s_ashr_i32 s29, s28, 31
	s_waitcnt vmcnt(0)
	v_pk_add_f32 v[126:127], v[126:127], v[192:193]
	v_pk_add_f32 v[124:125], v[124:125], v[190:191]
	v_pk_add_f32 v[120:121], v[120:121], v[194:195]
	v_pk_add_f32 v[122:123], v[122:123], v[196:197]
	v_pk_add_f32 v[116:117], v[116:117], v[198:199]
	v_pk_add_f32 v[190:191], v[112:113], v[202:203]
	global_store_dwordx4 v[208:209], v[124:127], off
	v_cvt_pk_bf16_f32 v112, v124, v125
	v_mul_f32_e32 v196, v120, v120
	v_mul_f32_e32 v197, v116, v116
	v_mul_f32_e32 v124, v124, v124
	v_fmac_f32_e32 v124, v125, v125
	v_fmac_f32_e32 v196, v121, v121
	v_pk_add_f32 v[118:119], v[118:119], v[200:201]
	v_mul_f32_e32 v198, v190, v190
	v_fmac_f32_e32 v197, v117, v117
	v_fmac_f32_e32 v124, v126, v126
	v_fmac_f32_e32 v196, v122, v122
	v_pk_add_f32 v[192:193], v[114:115], v[204:205]
	v_fmac_f32_e32 v198, v191, v191
	v_fmac_f32_e32 v197, v118, v118
	v_fmac_f32_e32 v124, v127, v127
	v_fmac_f32_e32 v196, v123, v123
	v_cvt_pk_bf16_f32 v113, v126, v127
	v_bfe_u32 v246, v176, 4, 1
	v_mul_u32_u24_e32 v246, 24, v246
	v_mov_b32_e32 v247, 0
	s_nop 1
	v_mov_b32_e32 v240, v112
	v_mov_b32_e32 v241, v113
	v_lshl_add_u64 v[244:245], v[210:211], 0, v[246:247]
	v_fmac_f32_e32 v198, v192, v192
	v_fmac_f32_e32 v197, v119, v119
	v_add_f32_e32 v112, v124, v196
	v_fmac_f32_e32 v198, v193, v193
	v_add_f32_e32 v112, v112, v197
	v_add_f32_e32 v112, v112, v198
	ds_bpermute_b32 v113, v188, v112
	v_cvt_pk_bf16_f32 v114, v120, v121
	v_cvt_pk_bf16_f32 v115, v122, v123
	v_cvt_pk_bf16_f32 v194, v116, v117
	v_cvt_pk_bf16_f32 v195, v118, v119
	global_store_dwordx4 v[208:209], v[120:123], off offset:64
	v_mov_b32_e32 v242, v114
	v_mov_b32_e32 v243, v115
	s_nop 1
	v_permlane16_swap_b32 v240, v242
	v_permlane16_swap_b32 v241, v243
	global_store_dwordx4 v[244:245], v[240:243], off
	global_store_dwordx4 v[208:209], v[116:119], off offset:512
	s_nop 1
	v_mov_b32_e32 v240, v194
	v_mov_b32_e32 v241, v195
	v_lshl_add_u64 v[244:245], v[214:215], 0, v[246:247]
	global_store_dwordx4 v[208:209], v[190:193], off offset:576
	s_waitcnt lgkmcnt(0)
	v_add_f32_e32 v112, v112, v113
	v_lshlrev_b32_e32 v116, 2, v189
	ds_bpermute_b32 v113, v116, v112
	v_lshl_add_u64 v[114:115], s[2:3], 0, v[206:207]
	v_cvt_pk_bf16_f32 v118, v190, v191
	v_cvt_pk_bf16_f32 v119, v192, v193
	v_mov_b32_e32 v242, v118
	v_mov_b32_e32 v243, v119
	s_nop 1
	v_permlane16_swap_b32 v240, v242
	v_permlane16_swap_b32 v241, v243
	global_store_dwordx4 v[244:245], v[240:243], off
	s_and_saveexec_b64 s[30:31], s[6:7]
	s_cbranch_execz .LBB0_2167
	v_lshlrev_b64 v[114:115], 6, v[164:165]
	v_lshl_add_u64 v[114:115], s[4:5], 0, v[114:115]
	v_lshl_add_u64 v[114:115], s[28:29], 2, v[114:115]
	s_lshl_b32 s12, s53, 2
	v_lshl_add_u64 v[114:115], v[114:115], 0, s[12:13]
	s_waitcnt lgkmcnt(0)
	v_add_f32_e32 v112, v112, v113
	v_mov_b32_e32 v232, v114
	v_mov_b32_e32 v233, v115
	v_mov_b32_e32 v234, v112
.LBB0_2167:
	s_or_b64 exec, exec, s[30:31]
	s_waitcnt lgkmcnt(0)
	v_lshlrev_b64 v[112:113], 10, v[168:169]
	v_lshl_add_u64 v[112:113], v[112:113], 0, v[162:163]
	v_pk_add_f32 v[108:109], v[108:109], v[140:141]
	v_lshl_add_u64 v[114:115], v[112:113], 2, s[78:79]
	v_lshlrev_b64 v[112:113], 1, v[112:113]
	v_mul_f32_e32 v117, v108, v108
	v_pk_add_f32 v[110:111], v[110:111], v[142:143]
	v_lshl_add_u64 v[118:119], s[2:3], 0, v[112:113]
	v_fmac_f32_e32 v117, v109, v109
	v_pk_add_f32 v[106:107], v[106:107], v[138:139]
	v_pk_add_f32 v[104:105], v[104:105], v[136:137]
	global_store_dwordx4 v[114:115], v[108:111], off
	v_cvt_pk_bf16_f32 v120, v108, v109
	v_cvt_pk_bf16_f32 v121, v110, v111
	s_nop 1
	v_mov_b32_e32 v240, v120
	v_mov_b32_e32 v241, v121
	v_lshl_add_u64 v[244:245], v[118:119], 0, v[246:247]
	v_fmac_f32_e32 v117, v110, v110
	global_store_dwordx4 v[114:115], v[104:107], off offset:64
	v_or_b32_e32 v108, 32, v112
	v_mov_b32_e32 v109, v113
	v_cvt_pk_bf16_f32 v110, v104, v105
	v_mul_f32_e32 v104, v104, v104
	v_lshl_add_u64 v[108:109], s[2:3], 0, v[108:109]
	v_fmac_f32_e32 v104, v105, v105
	v_pk_add_f32 v[102:103], v[102:103], v[134:135]
	v_pk_add_f32 v[100:101], v[100:101], v[132:133]
	v_fmac_f32_e32 v117, v111, v111
	v_cvt_pk_bf16_f32 v111, v106, v107
	v_mov_b32_e32 v242, v110
	v_mov_b32_e32 v243, v111
	s_nop 1
	v_permlane16_swap_b32 v240, v242
	v_permlane16_swap_b32 v241, v243
	global_store_dwordx4 v[244:245], v[240:243], off
	v_fmac_f32_e32 v104, v106, v106
	global_store_dwordx4 v[114:115], v[100:103], off offset:512
	v_cvt_pk_bf16_f32 v106, v100, v101
	v_fmac_f32_e32 v104, v107, v107
	v_add_f32_e32 v107, v117, v104
	v_mul_f32_e32 v100, v100, v100
	v_fmac_f32_e32 v100, v101, v101
	v_fmac_f32_e32 v100, v102, v102
	v_fmac_f32_e32 v100, v103, v103
	v_add_f32_e32 v107, v107, v100
	v_pk_add_f32 v[100:101], v[98:99], v[130:131]
	v_pk_add_f32 v[98:99], v[96:97], v[128:129]
	v_or_b32_e32 v104, 0x100, v112
	v_mul_f32_e32 v96, v98, v98
	v_fmac_f32_e32 v96, v99, v99
	v_fmac_f32_e32 v96, v100, v100
	v_fmac_f32_e32 v96, v101, v101
	v_add_f32_e32 v96, v107, v96
	ds_bpermute_b32 v97, v188, v96
	v_mov_b32_e32 v105, v113
	v_or_b32_e32 v112, 0x120, v112
	v_lshl_add_u64 v[104:105], s[2:3], 0, v[104:105]
	v_cvt_pk_bf16_f32 v107, v102, v103
	s_waitcnt lgkmcnt(0)
	v_add_f32_e32 v96, v96, v97
	ds_bpermute_b32 v97, v116, v96
	v_lshl_add_u64 v[102:103], s[2:3], 0, v[112:113]
	s_nop 1
	v_mov_b32_e32 v240, v106
	v_mov_b32_e32 v241, v107
	v_lshl_add_u64 v[244:245], v[104:105], 0, v[246:247]
	global_store_dwordx4 v[114:115], v[98:101], off offset:576
	s_nop 1
	v_cvt_pk_bf16_f32 v98, v98, v99
	v_cvt_pk_bf16_f32 v99, v100, v101
	v_mov_b32_e32 v242, v98
	v_mov_b32_e32 v243, v99
	s_nop 1
	v_permlane16_swap_b32 v240, v242
	v_permlane16_swap_b32 v241, v243
	global_store_dwordx4 v[244:245], v[240:243], off
	s_and_saveexec_b64 s[30:31], s[6:7]
	s_cbranch_execz .LBB0_2169
	v_lshlrev_b64 v[98:99], 6, v[168:169]
	v_lshl_add_u64 v[98:99], s[4:5], 0, v[98:99]
	v_lshl_add_u64 v[98:99], s[28:29], 2, v[98:99]
	s_lshl_b32 s12, s53, 2
	v_lshl_add_u64 v[98:99], v[98:99], 0, s[12:13]
	s_waitcnt lgkmcnt(0)
	v_add_f32_e32 v96, v96, v97
	v_mov_b32_e32 v236, v98
	v_mov_b32_e32 v237, v99
	v_mov_b32_e32 v238, v96
.LBB0_2169:
	s_or_b64 exec, exec, s[30:31]
	s_nop 4
	v_permlane16_swap_b32 v236, v232
	v_permlane16_swap_b32 v237, v233
	v_permlane16_swap_b32 v238, v234
	s_mov_b64 s[30:31], exec
	s_mov_b64 exec, 0xffffffff
	global_store_dword v[236:237], v238, off
	s_mov_b64 exec, s[30:31]
	v_or_b32_e32 v114, 32, v164
	v_mov_b32_e32 v115, v165
	s_waitcnt lgkmcnt(0)
	v_lshlrev_b64 v[96:97], 12, v[114:115]
	v_lshl_add_u64 v[96:97], v[166:167], 0, v[96:97]
	global_load_dwordx4 v[118:121], v[96:97], off
	global_load_dwordx4 v[122:125], v[96:97], off offset:64
	global_load_dwordx4 v[126:129], v[96:97], off offset:512
	global_load_dwordx4 v[130:133], v[96:97], off offset:576
	v_or_b32_e32 v112, 48, v164
	v_mov_b32_e32 v113, v165
	v_lshlrev_b64 v[96:97], 12, v[112:113]
	v_lshl_add_u64 v[96:97], v[166:167], 0, v[96:97]
	global_load_dwordx4 v[108:111], v[96:97], off
	global_load_dwordx4 v[104:107], v[96:97], off offset:64
	global_load_dwordx4 v[100:103], v[96:97], off offset:512
	s_nop 0
	global_load_dwordx4 v[96:99], v[96:97], off offset:576
	v_lshlrev_b64 v[134:135], 10, v[114:115]
	v_lshl_add_u64 v[134:135], v[134:135], 0, v[162:163]
	v_lshl_add_u64 v[136:137], v[134:135], 2, s[78:79]
	v_lshlrev_b64 v[134:135], 1, v[134:135]
	v_lshl_add_u64 v[138:139], s[2:3], 0, v[134:135]
	s_waitcnt vmcnt(0)
	v_or_b32_e32 v140, 32, v134
	v_mov_b32_e32 v141, v135
	v_or_b32_e32 v142, 0x100, v134
	v_mov_b32_e32 v143, v135
	v_or_b32_e32 v134, 0x120, v134
	v_lshl_add_u64 v[140:141], s[2:3], 0, v[140:141]
	v_lshl_add_u64 v[142:143], s[2:3], 0, v[142:143]
	s_waitcnt vmcnt(0)
	v_pk_add_f32 v[92:93], v[92:93], v[118:119]
	v_pk_add_f32 v[88:89], v[88:89], v[122:123]
	v_pk_add_f32 v[84:85], v[84:85], v[126:127]
	v_mul_f32_e32 v117, v92, v92
	v_mul_f32_e32 v122, v88, v88
	v_pk_add_f32 v[94:95], v[94:95], v[120:121]
	v_pk_add_f32 v[90:91], v[90:91], v[124:125]
	v_pk_add_f32 v[118:119], v[80:81], v[130:131]
	v_mul_f32_e32 v123, v84, v84
	v_fmac_f32_e32 v117, v93, v93
	v_fmac_f32_e32 v122, v89, v89
	v_pk_add_f32 v[86:87], v[86:87], v[128:129]
	v_mul_f32_e32 v124, v118, v118
	v_fmac_f32_e32 v123, v85, v85
	v_fmac_f32_e32 v117, v94, v94
	v_fmac_f32_e32 v122, v90, v90
	v_pk_add_f32 v[120:121], v[82:83], v[132:133]
	v_cvt_pk_bf16_f32 v80, v92, v93
	v_fmac_f32_e32 v124, v119, v119
	v_fmac_f32_e32 v123, v86, v86
	v_fmac_f32_e32 v117, v95, v95
	v_fmac_f32_e32 v122, v91, v91
	global_store_dwordx4 v[136:137], v[92:95], off
	v_cvt_pk_bf16_f32 v81, v94, v95
	s_nop 1
	v_mov_b32_e32 v240, v80
	v_mov_b32_e32 v241, v81
	v_lshl_add_u64 v[244:245], v[138:139], 0, v[246:247]
	v_fmac_f32_e32 v124, v120, v120
	v_fmac_f32_e32 v123, v87, v87
	v_add_f32_e32 v80, v117, v122
	v_add_f32_e32 v80, v80, v123
	v_fmac_f32_e32 v124, v121, v121
	v_add_f32_e32 v80, v80, v124
	ds_bpermute_b32 v81, v188, v80
	v_cvt_pk_bf16_f32 v82, v88, v89
	v_cvt_pk_bf16_f32 v83, v90, v91
	v_cvt_pk_bf16_f32 v92, v84, v85
	global_store_dwordx4 v[136:137], v[88:91], off offset:64
	v_mov_b32_e32 v242, v82
	v_mov_b32_e32 v243, v83
	s_nop 1
	v_permlane16_swap_b32 v240, v242
	v_permlane16_swap_b32 v241, v243
	global_store_dwordx4 v[244:245], v[240:243], off
	s_waitcnt lgkmcnt(0)
	v_add_f32_e32 v80, v80, v81
	ds_bpermute_b32 v81, v116, v80
	v_cvt_pk_bf16_f32 v93, v86, v87
	v_lshl_add_u64 v[82:83], s[2:3], 0, v[134:135]
	global_store_dwordx4 v[136:137], v[84:87], off offset:512
	s_nop 1
	v_mov_b32_e32 v240, v92
	v_mov_b32_e32 v241, v93
	v_lshl_add_u64 v[244:245], v[142:143], 0, v[246:247]
	global_store_dwordx4 v[136:137], v[118:121], off offset:576
	v_cvt_pk_bf16_f32 v84, v118, v119
	v_cvt_pk_bf16_f32 v85, v120, v121
	v_mov_b32_e32 v242, v84
	v_mov_b32_e32 v243, v85
	s_nop 1
	v_permlane16_swap_b32 v240, v242
	v_permlane16_swap_b32 v241, v243
	global_store_dwordx4 v[244:245], v[240:243], off
	s_and_saveexec_b64 s[30:31], s[6:7]
	s_cbranch_execz .LBB0_2171
	v_lshlrev_b64 v[82:83], 6, v[114:115]
	v_lshl_add_u64 v[82:83], s[4:5], 0, v[82:83]
	v_lshl_add_u64 v[82:83], s[28:29], 2, v[82:83]
	s_lshl_b32 s12, s53, 2
	v_lshl_add_u64 v[82:83], v[82:83], 0, s[12:13]
	s_waitcnt lgkmcnt(0)
	v_add_f32_e32 v80, v80, v81
	v_mov_b32_e32 v232, v82
	v_mov_b32_e32 v233, v83
	v_mov_b32_e32 v234, v80
.LBB0_2171:
	s_or_b64 exec, exec, s[30:31]
	s_waitcnt lgkmcnt(0)
	v_lshlrev_b64 v[80:81], 10, v[112:113]
	v_lshl_add_u64 v[80:81], v[80:81], 0, v[162:163]
	v_lshl_add_u64 v[82:83], v[80:81], 2, s[78:79]
	v_lshlrev_b64 v[80:81], 1, v[80:81]
	v_pk_add_f32 v[78:79], v[78:79], v[110:111]
	v_pk_add_f32 v[76:77], v[76:77], v[108:109]
	v_lshl_add_u64 v[84:85], s[2:3], 0, v[80:81]
	global_store_dwordx4 v[82:83], v[76:79], off
	v_cvt_pk_bf16_f32 v86, v76, v77
	v_cvt_pk_bf16_f32 v87, v78, v79
	s_nop 1
	v_mov_b32_e32 v240, v86
	v_mov_b32_e32 v241, v87
	v_lshl_add_u64 v[244:245], v[84:85], 0, v[246:247]
	v_mul_f32_e32 v84, v76, v76
	v_fmac_f32_e32 v84, v77, v77
	v_pk_add_f32 v[74:75], v[74:75], v[106:107]
	v_pk_add_f32 v[72:73], v[72:73], v[104:105]
	v_fmac_f32_e32 v84, v78, v78
	global_store_dwordx4 v[82:83], v[72:75], off offset:64
	v_or_b32_e32 v76, 32, v80
	v_mov_b32_e32 v77, v81
	v_cvt_pk_bf16_f32 v78, v72, v73
	v_mul_f32_e32 v72, v72, v72
	v_lshl_add_u64 v[76:77], s[2:3], 0, v[76:77]
	v_fmac_f32_e32 v72, v73, v73
	v_pk_add_f32 v[70:71], v[70:71], v[102:103]
	v_pk_add_f32 v[68:69], v[68:69], v[100:101]
	v_fmac_f32_e32 v84, v79, v79
	v_cvt_pk_bf16_f32 v79, v74, v75
	v_mov_b32_e32 v242, v78
	v_mov_b32_e32 v243, v79
	s_nop 1
	v_permlane16_swap_b32 v240, v242
	v_permlane16_swap_b32 v241, v243
	global_store_dwordx4 v[244:245], v[240:243], off
	v_fmac_f32_e32 v72, v74, v74
	global_store_dwordx4 v[82:83], v[68:71], off offset:512
	v_cvt_pk_bf16_f32 v74, v68, v69
	v_fmac_f32_e32 v72, v75, v75
	v_add_f32_e32 v75, v84, v72
	v_mul_f32_e32 v68, v68, v68
	v_fmac_f32_e32 v68, v69, v69
	v_fmac_f32_e32 v68, v70, v70
	v_fmac_f32_e32 v68, v71, v71
	v_add_f32_e32 v75, v75, v68
	v_pk_add_f32 v[68:69], v[66:67], v[98:99]
	v_pk_add_f32 v[66:67], v[64:65], v[96:97]
	v_or_b32_e32 v72, 0x100, v80
	v_mul_f32_e32 v64, v66, v66
	v_fmac_f32_e32 v64, v67, v67
	v_fmac_f32_e32 v64, v68, v68
	v_fmac_f32_e32 v64, v69, v69
	v_add_f32_e32 v64, v75, v64
	ds_bpermute_b32 v65, v188, v64
	v_mov_b32_e32 v73, v81
	v_or_b32_e32 v80, 0x120, v80
	v_lshl_add_u64 v[72:73], s[2:3], 0, v[72:73]
	v_cvt_pk_bf16_f32 v75, v70, v71
	s_waitcnt lgkmcnt(0)
	v_add_f32_e32 v64, v64, v65
	ds_bpermute_b32 v65, v116, v64
	v_lshl_add_u64 v[70:71], s[2:3], 0, v[80:81]
	s_nop 1
	v_mov_b32_e32 v240, v74
	v_mov_b32_e32 v241, v75
	v_lshl_add_u64 v[244:245], v[72:73], 0, v[246:247]
	global_store_dwordx4 v[82:83], v[66:69], off offset:576
	s_nop 1
	v_cvt_pk_bf16_f32 v66, v66, v67
	v_cvt_pk_bf16_f32 v67, v68, v69
	v_mov_b32_e32 v242, v66
	v_mov_b32_e32 v243, v67
	s_nop 1
	v_permlane16_swap_b32 v240, v242
	v_permlane16_swap_b32 v241, v243
	global_store_dwordx4 v[244:245], v[240:243], off
	s_and_saveexec_b64 s[30:31], s[6:7]
	s_cbranch_execz .LBB0_2173
	v_lshlrev_b64 v[66:67], 6, v[112:113]
	v_lshl_add_u64 v[66:67], s[4:5], 0, v[66:67]
	v_lshl_add_u64 v[66:67], s[28:29], 2, v[66:67]
	s_lshl_b32 s12, s53, 2
	v_lshl_add_u64 v[66:67], v[66:67], 0, s[12:13]
	s_waitcnt lgkmcnt(0)
	v_add_f32_e32 v64, v64, v65
	v_mov_b32_e32 v236, v66
	v_mov_b32_e32 v237, v67
	v_mov_b32_e32 v238, v64
.LBB0_2173:
	s_or_b64 exec, exec, s[30:31]
	s_nop 4
	v_permlane16_swap_b32 v236, v232
	v_permlane16_swap_b32 v237, v233
	v_permlane16_swap_b32 v238, v234
	s_mov_b64 s[30:31], exec
	s_mov_b64 exec, 0xffffffff
	global_store_dword v[236:237], v238, off
	s_mov_b64 exec, s[30:31]
	v_lshl_add_u64 v[82:83], v[164:165], 0, s[10:11]
	s_waitcnt lgkmcnt(0)
	v_lshlrev_b64 v[64:65], 12, v[82:83]
	v_lshl_add_u64 v[64:65], v[166:167], 0, v[64:65]
	global_load_dwordx4 v[84:87], v[64:65], off
	global_load_dwordx4 v[88:91], v[64:65], off offset:64
	global_load_dwordx4 v[92:95], v[64:65], off offset:512
	global_load_dwordx4 v[96:99], v[64:65], off offset:576
	v_lshl_add_u64 v[80:81], v[164:165], 0, s[14:15]
	v_lshlrev_b64 v[64:65], 12, v[80:81]
	v_lshl_add_u64 v[64:65], v[166:167], 0, v[64:65]
	global_load_dwordx4 v[76:79], v[64:65], off
	global_load_dwordx4 v[72:75], v[64:65], off offset:64
	global_load_dwordx4 v[68:71], v[64:65], off offset:512
	s_nop 0
	global_load_dwordx4 v[64:67], v[64:65], off offset:576
	v_lshlrev_b64 v[100:101], 10, v[82:83]
	v_lshl_add_u64 v[100:101], v[100:101], 0, v[162:163]
	v_lshl_add_u64 v[102:103], v[100:101], 2, s[78:79]
	v_lshlrev_b64 v[100:101], 1, v[100:101]
	v_lshl_add_u64 v[104:105], s[2:3], 0, v[100:101]
	s_waitcnt vmcnt(0)
	v_or_b32_e32 v106, 32, v100
	v_mov_b32_e32 v107, v101
	v_or_b32_e32 v108, 0x100, v100
	v_mov_b32_e32 v109, v101
	v_or_b32_e32 v100, 0x120, v100
	v_lshl_add_u64 v[106:107], s[2:3], 0, v[106:107]
	v_lshl_add_u64 v[108:109], s[2:3], 0, v[108:109]
	s_waitcnt vmcnt(0)
	v_pk_add_f32 v[60:61], v[60:61], v[84:85]
	v_pk_add_f32 v[56:57], v[56:57], v[88:89]
	v_pk_add_f32 v[52:53], v[52:53], v[92:93]
	v_mul_f32_e32 v88, v60, v60
	v_mul_f32_e32 v89, v56, v56
	v_pk_add_f32 v[62:63], v[62:63], v[86:87]
	v_pk_add_f32 v[58:59], v[58:59], v[90:91]
	v_pk_add_f32 v[84:85], v[48:49], v[96:97]
	v_mul_f32_e32 v90, v52, v52
	v_fmac_f32_e32 v88, v61, v61
	v_fmac_f32_e32 v89, v57, v57
	v_pk_add_f32 v[54:55], v[54:55], v[94:95]
	v_mul_f32_e32 v91, v84, v84
	v_fmac_f32_e32 v90, v53, v53
	v_fmac_f32_e32 v88, v62, v62
	v_fmac_f32_e32 v89, v58, v58
	v_pk_add_f32 v[86:87], v[50:51], v[98:99]
	v_cvt_pk_bf16_f32 v48, v60, v61
	v_fmac_f32_e32 v91, v85, v85
	v_fmac_f32_e32 v90, v54, v54
	v_fmac_f32_e32 v88, v63, v63
	v_fmac_f32_e32 v89, v59, v59
	global_store_dwordx4 v[102:103], v[60:63], off
	v_cvt_pk_bf16_f32 v49, v62, v63
	s_nop 1
	v_mov_b32_e32 v240, v48
	v_mov_b32_e32 v241, v49
	v_lshl_add_u64 v[244:245], v[104:105], 0, v[246:247]
	v_fmac_f32_e32 v91, v86, v86
	v_fmac_f32_e32 v90, v55, v55
	v_add_f32_e32 v48, v88, v89
	v_add_f32_e32 v48, v48, v90
	v_fmac_f32_e32 v91, v87, v87
	v_add_f32_e32 v48, v48, v91
	ds_bpermute_b32 v49, v188, v48
	v_cvt_pk_bf16_f32 v50, v56, v57
	v_cvt_pk_bf16_f32 v51, v58, v59
	v_cvt_pk_bf16_f32 v60, v52, v53
	global_store_dwordx4 v[102:103], v[56:59], off offset:64
	v_mov_b32_e32 v242, v50
	v_mov_b32_e32 v243, v51
	s_nop 1
	v_permlane16_swap_b32 v240, v242
	v_permlane16_swap_b32 v241, v243
	global_store_dwordx4 v[244:245], v[240:243], off
	s_waitcnt lgkmcnt(0)
	v_add_f32_e32 v48, v48, v49
	ds_bpermute_b32 v49, v116, v48
	v_cvt_pk_bf16_f32 v61, v54, v55
	v_lshl_add_u64 v[50:51], s[2:3], 0, v[100:101]
	global_store_dwordx4 v[102:103], v[52:55], off offset:512
	s_nop 1
	v_mov_b32_e32 v240, v60
	v_mov_b32_e32 v241, v61
	v_lshl_add_u64 v[244:245], v[108:109], 0, v[246:247]
	global_store_dwordx4 v[102:103], v[84:87], off offset:576
	v_cvt_pk_bf16_f32 v52, v84, v85
	v_cvt_pk_bf16_f32 v53, v86, v87
	v_mov_b32_e32 v242, v52
	v_mov_b32_e32 v243, v53
	s_nop 1
	v_permlane16_swap_b32 v240, v242
	v_permlane16_swap_b32 v241, v243
	global_store_dwordx4 v[244:245], v[240:243], off
	s_and_saveexec_b64 s[30:31], s[6:7]
	s_cbranch_execz .LBB0_2175
	v_lshlrev_b64 v[50:51], 6, v[82:83]
	v_lshl_add_u64 v[50:51], s[4:5], 0, v[50:51]
	v_lshl_add_u64 v[50:51], s[28:29], 2, v[50:51]
	s_lshl_b32 s12, s53, 2
	v_lshl_add_u64 v[50:51], v[50:51], 0, s[12:13]
	s_waitcnt lgkmcnt(0)
	v_add_f32_e32 v48, v48, v49
	v_mov_b32_e32 v232, v50
	v_mov_b32_e32 v233, v51
	v_mov_b32_e32 v234, v48
.LBB0_2175:
	s_or_b64 exec, exec, s[30:31]
	s_waitcnt lgkmcnt(0)
	v_lshlrev_b64 v[48:49], 10, v[80:81]
	v_lshl_add_u64 v[48:49], v[48:49], 0, v[162:163]
	v_lshl_add_u64 v[50:51], v[48:49], 2, s[78:79]
	v_lshlrev_b64 v[48:49], 1, v[48:49]
	v_pk_add_f32 v[46:47], v[46:47], v[78:79]
	v_pk_add_f32 v[44:45], v[44:45], v[76:77]
	v_lshl_add_u64 v[52:53], s[2:3], 0, v[48:49]
	global_store_dwordx4 v[50:51], v[44:47], off
	v_cvt_pk_bf16_f32 v54, v44, v45
	v_cvt_pk_bf16_f32 v55, v46, v47
	s_nop 1
	v_mov_b32_e32 v240, v54
	v_mov_b32_e32 v241, v55
	v_lshl_add_u64 v[244:245], v[52:53], 0, v[246:247]
	v_mul_f32_e32 v52, v44, v44
	v_fmac_f32_e32 v52, v45, v45
	v_pk_add_f32 v[42:43], v[42:43], v[74:75]
	v_pk_add_f32 v[40:41], v[40:41], v[72:73]
	v_fmac_f32_e32 v52, v46, v46
	global_store_dwordx4 v[50:51], v[40:43], off offset:64
	v_or_b32_e32 v44, 32, v48
	v_mov_b32_e32 v45, v49
	v_cvt_pk_bf16_f32 v46, v40, v41
	v_mul_f32_e32 v40, v40, v40
	v_lshl_add_u64 v[44:45], s[2:3], 0, v[44:45]
	v_fmac_f32_e32 v40, v41, v41
	v_pk_add_f32 v[38:39], v[38:39], v[70:71]
	v_pk_add_f32 v[36:37], v[36:37], v[68:69]
	v_fmac_f32_e32 v52, v47, v47
	v_cvt_pk_bf16_f32 v47, v42, v43
	v_mov_b32_e32 v242, v46
	v_mov_b32_e32 v243, v47
	s_nop 1
	v_permlane16_swap_b32 v240, v242
	v_permlane16_swap_b32 v241, v243
	global_store_dwordx4 v[244:245], v[240:243], off
	v_fmac_f32_e32 v40, v42, v42
	global_store_dwordx4 v[50:51], v[36:39], off offset:512
	v_cvt_pk_bf16_f32 v42, v36, v37
	v_fmac_f32_e32 v40, v43, v43
	v_add_f32_e32 v43, v52, v40
	v_mul_f32_e32 v36, v36, v36
	v_fmac_f32_e32 v36, v37, v37
	v_fmac_f32_e32 v36, v38, v38
	v_fmac_f32_e32 v36, v39, v39
	v_add_f32_e32 v43, v43, v36
	v_pk_add_f32 v[36:37], v[34:35], v[66:67]
	v_pk_add_f32 v[34:35], v[32:33], v[64:65]
	v_or_b32_e32 v40, 0x100, v48
	v_mul_f32_e32 v32, v34, v34
	v_fmac_f32_e32 v32, v35, v35
	v_fmac_f32_e32 v32, v36, v36
	v_fmac_f32_e32 v32, v37, v37
	v_add_f32_e32 v32, v43, v32
	ds_bpermute_b32 v33, v188, v32
	v_mov_b32_e32 v41, v49
	v_or_b32_e32 v48, 0x120, v48
	v_lshl_add_u64 v[40:41], s[2:3], 0, v[40:41]
	v_cvt_pk_bf16_f32 v43, v38, v39
	s_waitcnt lgkmcnt(0)
	v_add_f32_e32 v32, v32, v33
	ds_bpermute_b32 v33, v116, v32
	v_lshl_add_u64 v[38:39], s[2:3], 0, v[48:49]
	s_nop 1
	v_mov_b32_e32 v240, v42
	v_mov_b32_e32 v241, v43
	v_lshl_add_u64 v[244:245], v[40:41], 0, v[246:247]
	global_store_dwordx4 v[50:51], v[34:37], off offset:576
	s_nop 1
	v_cvt_pk_bf16_f32 v34, v34, v35
	v_cvt_pk_bf16_f32 v35, v36, v37
	v_mov_b32_e32 v242, v34
	v_mov_b32_e32 v243, v35
	s_nop 1
	v_permlane16_swap_b32 v240, v242
	v_permlane16_swap_b32 v241, v243
	global_store_dwordx4 v[244:245], v[240:243], off
	s_and_saveexec_b64 s[30:31], s[6:7]
	s_cbranch_execz .LBB0_2177
	v_lshlrev_b64 v[34:35], 6, v[80:81]
	v_lshl_add_u64 v[34:35], s[4:5], 0, v[34:35]
	v_lshl_add_u64 v[34:35], s[28:29], 2, v[34:35]
	s_lshl_b32 s12, s53, 2
	v_lshl_add_u64 v[34:35], v[34:35], 0, s[12:13]
	s_waitcnt lgkmcnt(0)
	v_add_f32_e32 v32, v32, v33
	v_mov_b32_e32 v236, v34
	v_mov_b32_e32 v237, v35
	v_mov_b32_e32 v238, v32
.LBB0_2177:
	s_or_b64 exec, exec, s[30:31]
	s_nop 4
	v_permlane16_swap_b32 v236, v232
	v_permlane16_swap_b32 v237, v233
	v_permlane16_swap_b32 v238, v234
	s_mov_b64 s[30:31], exec
	s_mov_b64 exec, 0xffffffff
	global_store_dword v[236:237], v238, off
	s_mov_b64 exec, s[30:31]
	v_lshl_add_u64 v[50:51], v[164:165], 0, s[16:17]
	s_waitcnt lgkmcnt(0)
	v_lshlrev_b64 v[32:33], 12, v[50:51]
	v_lshl_add_u64 v[32:33], v[166:167], 0, v[32:33]
	global_load_dwordx4 v[52:55], v[32:33], off
	global_load_dwordx4 v[56:59], v[32:33], off offset:64
	global_load_dwordx4 v[60:63], v[32:33], off offset:512
	global_load_dwordx4 v[64:67], v[32:33], off offset:576
	v_lshl_add_u64 v[48:49], v[164:165], 0, s[18:19]
	v_lshlrev_b64 v[32:33], 12, v[48:49]
	v_lshl_add_u64 v[32:33], v[166:167], 0, v[32:33]
	global_load_dwordx4 v[44:47], v[32:33], off
	global_load_dwordx4 v[40:43], v[32:33], off offset:64
	global_load_dwordx4 v[36:39], v[32:33], off offset:512
	s_nop 0
	global_load_dwordx4 v[32:35], v[32:33], off offset:576
	v_lshlrev_b64 v[68:69], 10, v[50:51]
	v_lshl_add_u64 v[68:69], v[68:69], 0, v[162:163]
	v_lshl_add_u64 v[70:71], v[68:69], 2, s[78:79]
	v_lshlrev_b64 v[68:69], 1, v[68:69]
	v_lshl_add_u64 v[72:73], s[2:3], 0, v[68:69]
	s_waitcnt vmcnt(0)
	v_or_b32_e32 v74, 32, v68
	v_mov_b32_e32 v75, v69
	v_or_b32_e32 v76, 0x100, v68
	v_mov_b32_e32 v77, v69
	v_or_b32_e32 v68, 0x120, v68
	v_lshl_add_u64 v[74:75], s[2:3], 0, v[74:75]
	v_lshl_add_u64 v[76:77], s[2:3], 0, v[76:77]
	s_waitcnt vmcnt(0)
	v_pk_add_f32 v[28:29], v[28:29], v[52:53]
	v_pk_add_f32 v[24:25], v[24:25], v[56:57]
	v_pk_add_f32 v[20:21], v[20:21], v[60:61]
	v_mul_f32_e32 v56, v28, v28
	v_mul_f32_e32 v57, v24, v24
	v_pk_add_f32 v[30:31], v[30:31], v[54:55]
	v_pk_add_f32 v[26:27], v[26:27], v[58:59]
	v_pk_add_f32 v[52:53], v[16:17], v[64:65]
	v_mul_f32_e32 v58, v20, v20
	v_fmac_f32_e32 v56, v29, v29
	v_fmac_f32_e32 v57, v25, v25
	v_pk_add_f32 v[22:23], v[22:23], v[62:63]
	v_mul_f32_e32 v59, v52, v52
	v_fmac_f32_e32 v58, v21, v21
	v_fmac_f32_e32 v56, v30, v30
	v_fmac_f32_e32 v57, v26, v26
	v_pk_add_f32 v[54:55], v[18:19], v[66:67]
	v_cvt_pk_bf16_f32 v16, v28, v29
	v_fmac_f32_e32 v59, v53, v53
	v_fmac_f32_e32 v58, v22, v22
	v_fmac_f32_e32 v56, v31, v31
	v_fmac_f32_e32 v57, v27, v27
	global_store_dwordx4 v[70:71], v[28:31], off
	v_cvt_pk_bf16_f32 v17, v30, v31
	s_nop 1
	v_mov_b32_e32 v240, v16
	v_mov_b32_e32 v241, v17
	v_lshl_add_u64 v[244:245], v[72:73], 0, v[246:247]
	v_fmac_f32_e32 v59, v54, v54
	v_fmac_f32_e32 v58, v23, v23
	v_add_f32_e32 v16, v56, v57
	v_add_f32_e32 v16, v16, v58
	v_fmac_f32_e32 v59, v55, v55
	v_add_f32_e32 v16, v16, v59
	ds_bpermute_b32 v17, v188, v16
	v_cvt_pk_bf16_f32 v18, v24, v25
	v_cvt_pk_bf16_f32 v19, v26, v27
	v_cvt_pk_bf16_f32 v28, v20, v21
	global_store_dwordx4 v[70:71], v[24:27], off offset:64
	v_mov_b32_e32 v242, v18
	v_mov_b32_e32 v243, v19
	s_nop 1
	v_permlane16_swap_b32 v240, v242
	v_permlane16_swap_b32 v241, v243
	global_store_dwordx4 v[244:245], v[240:243], off
	s_waitcnt lgkmcnt(0)
	v_add_f32_e32 v16, v16, v17
	ds_bpermute_b32 v17, v116, v16
	v_cvt_pk_bf16_f32 v29, v22, v23
	v_lshl_add_u64 v[18:19], s[2:3], 0, v[68:69]
	global_store_dwordx4 v[70:71], v[20:23], off offset:512
	s_nop 1
	v_mov_b32_e32 v240, v28
	v_mov_b32_e32 v241, v29
	v_lshl_add_u64 v[244:245], v[76:77], 0, v[246:247]
	global_store_dwordx4 v[70:71], v[52:55], off offset:576
	v_cvt_pk_bf16_f32 v20, v52, v53
	v_cvt_pk_bf16_f32 v21, v54, v55
	v_mov_b32_e32 v242, v20
	v_mov_b32_e32 v243, v21
	s_nop 1
	v_permlane16_swap_b32 v240, v242
	v_permlane16_swap_b32 v241, v243
	global_store_dwordx4 v[244:245], v[240:243], off
	s_and_saveexec_b64 s[30:31], s[6:7]
	s_cbranch_execz .LBB0_2179
	v_lshlrev_b64 v[18:19], 6, v[50:51]
	v_lshl_add_u64 v[18:19], s[4:5], 0, v[18:19]
	v_lshl_add_u64 v[18:19], s[28:29], 2, v[18:19]
	s_lshl_b32 s12, s53, 2
	v_lshl_add_u64 v[18:19], v[18:19], 0, s[12:13]
	s_waitcnt lgkmcnt(0)
	v_add_f32_e32 v16, v16, v17
	flat_store_dword v[18:19], v16
